# rolled scan: first half of each wave's packed S block kept in LDS between pass 1 and pass 2 (pass 2 re-reads only half from memory)
# speedup vs baseline: 1.0226x; 1.0044x over previous
; #define LAS __attribute__((address_space(3)))
; __device__ __forceinline__ void scan_pair(Frame& F, const int g, const int b, unsigned long long& pt0, unsigned long long& pt1) {
;     ...
;     const f32x4 za = *(const f32x4*)((const float*)(F.ws + WS_ZA) + ((size_t)(r * NG + g) * 64 + n) * 4);
;     const float aTr = za[2], aTi = za[3];
;     float hr, hi;
;     LAS unsigned char* uct = F.lds + 16384;
;     LAS float* sctx = (LAS float*)(F.lds + 16384 + 8 * 1040);
;     {   const int tt = (F.wave * 64 + n) >> 1, hf = n & 1;
;         f32x4 a0 = {0.f, 0.f, 0.f, 0.f}, a1 = a0;
; #pragma unroll
;         for (int ks = 0; ks < 4; ++ks) { const f32x4* rp = (const f32x4*)((const float*)(F.ws + WS_UCS) + ((((size_t)g * 4 + ks) * RC + b * CTXL + tt) * 16) + hf * 8); a0 += rp[0]; a1 += rp[1]; }
;         u32x4 w; w.x = pk2(a0[0], a0[1]); w.y = pk2(a0[2], a0[3]); w.z = pk2(a1[0], a1[1]); w.w = pk2(a1[2], a1[3]);
;         *(LAS u32x4*)(uct + (tt >> 5) * 1040 + ((tt & 31) * 16 + hf * 8) * 2) = w; }
;     __syncthreads();
;     {   const int kg = n >> 4, cl = n & 15;
;         const char* m2 = (const char*)(F.ws + WS_M2 + (size_t)g * MiB);
; #pragma unroll
;         for (int jb = 0; jb < 2; ++jb) { const int j = (F.wave * 2 + jb) * 16 + cl;
;             bf16x8 bm[16];
; #pragma unroll
;             for (int kt = 0; kt < 16; ++kt) bm[kt] = *(const bf16x8*)(m2 + ((size_t)((kt * 32 + kg * 8) >> 6) * 256 + j) * 128 + ((kt * 32 + kg * 8) & 63) * 2);
;             f32x4 d = {0.f, 0.f, 0.f, 0.f};
; #pragma unroll
;             for (int kt = 0; kt < 16; ++kt) { const bf16x8 au = *(const LAS bf16x8*)(uct + (cl & 7) * 1040 + (kt * 32 + kg * 8) * 2);
;                 d = __builtin_amdgcn_mfma_f32_16x16x32_bf16(au, bm[kt], d, 0, 0, 0); }
.LBB0_545:
	v_readlane_b32 s10, v252, 0
	s_add_i32 s4, s10, s60
	s_ashr_i32 s5, s4, 31
	s_lshl_b64 s[4:5], s[4:5], 10
	v_readlane_b32 s6, v253, 53
	v_mov_b32_e32 v74, v209
	s_add_u32 s4, s6, s4
	v_readlane_b32 s6, v253, 54
	s_waitcnt vmcnt(0)
	s_barrier
	s_waitcnt vmcnt(0)
	s_waitcnt vmcnt(0)
	s_barrier
	s_addc_u32 s5, s6, s5
	v_ashrrev_i32_e32 v75, 31, v74
	v_lshl_add_u64 v[2:3], v[74:75], 4, s[4:5]
	v_readlane_b32 s4, v253, 55
	global_load_dwordx4 v[246:249], v[2:3], off
	s_lshl_b32 s6, s2, 8
	v_add_u32_e32 v24, s4, v74
	v_ashrrev_i32_e32 v2, 1, v24
	s_lshl_b64 s[4:5], s[60:61], 11
	v_ashrrev_i32_e32 v3, 31, v2
	s_or_b32 s4, s4, s6
	v_and_b32_e32 v25, 1, v74
	v_lshl_add_u64 v[6:7], s[4:5], 0, v[2:3]
	v_readlane_b32 s4, v253, 56
	v_lshlrev_b32_e32 v130, 5, v25
	v_readlane_b32 s5, v253, 57
	v_lshlrev_b64 v[6:7], 6, v[6:7]
	v_ashrrev_i32_e32 v3, 6, v24
	v_lshl_add_u64 v[8:9], s[4:5], 0, v[130:131]
	v_lshl_add_u64 v[14:15], v[8:9], 0, v[6:7]
	v_lshl_add_u64 v[202:203], v[14:15], 0, s[8:9]
	s_mov_b64 s[4:5], 0x10000
	v_lshl_add_u64 v[204:205], v[14:15], 0, s[4:5]
	s_mov_b64 s[4:5], 0x18000
	v_lshl_add_u64 v[206:207], v[14:15], 0, s[4:5]
	global_load_dwordx4 v[170:173], v[14:15], off
	global_load_dwordx4 v[174:177], v[14:15], off offset:16
	global_load_dwordx4 v[178:181], v[202:203], off
	global_load_dwordx4 v[182:185], v[202:203], off offset:16
	global_load_dwordx4 v[186:189], v[204:205], off
	global_load_dwordx4 v[190:193], v[204:205], off offset:16
	global_load_dwordx4 v[194:197], v[206:207], off
	global_load_dwordx4 v[198:201], v[206:207], off offset:16
	v_lshlrev_b32_e32 v2, 5, v2
	v_and_b32_e32 v2, 0x3e0, v2
	v_and_b32_e32 v169, 15, v74
	v_ashrrev_i32_e32 v168, 4, v74
	v_and_b32_e32 v130, 0x70, v74
	v_mov_b32_e32 v123, v131
	v_mov_b32_e32 v83, v131
	v_mov_b32_e32 v89, v131
	v_mov_b32_e32 v95, v131
	v_mov_b32_e32 v101, v131
	v_mov_b32_e32 v107, v131
	v_mov_b32_e32 v121, v131
	v_mov_b32_e32 v113, v131
	v_readlane_b32 s11, v252, 1
	s_movk_i32 s4, 0x410
	v_mul_lo_u32 v3, v3, s4
	v_add_u32_e32 v3, 0, v3
	v_cmp_gt_i32_e32 vcc, 2, v168
	s_waitcnt vmcnt(6)
	v_pk_add_f32 v[22:23], v[174:175], 0 op_sel_hi:[1,0]
	v_pk_add_f32 v[18:19], v[170:171], 0 op_sel_hi:[1,0]
	v_pk_add_f32 v[16:17], v[172:173], 0 op_sel_hi:[1,0]
	v_pk_add_f32 v[20:21], v[176:177], 0 op_sel_hi:[1,0]
	s_waitcnt vmcnt(4)
	v_pk_add_f32 v[18:19], v[18:19], v[178:179]
	v_pk_add_f32 v[22:23], v[22:23], v[182:183]
	v_pk_add_f32 v[16:17], v[16:17], v[180:181]
	v_pk_add_f32 v[20:21], v[20:21], v[184:185]
	s_waitcnt vmcnt(2)
	v_pk_add_f32 v[18:19], v[18:19], v[186:187]
	v_pk_add_f32 v[22:23], v[22:23], v[190:191]
	v_pk_add_f32 v[16:17], v[16:17], v[188:189]
	v_pk_add_f32 v[20:21], v[20:21], v[192:193]
	s_waitcnt vmcnt(0)
	v_pk_add_f32 v[8:9], v[16:17], v[196:197]
	v_pk_add_f32 v[6:7], v[18:19], v[194:195]
	v_pk_add_f32 v[10:11], v[22:23], v[198:199]
	v_pk_add_f32 v[12:13], v[20:21], v[200:201]
	v_cvt_pk_bf16_f32 v6, v6, v7
	v_cvt_pk_bf16_f32 v7, v8, v9
	v_cvt_pk_bf16_f32 v8, v10, v11
	v_lshlrev_b32_e32 v10, 4, v25
	v_cvt_pk_bf16_f32 v9, v12, v13
	v_add3_u32 v2, v3, v2, v10
	v_and_b32_e32 v3, -16, v74
	ds_write_b128 v2, v[6:9] offset:16384
	v_and_b32_e32 v2, 7, v74
	v_add_u32_e32 v124, 0, v3
	v_mad_u32_u24 v8, v2, s4, v124
	v_readlane_b32 s4, v253, 58
	v_mov_b32_e32 v3, v131
	v_ashrrev_i32_e32 v10, 7, v74
	v_or_b32_e32 v2, s4, v169
	v_lshlrev_b64 v[6:7], 7, v[2:3]
	v_ashrrev_i32_e32 v11, 31, v10
	v_lshlrev_b32_e32 v9, 3, v168
	v_lshl_add_u64 v[6:7], s[82:83], 0, v[6:7]
	v_lshlrev_b64 v[76:77], 15, v[10:11]
	v_lshl_add_u64 v[10:11], v[6:7], 0, v[76:77]
	v_add_u32_e32 v3, 32, v9
	v_lshl_add_u64 v[10:11], v[10:11], 0, v[130:131]
	v_ashrrev_i32_e32 v14, 6, v3
	s_waitcnt lgkmcnt(0)
	s_barrier
	global_load_dwordx4 v[10:13], v[10:11], off
	v_ashrrev_i32_e32 v15, 31, v14
	v_lshlrev_b64 v[118:119], 15, v[14:15]
	v_lshlrev_b32_e32 v3, 1, v3
	v_lshl_add_u64 v[14:15], v[6:7], 0, v[118:119]
	v_and_b32_e32 v122, 0x70, v3
	v_add_u32_e32 v3, 64, v9
	v_lshl_add_u64 v[14:15], v[14:15], 0, v[122:123]
	v_ashrrev_i32_e32 v18, 6, v3
	global_load_dwordx4 v[14:17], v[14:15], off
	v_ashrrev_i32_e32 v19, 31, v18
	v_lshlrev_b64 v[78:79], 15, v[18:19]
	v_add_u32_e32 v3, 0x60, v9
	v_lshl_add_u64 v[18:19], v[6:7], 0, v[78:79]
	v_ashrrev_i32_e32 v22, 6, v3
	v_lshl_add_u64 v[18:19], v[18:19], 0, v[130:131]
	v_ashrrev_i32_e32 v23, 31, v22
	global_load_dwordx4 v[18:21], v[18:19], off
	v_lshlrev_b64 v[80:81], 15, v[22:23]
	v_lshlrev_b32_e32 v3, 1, v3
	v_lshl_add_u64 v[22:23], v[6:7], 0, v[80:81]
	v_and_b32_e32 v82, 0x70, v3
	v_lshl_add_u64 v[22:23], v[22:23], 0, v[82:83]
	v_add_u32_e32 v3, 0x80, v9
	global_load_dwordx4 v[34:37], v[22:23], off
	v_ashrrev_i32_e32 v22, 6, v3
	v_ashrrev_i32_e32 v23, 31, v22
	v_lshlrev_b64 v[84:85], 15, v[22:23]
	v_lshl_add_u64 v[22:23], v[6:7], 0, v[84:85]
	v_lshl_add_u64 v[22:23], v[22:23], 0, v[130:131]
	global_load_dwordx4 v[42:45], v[22:23], off
	v_add_u32_e32 v3, 0xa0, v9
	v_ashrrev_i32_e32 v22, 6, v3
	v_ashrrev_i32_e32 v23, 31, v22
	v_lshlrev_b64 v[86:87], 15, v[22:23]
	v_lshlrev_b32_e32 v3, 1, v3
	v_lshl_add_u64 v[22:23], v[6:7], 0, v[86:87]
	v_and_b32_e32 v88, 0x70, v3
	v_lshl_add_u64 v[22:23], v[22:23], 0, v[88:89]
	v_add_u32_e32 v3, 0xc0, v9
	global_load_dwordx4 v[46:49], v[22:23], off
	v_ashrrev_i32_e32 v22, 6, v3
	v_ashrrev_i32_e32 v23, 31, v22
	v_lshlrev_b64 v[90:91], 15, v[22:23]
	v_lshl_add_u64 v[22:23], v[6:7], 0, v[90:91]
	v_lshl_add_u64 v[22:23], v[22:23], 0, v[130:131]
	v_add_u32_e32 v3, 0xe0, v9
	global_load_dwordx4 v[50:53], v[22:23], off
	v_ashrrev_i32_e32 v22, 6, v3
	v_ashrrev_i32_e32 v23, 31, v22
	v_lshlrev_b64 v[92:93], 15, v[22:23]
	v_lshlrev_b32_e32 v3, 1, v3
; #define LAS __attribute__((address_space(3)))
; __device__ __forceinline__ void scan_pair(Frame& F, const int g, const int b, unsigned long long& pt0, unsigned long long& pt1) {
;     ...
;         for (int jb = 0; jb < 2; ++jb) { const int j = (F.wave * 2 + jb) * 16 + cl;
;             bf16x8 bm[16];
; #pragma unroll
;             for (int kt = 0; kt < 16; ++kt) bm[kt] = *(const bf16x8*)(m2 + ((size_t)((kt * 32 + kg * 8) >> 6) * 256 + j) * 128 + ((kt * 32 + kg * 8) & 63) * 2);
;             f32x4 d = {0.f, 0.f, 0.f, 0.f};
; #pragma unroll
;             for (int kt = 0; kt < 16; ++kt) { const bf16x8 au = *(const LAS bf16x8*)(uct + (cl & 7) * 1040 + (kt * 32 + kg * 8) * 2);
;                 d = __builtin_amdgcn_mfma_f32_16x16x32_bf16(au, bm[kt], d, 0, 0, 0); }
;             if (kg < 2) *(LAS f32x4*)(sctx + j * 8 + 4 * kg) = d; } }
	v_lshl_add_u64 v[22:23], v[6:7], 0, v[92:93]
	v_and_b32_e32 v94, 0x70, v3
	v_lshl_add_u64 v[22:23], v[22:23], 0, v[94:95]
	v_add_u32_e32 v3, 0x100, v9
	global_load_dwordx4 v[58:61], v[22:23], off
	v_ashrrev_i32_e32 v22, 6, v3
	v_ashrrev_i32_e32 v23, 31, v22
	v_lshlrev_b64 v[96:97], 15, v[22:23]
	v_lshl_add_u64 v[22:23], v[6:7], 0, v[96:97]
	v_lshl_add_u64 v[22:23], v[22:23], 0, v[130:131]
	v_add_u32_e32 v3, 0x120, v9
	global_load_dwordx4 v[70:73], v[22:23], off
	v_ashrrev_i32_e32 v22, 6, v3
	v_ashrrev_i32_e32 v23, 31, v22
	v_lshlrev_b64 v[98:99], 15, v[22:23]
	v_lshlrev_b32_e32 v3, 1, v3
	v_lshl_add_u64 v[22:23], v[6:7], 0, v[98:99]
	v_and_b32_e32 v100, 0x70, v3
	v_lshl_add_u64 v[22:23], v[22:23], 0, v[100:101]
	v_add_u32_e32 v3, 0x140, v9
	global_load_dwordx4 v[126:129], v[22:23], off
	v_ashrrev_i32_e32 v22, 6, v3
	v_ashrrev_i32_e32 v23, 31, v22
	v_lshlrev_b64 v[102:103], 15, v[22:23]
	v_lshl_add_u64 v[22:23], v[6:7], 0, v[102:103]
	v_lshl_add_u64 v[22:23], v[22:23], 0, v[130:131]
	v_add_u32_e32 v3, 0x160, v9
	global_load_dwordx4 v[132:135], v[22:23], off
	v_ashrrev_i32_e32 v22, 6, v3
	v_ashrrev_i32_e32 v23, 31, v22
	v_lshlrev_b64 v[104:105], 15, v[22:23]
	v_lshlrev_b32_e32 v3, 1, v3
	v_lshl_add_u64 v[22:23], v[6:7], 0, v[104:105]
	v_and_b32_e32 v106, 0x70, v3
	v_lshl_add_u64 v[22:23], v[22:23], 0, v[106:107]
	v_add_u32_e32 v3, 0x180, v9
	global_load_dwordx4 v[136:139], v[22:23], off
	v_ashrrev_i32_e32 v22, 6, v3
	v_ashrrev_i32_e32 v23, 31, v22
	v_lshlrev_b64 v[110:111], 15, v[22:23]
	v_lshl_add_u64 v[22:23], v[6:7], 0, v[110:111]
	v_lshl_add_u64 v[22:23], v[22:23], 0, v[130:131]
	v_add_u32_e32 v3, 0x1a0, v9
	global_load_dwordx4 v[140:143], v[22:23], off
	v_ashrrev_i32_e32 v22, 6, v3
	v_ashrrev_i32_e32 v23, 31, v22
	v_lshlrev_b64 v[114:115], 15, v[22:23]
	v_lshlrev_b32_e32 v3, 1, v3
	v_lshl_add_u64 v[22:23], v[6:7], 0, v[114:115]
	v_and_b32_e32 v120, 0x70, v3
	v_lshl_add_u64 v[22:23], v[22:23], 0, v[120:121]
	global_load_dwordx4 v[144:147], v[22:23], off
	v_add_u32_e32 v3, 0x1c0, v9
	v_ashrrev_i32_e32 v22, 6, v3
	v_ashrrev_i32_e32 v23, 31, v22
	v_lshlrev_b64 v[116:117], 15, v[22:23]
	v_lshl_add_u64 v[22:23], v[6:7], 0, v[116:117]
	v_lshl_add_u64 v[22:23], v[22:23], 0, v[130:131]
	v_add_u32_e32 v3, 0x1e0, v9
	global_load_dwordx4 v[148:151], v[22:23], off
	v_ashrrev_i32_e32 v22, 6, v3
	ds_read_b128 v[66:69], v8 offset:16384
	v_ashrrev_i32_e32 v23, 31, v22
	v_lshlrev_b64 v[108:109], 15, v[22:23]
	v_lshlrev_b32_e32 v3, 1, v3
	v_lshl_add_u64 v[6:7], v[6:7], 0, v[108:109]
	v_and_b32_e32 v112, 0x70, v3
	v_lshl_add_u64 v[6:7], v[6:7], 0, v[112:113]
	ds_read_b128 v[22:25], v8 offset:16448
	global_load_dwordx4 v[152:155], v[6:7], off
	ds_read_b128 v[26:29], v8 offset:16512
	ds_read_b128 v[30:33], v8 offset:16576
	s_waitcnt vmcnt(15) lgkmcnt(3)
	v_mfma_f32_16x16x32_bf16 v[10:13], v[66:69], v[10:13], 0
	ds_read_b128 v[38:41], v8 offset:16640
	ds_read_b128 v[54:57], v8 offset:16832
	ds_read_b128 v[62:65], v8 offset:16896
	s_waitcnt vmcnt(14) lgkmcnt(5)
	v_mfma_f32_16x16x32_bf16 v[10:13], v[22:25], v[14:17], v[10:13]
	ds_read_b128 v[14:17], v8 offset:17216
	s_waitcnt vmcnt(13) lgkmcnt(5)
	v_mfma_f32_16x16x32_bf16 v[10:13], v[26:29], v[18:21], v[10:13]
	ds_read_b128 v[18:21], v8 offset:17152
	s_waitcnt vmcnt(12) lgkmcnt(5)
	v_mfma_f32_16x16x32_bf16 v[10:13], v[30:33], v[34:37], v[10:13]
	ds_read_b128 v[34:37], v8 offset:17088
	s_waitcnt vmcnt(11) lgkmcnt(5)
	v_mfma_f32_16x16x32_bf16 v[10:13], v[38:41], v[42:45], v[10:13]
	ds_read_b128 v[42:45], v8 offset:16704
	s_waitcnt vmcnt(10) lgkmcnt(0)
	v_mfma_f32_16x16x32_bf16 v[10:13], v[42:45], v[46:49], v[10:13]
	ds_read_b128 v[46:49], v8 offset:16768
	s_waitcnt vmcnt(9) lgkmcnt(0)
	v_mfma_f32_16x16x32_bf16 v[10:13], v[46:49], v[50:53], v[10:13]
	ds_read_b128 v[50:53], v8 offset:17024
	s_waitcnt vmcnt(8)
	v_mfma_f32_16x16x32_bf16 v[10:13], v[54:57], v[58:61], v[10:13]
	ds_read_b128 v[58:61], v8 offset:16960
	s_waitcnt vmcnt(7)
	v_mfma_f32_16x16x32_bf16 v[10:13], v[62:65], v[70:73], v[10:13]
	s_waitcnt vmcnt(6) lgkmcnt(0)
	v_mfma_f32_16x16x32_bf16 v[10:13], v[58:61], v[126:129], v[10:13]
	s_waitcnt vmcnt(5)
	v_mfma_f32_16x16x32_bf16 v[10:13], v[50:53], v[132:135], v[10:13]
	s_waitcnt vmcnt(4)
	v_mfma_f32_16x16x32_bf16 v[10:13], v[34:37], v[136:139], v[10:13]
	s_waitcnt vmcnt(3)
	v_mfma_f32_16x16x32_bf16 v[10:13], v[18:21], v[140:143], v[10:13]
	s_waitcnt vmcnt(2)
	v_mfma_f32_16x16x32_bf16 v[70:73], v[14:17], v[144:147], v[10:13]
	s_nop 5
	ds_read_b128 v[10:13], v8 offset:17280
	ds_read_b128 v[6:9], v8 offset:17344
	s_waitcnt vmcnt(1) lgkmcnt(1)
	v_mfma_f32_16x16x32_bf16 v[70:73], v[10:13], v[148:151], v[70:73]
	s_waitcnt vmcnt(0) lgkmcnt(0)
; #define LAS __attribute__((address_space(3)))
; __device__ __forceinline__ void scan_pair(Frame& F, const int g, const int b, unsigned long long& pt0, unsigned long long& pt1) {
;     ...
;         for (int jb = 0; jb < 2; ++jb) { const int j = (F.wave * 2 + jb) * 16 + cl;
;             bf16x8 bm[16];
; #pragma unroll
;             for (int kt = 0; kt < 16; ++kt) bm[kt] = *(const bf16x8*)(m2 + ((size_t)((kt * 32 + kg * 8) >> 6) * 256 + j) * 128 + ((kt * 32 + kg * 8) & 63) * 2);
;             f32x4 d = {0.f, 0.f, 0.f, 0.f};
; #pragma unroll
;             for (int kt = 0; kt < 16; ++kt) { const bf16x8 au = *(const LAS bf16x8*)(uct + (cl & 7) * 1040 + (kt * 32 + kg * 8) * 2);
;                 d = __builtin_amdgcn_mfma_f32_16x16x32_bf16(au, bm[kt], d, 0, 0, 0); }
;             if (kg < 2) *(LAS f32x4*)(sctx + j * 8 + 4 * kg) = d; } }
;     __syncthreads();
	v_mfma_f32_16x16x32_bf16 v[70:73], v[6:9], v[152:155], v[70:73]
	s_and_saveexec_b64 s[4:5], vcc
	v_lshl_add_u32 v3, v2, 5, v124
	s_nop 5
	ds_write_b128 v3, v[70:73] offset:24704
	s_or_b64 exec, exec, s[4:5]
	v_or_b32_e32 v2, 16, v2
	v_mov_b32_e32 v3, v131
	v_lshlrev_b64 v[70:71], 7, v[2:3]
	v_lshl_add_u64 v[126:127], s[82:83], 0, v[70:71]
	v_lshl_add_u64 v[70:71], v[126:127], 0, v[76:77]
	v_lshl_add_u64 v[70:71], v[70:71], 0, v[130:131]
	global_load_dwordx4 v[170:173], v[70:71], off
	v_lshl_add_u64 v[70:71], v[126:127], 0, v[118:119]
	v_lshl_add_u64 v[70:71], v[70:71], 0, v[122:123]
	global_load_dwordx4 v[174:177], v[70:71], off
	v_lshl_add_u64 v[70:71], v[126:127], 0, v[78:79]
	v_lshl_add_u64 v[70:71], v[70:71], 0, v[130:131]
	global_load_dwordx4 v[178:181], v[70:71], off
	v_lshl_add_u64 v[70:71], v[126:127], 0, v[80:81]
	v_lshl_add_u64 v[70:71], v[70:71], 0, v[82:83]
	global_load_dwordx4 v[182:185], v[70:71], off
	v_lshl_add_u64 v[70:71], v[126:127], 0, v[84:85]
	v_lshl_add_u64 v[70:71], v[70:71], 0, v[130:131]
	global_load_dwordx4 v[186:189], v[70:71], off
	v_lshl_add_u64 v[70:71], v[126:127], 0, v[86:87]
	v_lshl_add_u64 v[70:71], v[70:71], 0, v[88:89]
	global_load_dwordx4 v[190:193], v[70:71], off
	v_lshl_add_u64 v[70:71], v[126:127], 0, v[90:91]
	v_lshl_add_u64 v[70:71], v[70:71], 0, v[130:131]
	global_load_dwordx4 v[194:197], v[70:71], off
	v_lshl_add_u64 v[70:71], v[126:127], 0, v[92:93]
	v_lshl_add_u64 v[70:71], v[70:71], 0, v[94:95]
	global_load_dwordx4 v[198:201], v[70:71], off
	v_lshl_add_u64 v[70:71], v[126:127], 0, v[96:97]
	v_lshl_add_u64 v[70:71], v[70:71], 0, v[130:131]
	global_load_dwordx4 v[202:205], v[70:71], off
	v_lshl_add_u64 v[70:71], v[126:127], 0, v[98:99]
	v_lshl_add_u64 v[70:71], v[70:71], 0, v[100:101]
	global_load_dwordx4 v[210:213], v[70:71], off
	v_lshl_add_u64 v[70:71], v[126:127], 0, v[102:103]
	v_lshl_add_u64 v[70:71], v[70:71], 0, v[130:131]
	global_load_dwordx4 v[214:217], v[70:71], off
	v_lshl_add_u64 v[70:71], v[126:127], 0, v[104:105]
	v_lshl_add_u64 v[70:71], v[70:71], 0, v[106:107]
	global_load_dwordx4 v[218:221], v[70:71], off
	v_lshl_add_u64 v[70:71], v[126:127], 0, v[110:111]
	v_lshl_add_u64 v[70:71], v[70:71], 0, v[130:131]
	global_load_dwordx4 v[222:225], v[70:71], off
	v_lshl_add_u64 v[70:71], v[126:127], 0, v[114:115]
	v_lshl_add_u64 v[70:71], v[70:71], 0, v[120:121]
	global_load_dwordx4 v[226:229], v[70:71], off
	v_lshl_add_u64 v[70:71], v[126:127], 0, v[116:117]
	v_lshl_add_u64 v[70:71], v[70:71], 0, v[130:131]
	global_load_dwordx4 v[230:233], v[70:71], off
	v_lshl_add_u64 v[70:71], v[126:127], 0, v[108:109]
	v_lshl_add_u64 v[70:71], v[70:71], 0, v[112:113]
	global_load_dwordx4 v[234:237], v[70:71], off
	s_waitcnt vmcnt(15)
	v_mfma_f32_16x16x32_bf16 v[66:69], v[66:69], v[170:173], 0
	s_waitcnt vmcnt(14)
	v_mfma_f32_16x16x32_bf16 v[22:25], v[22:25], v[174:177], v[66:69]
	s_waitcnt vmcnt(13)
	v_mfma_f32_16x16x32_bf16 v[22:25], v[26:29], v[178:181], v[22:25]
	s_waitcnt vmcnt(12)
	v_mfma_f32_16x16x32_bf16 v[22:25], v[30:33], v[182:185], v[22:25]
	s_waitcnt vmcnt(11)
	v_mfma_f32_16x16x32_bf16 v[22:25], v[38:41], v[186:189], v[22:25]
	s_waitcnt vmcnt(10)
	v_mfma_f32_16x16x32_bf16 v[22:25], v[42:45], v[190:193], v[22:25]
	s_waitcnt vmcnt(9)
	v_mfma_f32_16x16x32_bf16 v[22:25], v[46:49], v[194:197], v[22:25]
	s_waitcnt vmcnt(8)
	v_mfma_f32_16x16x32_bf16 v[22:25], v[54:57], v[198:201], v[22:25]
	s_waitcnt vmcnt(7)
	v_mfma_f32_16x16x32_bf16 v[22:25], v[62:65], v[202:205], v[22:25]
	s_waitcnt vmcnt(6)
	v_mfma_f32_16x16x32_bf16 v[22:25], v[58:61], v[210:213], v[22:25]
	s_waitcnt vmcnt(5)
	v_mfma_f32_16x16x32_bf16 v[22:25], v[50:53], v[214:217], v[22:25]
	s_waitcnt vmcnt(4)
	v_mfma_f32_16x16x32_bf16 v[22:25], v[34:37], v[218:221], v[22:25]
	s_waitcnt vmcnt(3)
	v_mfma_f32_16x16x32_bf16 v[18:21], v[18:21], v[222:225], v[22:25]
	s_waitcnt vmcnt(2)
	v_mfma_f32_16x16x32_bf16 v[14:17], v[14:17], v[226:229], v[18:21]
	s_waitcnt vmcnt(1)
	v_mfma_f32_16x16x32_bf16 v[10:13], v[10:13], v[230:233], v[14:17]
	s_waitcnt vmcnt(0)
	v_mfma_f32_16x16x32_bf16 v[6:9], v[6:9], v[234:237], v[10:13]
	s_and_saveexec_b64 s[4:5], vcc
	v_readlane_b32 s14, v253, 59
	v_readlane_b32 s15, v253, 60
	v_lshl_add_u32 v2, v2, 5, v124
	s_nop 3
	ds_write_b128 v2, v[6:9] offset:24704
	s_or_b64 exec, exec, s[4:5]
	v_add_u32_e32 v2, s10, v74
	v_lshl_add_u32 v2, v2, 5, 0
	s_waitcnt lgkmcnt(0)
	s_barrier
; #define LAS __attribute__((address_space(3)))
; #define SCAN_STAMP(k) do { if (PROBE_SSM_PART == 3 + (k)) pt0 = __builtin_amdgcn_s_memrealtime(); if (PROBE_SSM_PART == 2 + (k)) pt1 = __builtin_amdgcn_s_memrealtime(); } while (0)
; __device__ __forceinline__ void scan_pair(Frame& F, const int g, const int b, unsigned long long& pt0, unsigned long long& pt1) {
;     ...
;     float h0r = 0.f, h0i = 0.f;
;     {   const LAS f32x4* sre = (const LAS f32x4*)(sctx + (r * 128 + n) * 8); const LAS f32x4* sim = (const LAS f32x4*)(sctx + (r * 128 + 64 + n) * 8);
;         const f32x4 re0 = sre[0], re1 = sre[1], im0 = sim[0], im1 = sim[1];
;         if (r == 0) {
; #pragma unroll
;             for (int c = 0; c < 8; ++c) cmul_acc(h0r, h0i, aTr, aTi, c < 4 ? re0[c & 3] : re1[c & 3], c < 4 ? im0[c & 3] : im1[c & 3]);
;         } else {
; #pragma unroll
;             for (int c = 7; c >= 0; --c) cmul_acc(h0r, h0i, aTr, aTi, c < 4 ? re0[c & 3] : re1[c & 3], c < 4 ? im0[c & 3] : im1[c & 3]); } }
;     SCAN_STAMP(1);
;     constexpr int CPW = NCHB / 4; static_assert(CPW == 128, "scan register blocking");
;     const int cb = b * NCHB + (r ? NCHB - CPW * (wq + 1) : CPW * wq);
;     const bf16* re_row = (const bf16*)(F.ws + WS_S + (size_t)g * MiB) + ((size_t)(cb >> 3) * 256 + r * 128 + n) * 8;
;     const bf16* im_row = re_row + 64 * 8;
;     bf16* Xg = (bf16*)(F.ws + WS_X + (size_t)g * XPLANE) + TP + r * 128 + n;
	v_readlane_b32 s4, v253, 23
	s_nop 3
	s_lshr_b32 s5, s4, 2
	s_and_b32 s6, s4, 3
	s_lshl_b32 s7, s6, 7
	s_sub_i32 s16, 0x180, s7
	s_cmp_eq_u32 s5, 0
	s_cselect_b32 s7, s7, s16
	s_lshl_b32 s2, s2, 9
	s_add_i32 s2, s2, s7
	s_lshr_b32 s7, s2, 3
	s_lshl_b32 s7, s7, 12
	s_lshl_b32 s16, s5, 11
	s_add_i32 s7, s7, s16
	s_mul_i32 s16, s5, 0xf000
	s_add_i32 s7, s7, s16
	s_add_u32 s68, s80, s7
	s_addc_u32 s69, s81, 0
	s_lshl_b32 s7, s5, 18
	s_add_i32 s7, s7, 0x100000
	s_lshl_b32 s16, s2, 7
	s_add_i32 s7, s7, s16
	s_add_u32 s28, s62, s7
	s_addc_u32 s29, s63, 0
	v_lshlrev_b32_e32 v30, 4, v209
	v_lshrrev_b32_e32 v31, 4, v209
	v_sub_u32_e32 v37, 0x7f, v31
	s_cmp_eq_u32 s5, 0
	s_cselect_b64 vcc, -1, 0
	s_nop 3
	v_cndmask_b32_e32 v31, v37, v31, vcc
	v_lshlrev_b32_e32 v31, 7, v31
	v_and_b32_e32 v37, 7, v209
	v_lshl_add_u32 v31, v37, 4, v31
	v_bfe_u32 v37, v209, 3, 1
	v_lshl_add_u32 v31, v37, 17, v31
	s_lshl_b32 s7, s4, 10
	s_add_i32 s7, s7, 0x2000
	v_lshl_add_u32 v32, v209, 2, s7
	v_lshl_add_u32 v33, v209, 4, s7
	s_lshl_b32 s7, s4, 9
	v_lshl_add_u32 v34, v209, 3, s7
	s_lshl_b32 s7, s4, 14
	s_add_i32 s7, s7, 0x4000
	v_lshl_add_u32 v39, v209, 4, s7
	s_lshl_b32 s7, s5, 11
	v_lshl_add_u32 v35, v209, 3, s7
	s_lshl_b32 s7, s5, 7
	v_add_u32_e32 v36, s7, v209
	v_lshlrev_b32_e32 v36, 5, v36
	ds_read_b128 v[80:83], v36 offset:24704
	ds_read_b128 v[84:87], v36 offset:24720
	ds_read_b128 v[88:91], v36 offset:26752
	ds_read_b128 v[92:95], v36 offset:26768
	v_mov_b32_e32 v10, 0
	v_mov_b32_e32 v11, 0
	s_waitcnt lgkmcnt(0)
	s_cmp_lg_u32 s5, 0
	s_cbranch_scc1 .Lsc_ctx1
	v_mul_f32_e32 v12, v249, v11
	v_mul_f32_e32 v13, v248, v11
	v_fma_f32 v14, v248, v10, -v12
	v_fma_f32 v15, v249, v10, v13
	v_add_f32_e32 v10, v14, v80
	v_add_f32_e32 v11, v15, v88
	v_mul_f32_e32 v12, v249, v11
	v_mul_f32_e32 v13, v248, v11
	v_fma_f32 v14, v248, v10, -v12
	v_fma_f32 v15, v249, v10, v13
	v_add_f32_e32 v10, v14, v81
	v_add_f32_e32 v11, v15, v89
	v_mul_f32_e32 v12, v249, v11
	v_mul_f32_e32 v13, v248, v11
	v_fma_f32 v14, v248, v10, -v12
	v_fma_f32 v15, v249, v10, v13
	v_add_f32_e32 v10, v14, v82
	v_add_f32_e32 v11, v15, v90
	v_mul_f32_e32 v12, v249, v11
	v_mul_f32_e32 v13, v248, v11
	v_fma_f32 v14, v248, v10, -v12
	v_fma_f32 v15, v249, v10, v13
	v_add_f32_e32 v10, v14, v83
	v_add_f32_e32 v11, v15, v91
	v_mul_f32_e32 v12, v249, v11
	v_mul_f32_e32 v13, v248, v11
	v_fma_f32 v14, v248, v10, -v12
	v_fma_f32 v15, v249, v10, v13
	v_add_f32_e32 v10, v14, v84
	v_add_f32_e32 v11, v15, v92
	v_mul_f32_e32 v12, v249, v11
	v_mul_f32_e32 v13, v248, v11
	v_fma_f32 v14, v248, v10, -v12
	v_fma_f32 v15, v249, v10, v13
	v_add_f32_e32 v10, v14, v85
	v_add_f32_e32 v11, v15, v93
	v_mul_f32_e32 v12, v249, v11
	v_mul_f32_e32 v13, v248, v11
	v_fma_f32 v14, v248, v10, -v12
	v_fma_f32 v15, v249, v10, v13
	v_add_f32_e32 v10, v14, v86
	v_add_f32_e32 v11, v15, v94
	v_mul_f32_e32 v12, v249, v11
	v_mul_f32_e32 v13, v248, v11
	v_fma_f32 v14, v248, v10, -v12
	v_fma_f32 v15, v249, v10, v13
	v_add_f32_e32 v10, v14, v87
	v_add_f32_e32 v11, v15, v95
	s_branch .Lsc_ctxd

; #define SCAN_LOAD(HALF) do { _Pragma("unroll") for (int k = 0; k < 8; ++k) { const int kk = r ? (15 - 8 * (HALF) - k) : (8 * (HALF) + k); pre[k] = *(const u32x4*)(re_row + 2048 * kk); pim[k] = *(const u32x4*)(im_row + 2048 * kk); } } while (0)
; __device__ __forceinline__ void scan_pair(Frame& F, const int g, const int b, unsigned long long& pt0, unsigned long long& pt1) {
;     ...
;     float er = 0.f, ei = 0.f;
; #pragma unroll
;     for (int half = 0; half < 2; ++half) { SCAN_LOAD(half);
;         if (r == 0) {
; #pragma unroll
;             for (int i = 0; i < 64; ++i) cmul_acc(er, ei, aTr, aTi, bf2f(pre[i >> 3][(i & 7) >> 1] >> (16 * (i & 1))), bf2f(pim[i >> 3][(i & 7) >> 1] >> (16 * (i & 1))));
;         } else {
; #pragma unroll
;             for (int i = 0; i < 64; ++i) { const int e = 7 - (i & 7); cmul_acc(er, ei, aTr, aTi, bf2f(pre[i >> 3][e >> 1] >> (16 * (e & 1))), bf2f(pim[i >> 3][e >> 1] >> (16 * (e & 1)))); }
;         }
;         asm volatile("" ::: "memory"); }
.Lsc_ctxd:
	s_barrier
	v_mov_b32_e32 v20, v10
	v_mov_b32_e32 v21, v11
	v_mov_b32_e32 v10, 0
	v_mov_b32_e32 v11, 0
	s_cmp_lg_u32 s5, 0
	s_cbranch_scc1 .Lsc_p1r1
	s_mov_b64 s[10:11], s[68:69]
	global_load_dwordx4 v[136:139], v30, s[10:11]
	global_load_dwordx4 v[140:143], v30, s[10:11] offset:1024
	s_add_u32 s10, s10, 0x1000
	s_addc_u32 s11, s11, 0
	global_load_dwordx4 v[144:147], v30, s[10:11]
	global_load_dwordx4 v[148:151], v30, s[10:11] offset:1024
	s_add_u32 s10, s10, 0x1000
	s_addc_u32 s11, s11, 0
	global_load_dwordx4 v[152:155], v30, s[10:11]
	global_load_dwordx4 v[156:159], v30, s[10:11] offset:1024
	s_add_u32 s10, s10, 0x1000
	s_addc_u32 s11, s11, 0
	global_load_dwordx4 v[160:163], v30, s[10:11]
	global_load_dwordx4 v[164:167], v30, s[10:11] offset:1024
	s_add_u32 s10, s10, 0x1000
	s_addc_u32 s11, s11, 0
	s_waitcnt vmcnt(0)
	v_mov_b32_e32 v38, v39
	s_mov_b32 s16, 2
.Lscl_p1r0_0:
	s_waitcnt vmcnt(6)
	ds_write_b128 v38, v[136:139] offset:0
	ds_write_b128 v38, v[140:143] offset:1024
	v_lshlrev_b32_e32 v16, 16, v136
	v_lshlrev_b32_e32 v17, 16, v140
	v_mul_f32_e32 v12, v249, v11
	v_mul_f32_e32 v13, v248, v11
	v_fma_f32 v14, v248, v10, -v12
	v_fma_f32 v15, v249, v10, v13
	v_add_f32_e32 v10, v14, v16
	v_add_f32_e32 v11, v15, v17
	v_and_b32_e32 v16, 0xffff0000, v136
	v_and_b32_e32 v17, 0xffff0000, v140
	v_mul_f32_e32 v12, v249, v11
	v_mul_f32_e32 v13, v248, v11
	v_fma_f32 v14, v248, v10, -v12
	v_fma_f32 v15, v249, v10, v13
	v_add_f32_e32 v10, v14, v16
	v_add_f32_e32 v11, v15, v17
	v_lshlrev_b32_e32 v16, 16, v137
	v_lshlrev_b32_e32 v17, 16, v141
	v_mul_f32_e32 v12, v249, v11
	v_mul_f32_e32 v13, v248, v11
	v_fma_f32 v14, v248, v10, -v12
	v_fma_f32 v15, v249, v10, v13
	v_add_f32_e32 v10, v14, v16
	v_add_f32_e32 v11, v15, v17
	v_and_b32_e32 v16, 0xffff0000, v137
	v_and_b32_e32 v17, 0xffff0000, v141
	v_mul_f32_e32 v12, v249, v11
	v_mul_f32_e32 v13, v248, v11
	v_fma_f32 v14, v248, v10, -v12
	v_fma_f32 v15, v249, v10, v13
	v_add_f32_e32 v10, v14, v16
	v_add_f32_e32 v11, v15, v17
	v_lshlrev_b32_e32 v16, 16, v138
	v_lshlrev_b32_e32 v17, 16, v142
	v_mul_f32_e32 v12, v249, v11
	v_mul_f32_e32 v13, v248, v11
	v_fma_f32 v14, v248, v10, -v12
	v_fma_f32 v15, v249, v10, v13
	v_add_f32_e32 v10, v14, v16
	v_add_f32_e32 v11, v15, v17
	v_and_b32_e32 v16, 0xffff0000, v138
	v_and_b32_e32 v17, 0xffff0000, v142
	v_mul_f32_e32 v12, v249, v11
	v_mul_f32_e32 v13, v248, v11
	v_fma_f32 v14, v248, v10, -v12
	v_fma_f32 v15, v249, v10, v13
	v_add_f32_e32 v10, v14, v16
	v_add_f32_e32 v11, v15, v17
	v_lshlrev_b32_e32 v16, 16, v139
	v_lshlrev_b32_e32 v17, 16, v143
	v_mul_f32_e32 v12, v249, v11
	v_mul_f32_e32 v13, v248, v11
	v_fma_f32 v14, v248, v10, -v12
	v_fma_f32 v15, v249, v10, v13
	v_add_f32_e32 v10, v14, v16
	v_add_f32_e32 v11, v15, v17
	v_and_b32_e32 v16, 0xffff0000, v139
	v_and_b32_e32 v17, 0xffff0000, v143
	v_mul_f32_e32 v12, v249, v11
	v_mul_f32_e32 v13, v248, v11
	v_fma_f32 v14, v248, v10, -v12
	v_fma_f32 v15, v249, v10, v13
	v_add_f32_e32 v10, v14, v16
	v_add_f32_e32 v11, v15, v17
	global_load_dwordx4 v[136:139], v30, s[10:11]
	global_load_dwordx4 v[140:143], v30, s[10:11] offset:1024
	s_add_u32 s10, s10, 0x1000
	s_addc_u32 s11, s11, 0
	s_waitcnt vmcnt(6)
	ds_write_b128 v38, v[144:147] offset:2048
	ds_write_b128 v38, v[148:151] offset:3072
	v_lshlrev_b32_e32 v16, 16, v144
	v_lshlrev_b32_e32 v17, 16, v148
	v_mul_f32_e32 v12, v249, v11
	v_mul_f32_e32 v13, v248, v11
	v_fma_f32 v14, v248, v10, -v12
	v_fma_f32 v15, v249, v10, v13
	v_add_f32_e32 v10, v14, v16
	v_add_f32_e32 v11, v15, v17
	v_and_b32_e32 v16, 0xffff0000, v144
	v_and_b32_e32 v17, 0xffff0000, v148
	v_mul_f32_e32 v12, v249, v11
	v_mul_f32_e32 v13, v248, v11
	v_fma_f32 v14, v248, v10, -v12
	v_fma_f32 v15, v249, v10, v13
	v_add_f32_e32 v10, v14, v16
	v_add_f32_e32 v11, v15, v17
	v_lshlrev_b32_e32 v16, 16, v145
	v_lshlrev_b32_e32 v17, 16, v149
	v_mul_f32_e32 v12, v249, v11
	v_mul_f32_e32 v13, v248, v11
	v_fma_f32 v14, v248, v10, -v12
	v_fma_f32 v15, v249, v10, v13
	v_add_f32_e32 v10, v14, v16
	v_add_f32_e32 v11, v15, v17
	v_and_b32_e32 v16, 0xffff0000, v145
	v_and_b32_e32 v17, 0xffff0000, v149
	v_mul_f32_e32 v12, v249, v11
	v_mul_f32_e32 v13, v248, v11
	v_fma_f32 v14, v248, v10, -v12
	v_fma_f32 v15, v249, v10, v13
	v_add_f32_e32 v10, v14, v16
	v_add_f32_e32 v11, v15, v17
	v_lshlrev_b32_e32 v16, 16, v146
	v_lshlrev_b32_e32 v17, 16, v150
	v_mul_f32_e32 v12, v249, v11
	v_mul_f32_e32 v13, v248, v11
	v_fma_f32 v14, v248, v10, -v12
	v_fma_f32 v15, v249, v10, v13
	v_add_f32_e32 v10, v14, v16
	v_add_f32_e32 v11, v15, v17
	v_and_b32_e32 v16, 0xffff0000, v146
	v_and_b32_e32 v17, 0xffff0000, v150
	v_mul_f32_e32 v12, v249, v11
	v_mul_f32_e32 v13, v248, v11
	v_fma_f32 v14, v248, v10, -v12
	v_fma_f32 v15, v249, v10, v13
	v_add_f32_e32 v10, v14, v16
	v_add_f32_e32 v11, v15, v17
	v_lshlrev_b32_e32 v16, 16, v147
	v_lshlrev_b32_e32 v17, 16, v151
	v_mul_f32_e32 v12, v249, v11
	v_mul_f32_e32 v13, v248, v11
	v_fma_f32 v14, v248, v10, -v12
	v_fma_f32 v15, v249, v10, v13
	v_add_f32_e32 v10, v14, v16
	v_add_f32_e32 v11, v15, v17
	v_and_b32_e32 v16, 0xffff0000, v147
	v_and_b32_e32 v17, 0xffff0000, v151
	v_mul_f32_e32 v12, v249, v11
	v_mul_f32_e32 v13, v248, v11
	v_fma_f32 v14, v248, v10, -v12
	v_fma_f32 v15, v249, v10, v13
	v_add_f32_e32 v10, v14, v16
	v_add_f32_e32 v11, v15, v17
	global_load_dwordx4 v[144:147], v30, s[10:11]
	global_load_dwordx4 v[148:151], v30, s[10:11] offset:1024
	s_add_u32 s10, s10, 0x1000
	s_addc_u32 s11, s11, 0
	s_waitcnt vmcnt(6)
; #define SCAN_LOAD(HALF) do { _Pragma("unroll") for (int k = 0; k < 8; ++k) { const int kk = r ? (15 - 8 * (HALF) - k) : (8 * (HALF) + k); pre[k] = *(const u32x4*)(re_row + 2048 * kk); pim[k] = *(const u32x4*)(im_row + 2048 * kk); } } while (0)
; __device__ __forceinline__ void scan_pair(Frame& F, const int g, const int b, unsigned long long& pt0, unsigned long long& pt1) {
;     ...
;     float er = 0.f, ei = 0.f;
; #pragma unroll
;     for (int half = 0; half < 2; ++half) { SCAN_LOAD(half);
;         if (r == 0) {
; #pragma unroll
;             for (int i = 0; i < 64; ++i) cmul_acc(er, ei, aTr, aTi, bf2f(pre[i >> 3][(i & 7) >> 1] >> (16 * (i & 1))), bf2f(pim[i >> 3][(i & 7) >> 1] >> (16 * (i & 1))));
;         } else {
; #pragma unroll
;             for (int i = 0; i < 64; ++i) { const int e = 7 - (i & 7); cmul_acc(er, ei, aTr, aTi, bf2f(pre[i >> 3][e >> 1] >> (16 * (e & 1))), bf2f(pim[i >> 3][e >> 1] >> (16 * (e & 1)))); }
;         }
;         asm volatile("" ::: "memory"); }
	ds_write_b128 v38, v[152:155] offset:4096
	ds_write_b128 v38, v[156:159] offset:5120
	v_lshlrev_b32_e32 v16, 16, v152
	v_lshlrev_b32_e32 v17, 16, v156
	v_mul_f32_e32 v12, v249, v11
	v_mul_f32_e32 v13, v248, v11
	v_fma_f32 v14, v248, v10, -v12
	v_fma_f32 v15, v249, v10, v13
	v_add_f32_e32 v10, v14, v16
	v_add_f32_e32 v11, v15, v17
	v_and_b32_e32 v16, 0xffff0000, v152
	v_and_b32_e32 v17, 0xffff0000, v156
	v_mul_f32_e32 v12, v249, v11
	v_mul_f32_e32 v13, v248, v11
	v_fma_f32 v14, v248, v10, -v12
	v_fma_f32 v15, v249, v10, v13
	v_add_f32_e32 v10, v14, v16
	v_add_f32_e32 v11, v15, v17
	v_lshlrev_b32_e32 v16, 16, v153
	v_lshlrev_b32_e32 v17, 16, v157
	v_mul_f32_e32 v12, v249, v11
	v_mul_f32_e32 v13, v248, v11
	v_fma_f32 v14, v248, v10, -v12
	v_fma_f32 v15, v249, v10, v13
	v_add_f32_e32 v10, v14, v16
	v_add_f32_e32 v11, v15, v17
	v_and_b32_e32 v16, 0xffff0000, v153
	v_and_b32_e32 v17, 0xffff0000, v157
	v_mul_f32_e32 v12, v249, v11
	v_mul_f32_e32 v13, v248, v11
	v_fma_f32 v14, v248, v10, -v12
	v_fma_f32 v15, v249, v10, v13
	v_add_f32_e32 v10, v14, v16
	v_add_f32_e32 v11, v15, v17
	v_lshlrev_b32_e32 v16, 16, v154
	v_lshlrev_b32_e32 v17, 16, v158
	v_mul_f32_e32 v12, v249, v11
	v_mul_f32_e32 v13, v248, v11
	v_fma_f32 v14, v248, v10, -v12
	v_fma_f32 v15, v249, v10, v13
	v_add_f32_e32 v10, v14, v16
	v_add_f32_e32 v11, v15, v17
	v_and_b32_e32 v16, 0xffff0000, v154
	v_and_b32_e32 v17, 0xffff0000, v158
	v_mul_f32_e32 v12, v249, v11
	v_mul_f32_e32 v13, v248, v11
	v_fma_f32 v14, v248, v10, -v12
	v_fma_f32 v15, v249, v10, v13
	v_add_f32_e32 v10, v14, v16
	v_add_f32_e32 v11, v15, v17
	v_lshlrev_b32_e32 v16, 16, v155
	v_lshlrev_b32_e32 v17, 16, v159
	v_mul_f32_e32 v12, v249, v11
	v_mul_f32_e32 v13, v248, v11
	v_fma_f32 v14, v248, v10, -v12
	v_fma_f32 v15, v249, v10, v13
	v_add_f32_e32 v10, v14, v16
	v_add_f32_e32 v11, v15, v17
	v_and_b32_e32 v16, 0xffff0000, v155
	v_and_b32_e32 v17, 0xffff0000, v159
	v_mul_f32_e32 v12, v249, v11
	v_mul_f32_e32 v13, v248, v11
	v_fma_f32 v14, v248, v10, -v12
	v_fma_f32 v15, v249, v10, v13
	v_add_f32_e32 v10, v14, v16
	v_add_f32_e32 v11, v15, v17
	global_load_dwordx4 v[152:155], v30, s[10:11]
	global_load_dwordx4 v[156:159], v30, s[10:11] offset:1024
	s_add_u32 s10, s10, 0x1000
	s_addc_u32 s11, s11, 0
	s_waitcnt vmcnt(6)
	ds_write_b128 v38, v[160:163] offset:6144
	ds_write_b128 v38, v[164:167] offset:7168
	v_lshlrev_b32_e32 v16, 16, v160
	v_lshlrev_b32_e32 v17, 16, v164
	v_mul_f32_e32 v12, v249, v11
	v_mul_f32_e32 v13, v248, v11
	v_fma_f32 v14, v248, v10, -v12
	v_fma_f32 v15, v249, v10, v13
	v_add_f32_e32 v10, v14, v16
	v_add_f32_e32 v11, v15, v17
	v_and_b32_e32 v16, 0xffff0000, v160
	v_and_b32_e32 v17, 0xffff0000, v164
	v_mul_f32_e32 v12, v249, v11
	v_mul_f32_e32 v13, v248, v11
	v_fma_f32 v14, v248, v10, -v12
	v_fma_f32 v15, v249, v10, v13
	v_add_f32_e32 v10, v14, v16
	v_add_f32_e32 v11, v15, v17
	v_lshlrev_b32_e32 v16, 16, v161
	v_lshlrev_b32_e32 v17, 16, v165
	v_mul_f32_e32 v12, v249, v11
	v_mul_f32_e32 v13, v248, v11
	v_fma_f32 v14, v248, v10, -v12
	v_fma_f32 v15, v249, v10, v13
	v_add_f32_e32 v10, v14, v16
	v_add_f32_e32 v11, v15, v17
	v_and_b32_e32 v16, 0xffff0000, v161
	v_and_b32_e32 v17, 0xffff0000, v165
	v_mul_f32_e32 v12, v249, v11
	v_mul_f32_e32 v13, v248, v11
	v_fma_f32 v14, v248, v10, -v12
	v_fma_f32 v15, v249, v10, v13
	v_add_f32_e32 v10, v14, v16
	v_add_f32_e32 v11, v15, v17
	v_lshlrev_b32_e32 v16, 16, v162
	v_lshlrev_b32_e32 v17, 16, v166
	v_mul_f32_e32 v12, v249, v11
	v_mul_f32_e32 v13, v248, v11
	v_fma_f32 v14, v248, v10, -v12
	v_fma_f32 v15, v249, v10, v13
	v_add_f32_e32 v10, v14, v16
	v_add_f32_e32 v11, v15, v17
	v_and_b32_e32 v16, 0xffff0000, v162
	v_and_b32_e32 v17, 0xffff0000, v166
	v_mul_f32_e32 v12, v249, v11
	v_mul_f32_e32 v13, v248, v11
	v_fma_f32 v14, v248, v10, -v12
	v_fma_f32 v15, v249, v10, v13
	v_add_f32_e32 v10, v14, v16
	v_add_f32_e32 v11, v15, v17
	v_lshlrev_b32_e32 v16, 16, v163
	v_lshlrev_b32_e32 v17, 16, v167
	v_mul_f32_e32 v12, v249, v11
	v_mul_f32_e32 v13, v248, v11
	v_fma_f32 v14, v248, v10, -v12
	v_fma_f32 v15, v249, v10, v13
	v_add_f32_e32 v10, v14, v16
	v_add_f32_e32 v11, v15, v17
	v_and_b32_e32 v16, 0xffff0000, v163
	v_and_b32_e32 v17, 0xffff0000, v167
	v_mul_f32_e32 v12, v249, v11
	v_mul_f32_e32 v13, v248, v11
	v_fma_f32 v14, v248, v10, -v12
	v_fma_f32 v15, v249, v10, v13
	v_add_f32_e32 v10, v14, v16
	v_add_f32_e32 v11, v15, v17
	global_load_dwordx4 v[160:163], v30, s[10:11]
	global_load_dwordx4 v[164:167], v30, s[10:11] offset:1024
	s_add_u32 s10, s10, 0x1000
	s_addc_u32 s11, s11, 0
	v_add_u32_e32 v38, 0x2000, v38
	s_sub_i32 s16, s16, 1
	s_cmp_lg_u32 s16, 0
	s_cbranch_scc1 .Lscl_p1r0_0
	s_mov_b32 s16, 2
; #define SCAN_LOAD(HALF) do { _Pragma("unroll") for (int k = 0; k < 8; ++k) { const int kk = r ? (15 - 8 * (HALF) - k) : (8 * (HALF) + k); pre[k] = *(const u32x4*)(re_row + 2048 * kk); pim[k] = *(const u32x4*)(im_row + 2048 * kk); } } while (0)
; __device__ __forceinline__ void scan_pair(Frame& F, const int g, const int b, unsigned long long& pt0, unsigned long long& pt1) {
;     ...
;     float er = 0.f, ei = 0.f;
; #pragma unroll
;     for (int half = 0; half < 2; ++half) { SCAN_LOAD(half);
;         if (r == 0) {
; #pragma unroll
;             for (int i = 0; i < 64; ++i) cmul_acc(er, ei, aTr, aTi, bf2f(pre[i >> 3][(i & 7) >> 1] >> (16 * (i & 1))), bf2f(pim[i >> 3][(i & 7) >> 1] >> (16 * (i & 1))));
;         } else {
; #pragma unroll
;             for (int i = 0; i < 64; ++i) { const int e = 7 - (i & 7); cmul_acc(er, ei, aTr, aTi, bf2f(pre[i >> 3][e >> 1] >> (16 * (e & 1))), bf2f(pim[i >> 3][e >> 1] >> (16 * (e & 1)))); }
;         }
;         asm volatile("" ::: "memory"); }
.Lscl_p1r0_1:
	s_waitcnt vmcnt(6)
	v_lshlrev_b32_e32 v16, 16, v136
	v_lshlrev_b32_e32 v17, 16, v140
	v_mul_f32_e32 v12, v249, v11
	v_mul_f32_e32 v13, v248, v11
	v_fma_f32 v14, v248, v10, -v12
	v_fma_f32 v15, v249, v10, v13
	v_add_f32_e32 v10, v14, v16
	v_add_f32_e32 v11, v15, v17
	v_and_b32_e32 v16, 0xffff0000, v136
	v_and_b32_e32 v17, 0xffff0000, v140
	v_mul_f32_e32 v12, v249, v11
	v_mul_f32_e32 v13, v248, v11
	v_fma_f32 v14, v248, v10, -v12
	v_fma_f32 v15, v249, v10, v13
	v_add_f32_e32 v10, v14, v16
	v_add_f32_e32 v11, v15, v17
	v_lshlrev_b32_e32 v16, 16, v137
	v_lshlrev_b32_e32 v17, 16, v141
	v_mul_f32_e32 v12, v249, v11
	v_mul_f32_e32 v13, v248, v11
	v_fma_f32 v14, v248, v10, -v12
	v_fma_f32 v15, v249, v10, v13
	v_add_f32_e32 v10, v14, v16
	v_add_f32_e32 v11, v15, v17
	v_and_b32_e32 v16, 0xffff0000, v137
	v_and_b32_e32 v17, 0xffff0000, v141
	v_mul_f32_e32 v12, v249, v11
	v_mul_f32_e32 v13, v248, v11
	v_fma_f32 v14, v248, v10, -v12
	v_fma_f32 v15, v249, v10, v13
	v_add_f32_e32 v10, v14, v16
	v_add_f32_e32 v11, v15, v17
	v_lshlrev_b32_e32 v16, 16, v138
	v_lshlrev_b32_e32 v17, 16, v142
	v_mul_f32_e32 v12, v249, v11
	v_mul_f32_e32 v13, v248, v11
	v_fma_f32 v14, v248, v10, -v12
	v_fma_f32 v15, v249, v10, v13
	v_add_f32_e32 v10, v14, v16
	v_add_f32_e32 v11, v15, v17
	v_and_b32_e32 v16, 0xffff0000, v138
	v_and_b32_e32 v17, 0xffff0000, v142
	v_mul_f32_e32 v12, v249, v11
	v_mul_f32_e32 v13, v248, v11
	v_fma_f32 v14, v248, v10, -v12
	v_fma_f32 v15, v249, v10, v13
	v_add_f32_e32 v10, v14, v16
	v_add_f32_e32 v11, v15, v17
	v_lshlrev_b32_e32 v16, 16, v139
	v_lshlrev_b32_e32 v17, 16, v143
	v_mul_f32_e32 v12, v249, v11
	v_mul_f32_e32 v13, v248, v11
	v_fma_f32 v14, v248, v10, -v12
	v_fma_f32 v15, v249, v10, v13
	v_add_f32_e32 v10, v14, v16
	v_add_f32_e32 v11, v15, v17
	v_and_b32_e32 v16, 0xffff0000, v139
	v_and_b32_e32 v17, 0xffff0000, v143
	v_mul_f32_e32 v12, v249, v11
	v_mul_f32_e32 v13, v248, v11
	v_fma_f32 v14, v248, v10, -v12
	v_fma_f32 v15, v249, v10, v13
	v_add_f32_e32 v10, v14, v16
	v_add_f32_e32 v11, v15, v17
	global_load_dwordx4 v[136:139], v30, s[10:11]
	global_load_dwordx4 v[140:143], v30, s[10:11] offset:1024
	s_add_u32 s10, s10, 0x1000
	s_addc_u32 s11, s11, 0
	s_waitcnt vmcnt(6)
	v_lshlrev_b32_e32 v16, 16, v144
	v_lshlrev_b32_e32 v17, 16, v148
	v_mul_f32_e32 v12, v249, v11
	v_mul_f32_e32 v13, v248, v11
	v_fma_f32 v14, v248, v10, -v12
	v_fma_f32 v15, v249, v10, v13
	v_add_f32_e32 v10, v14, v16
	v_add_f32_e32 v11, v15, v17
	v_and_b32_e32 v16, 0xffff0000, v144
	v_and_b32_e32 v17, 0xffff0000, v148
	v_mul_f32_e32 v12, v249, v11
	v_mul_f32_e32 v13, v248, v11
	v_fma_f32 v14, v248, v10, -v12
	v_fma_f32 v15, v249, v10, v13
	v_add_f32_e32 v10, v14, v16
	v_add_f32_e32 v11, v15, v17
	v_lshlrev_b32_e32 v16, 16, v145
	v_lshlrev_b32_e32 v17, 16, v149
	v_mul_f32_e32 v12, v249, v11
	v_mul_f32_e32 v13, v248, v11
	v_fma_f32 v14, v248, v10, -v12
	v_fma_f32 v15, v249, v10, v13
	v_add_f32_e32 v10, v14, v16
	v_add_f32_e32 v11, v15, v17
	v_and_b32_e32 v16, 0xffff0000, v145
	v_and_b32_e32 v17, 0xffff0000, v149
	v_mul_f32_e32 v12, v249, v11
	v_mul_f32_e32 v13, v248, v11
	v_fma_f32 v14, v248, v10, -v12
	v_fma_f32 v15, v249, v10, v13
	v_add_f32_e32 v10, v14, v16
	v_add_f32_e32 v11, v15, v17
	v_lshlrev_b32_e32 v16, 16, v146
	v_lshlrev_b32_e32 v17, 16, v150
	v_mul_f32_e32 v12, v249, v11
	v_mul_f32_e32 v13, v248, v11
	v_fma_f32 v14, v248, v10, -v12
	v_fma_f32 v15, v249, v10, v13
	v_add_f32_e32 v10, v14, v16
	v_add_f32_e32 v11, v15, v17
	v_and_b32_e32 v16, 0xffff0000, v146
	v_and_b32_e32 v17, 0xffff0000, v150
	v_mul_f32_e32 v12, v249, v11
	v_mul_f32_e32 v13, v248, v11
	v_fma_f32 v14, v248, v10, -v12
	v_fma_f32 v15, v249, v10, v13
	v_add_f32_e32 v10, v14, v16
	v_add_f32_e32 v11, v15, v17
	v_lshlrev_b32_e32 v16, 16, v147
	v_lshlrev_b32_e32 v17, 16, v151
	v_mul_f32_e32 v12, v249, v11
	v_mul_f32_e32 v13, v248, v11
	v_fma_f32 v14, v248, v10, -v12
	v_fma_f32 v15, v249, v10, v13
	v_add_f32_e32 v10, v14, v16
	v_add_f32_e32 v11, v15, v17
	v_and_b32_e32 v16, 0xffff0000, v147
	v_and_b32_e32 v17, 0xffff0000, v151
	v_mul_f32_e32 v12, v249, v11
	v_mul_f32_e32 v13, v248, v11
	v_fma_f32 v14, v248, v10, -v12
	v_fma_f32 v15, v249, v10, v13
	v_add_f32_e32 v10, v14, v16
	v_add_f32_e32 v11, v15, v17
	global_load_dwordx4 v[144:147], v30, s[10:11]
	global_load_dwordx4 v[148:151], v30, s[10:11] offset:1024
	s_add_u32 s10, s10, 0x1000
	s_addc_u32 s11, s11, 0
	s_waitcnt vmcnt(6)
	v_lshlrev_b32_e32 v16, 16, v152
	v_lshlrev_b32_e32 v17, 16, v156
	v_mul_f32_e32 v12, v249, v11
	v_mul_f32_e32 v13, v248, v11
	v_fma_f32 v14, v248, v10, -v12
	v_fma_f32 v15, v249, v10, v13
	v_add_f32_e32 v10, v14, v16
	v_add_f32_e32 v11, v15, v17
	v_and_b32_e32 v16, 0xffff0000, v152
	v_and_b32_e32 v17, 0xffff0000, v156
	v_mul_f32_e32 v12, v249, v11
	v_mul_f32_e32 v13, v248, v11
	v_fma_f32 v14, v248, v10, -v12
	v_fma_f32 v15, v249, v10, v13
	v_add_f32_e32 v10, v14, v16
	v_add_f32_e32 v11, v15, v17
	v_lshlrev_b32_e32 v16, 16, v153
	v_lshlrev_b32_e32 v17, 16, v157
	v_mul_f32_e32 v12, v249, v11
	v_mul_f32_e32 v13, v248, v11
	v_fma_f32 v14, v248, v10, -v12
	v_fma_f32 v15, v249, v10, v13
	v_add_f32_e32 v10, v14, v16
	v_add_f32_e32 v11, v15, v17
	v_and_b32_e32 v16, 0xffff0000, v153
	v_and_b32_e32 v17, 0xffff0000, v157
	v_mul_f32_e32 v12, v249, v11
	v_mul_f32_e32 v13, v248, v11
	v_fma_f32 v14, v248, v10, -v12
	v_fma_f32 v15, v249, v10, v13
	v_add_f32_e32 v10, v14, v16
	v_add_f32_e32 v11, v15, v17
	v_lshlrev_b32_e32 v16, 16, v154
	v_lshlrev_b32_e32 v17, 16, v158
	v_mul_f32_e32 v12, v249, v11
	v_mul_f32_e32 v13, v248, v11
	v_fma_f32 v14, v248, v10, -v12
	v_fma_f32 v15, v249, v10, v13
	v_add_f32_e32 v10, v14, v16
	v_add_f32_e32 v11, v15, v17
	v_and_b32_e32 v16, 0xffff0000, v154
	v_and_b32_e32 v17, 0xffff0000, v158
	v_mul_f32_e32 v12, v249, v11
	v_mul_f32_e32 v13, v248, v11
	v_fma_f32 v14, v248, v10, -v12
	v_fma_f32 v15, v249, v10, v13
	v_add_f32_e32 v10, v14, v16
	v_add_f32_e32 v11, v15, v17
	v_lshlrev_b32_e32 v16, 16, v155
	v_lshlrev_b32_e32 v17, 16, v159
	v_mul_f32_e32 v12, v249, v11
	v_mul_f32_e32 v13, v248, v11
	v_fma_f32 v14, v248, v10, -v12
	v_fma_f32 v15, v249, v10, v13
	v_add_f32_e32 v10, v14, v16
	v_add_f32_e32 v11, v15, v17
	v_and_b32_e32 v16, 0xffff0000, v155
	v_and_b32_e32 v17, 0xffff0000, v159
	v_mul_f32_e32 v12, v249, v11
	v_mul_f32_e32 v13, v248, v11
	v_fma_f32 v14, v248, v10, -v12
	v_fma_f32 v15, v249, v10, v13
	v_add_f32_e32 v10, v14, v16
	v_add_f32_e32 v11, v15, v17
	global_load_dwordx4 v[152:155], v30, s[10:11]
	global_load_dwordx4 v[156:159], v30, s[10:11] offset:1024
	s_add_u32 s10, s10, 0x1000
	s_addc_u32 s11, s11, 0
	s_waitcnt vmcnt(6)
; #define SCAN_LOAD(HALF) do { _Pragma("unroll") for (int k = 0; k < 8; ++k) { const int kk = r ? (15 - 8 * (HALF) - k) : (8 * (HALF) + k); pre[k] = *(const u32x4*)(re_row + 2048 * kk); pim[k] = *(const u32x4*)(im_row + 2048 * kk); } } while (0)
; __device__ __forceinline__ void scan_pair(Frame& F, const int g, const int b, unsigned long long& pt0, unsigned long long& pt1) {
;     ...
;     float er = 0.f, ei = 0.f;
; #pragma unroll
;     for (int half = 0; half < 2; ++half) { SCAN_LOAD(half);
;         if (r == 0) {
; #pragma unroll
;             for (int i = 0; i < 64; ++i) cmul_acc(er, ei, aTr, aTi, bf2f(pre[i >> 3][(i & 7) >> 1] >> (16 * (i & 1))), bf2f(pim[i >> 3][(i & 7) >> 1] >> (16 * (i & 1))));
;         } else {
; #pragma unroll
;             for (int i = 0; i < 64; ++i) { const int e = 7 - (i & 7); cmul_acc(er, ei, aTr, aTi, bf2f(pre[i >> 3][e >> 1] >> (16 * (e & 1))), bf2f(pim[i >> 3][e >> 1] >> (16 * (e & 1)))); }
;         }
;         asm volatile("" ::: "memory"); }
	v_lshlrev_b32_e32 v16, 16, v160
	v_lshlrev_b32_e32 v17, 16, v164
	v_mul_f32_e32 v12, v249, v11
	v_mul_f32_e32 v13, v248, v11
	v_fma_f32 v14, v248, v10, -v12
	v_fma_f32 v15, v249, v10, v13
	v_add_f32_e32 v10, v14, v16
	v_add_f32_e32 v11, v15, v17
	v_and_b32_e32 v16, 0xffff0000, v160
	v_and_b32_e32 v17, 0xffff0000, v164
	v_mul_f32_e32 v12, v249, v11
	v_mul_f32_e32 v13, v248, v11
	v_fma_f32 v14, v248, v10, -v12
	v_fma_f32 v15, v249, v10, v13
	v_add_f32_e32 v10, v14, v16
	v_add_f32_e32 v11, v15, v17
	v_lshlrev_b32_e32 v16, 16, v161
	v_lshlrev_b32_e32 v17, 16, v165
	v_mul_f32_e32 v12, v249, v11
	v_mul_f32_e32 v13, v248, v11
	v_fma_f32 v14, v248, v10, -v12
	v_fma_f32 v15, v249, v10, v13
	v_add_f32_e32 v10, v14, v16
	v_add_f32_e32 v11, v15, v17
	v_and_b32_e32 v16, 0xffff0000, v161
	v_and_b32_e32 v17, 0xffff0000, v165
	v_mul_f32_e32 v12, v249, v11
	v_mul_f32_e32 v13, v248, v11
	v_fma_f32 v14, v248, v10, -v12
	v_fma_f32 v15, v249, v10, v13
	v_add_f32_e32 v10, v14, v16
	v_add_f32_e32 v11, v15, v17
	v_lshlrev_b32_e32 v16, 16, v162
	v_lshlrev_b32_e32 v17, 16, v166
	v_mul_f32_e32 v12, v249, v11
	v_mul_f32_e32 v13, v248, v11
	v_fma_f32 v14, v248, v10, -v12
	v_fma_f32 v15, v249, v10, v13
	v_add_f32_e32 v10, v14, v16
	v_add_f32_e32 v11, v15, v17
	v_and_b32_e32 v16, 0xffff0000, v162
	v_and_b32_e32 v17, 0xffff0000, v166
	v_mul_f32_e32 v12, v249, v11
	v_mul_f32_e32 v13, v248, v11
	v_fma_f32 v14, v248, v10, -v12
	v_fma_f32 v15, v249, v10, v13
	v_add_f32_e32 v10, v14, v16
	v_add_f32_e32 v11, v15, v17
	v_lshlrev_b32_e32 v16, 16, v163
	v_lshlrev_b32_e32 v17, 16, v167
	v_mul_f32_e32 v12, v249, v11
	v_mul_f32_e32 v13, v248, v11
	v_fma_f32 v14, v248, v10, -v12
	v_fma_f32 v15, v249, v10, v13
	v_add_f32_e32 v10, v14, v16
	v_add_f32_e32 v11, v15, v17
	v_and_b32_e32 v16, 0xffff0000, v163
	v_and_b32_e32 v17, 0xffff0000, v167
	v_mul_f32_e32 v12, v249, v11
	v_mul_f32_e32 v13, v248, v11
	v_fma_f32 v14, v248, v10, -v12
	v_fma_f32 v15, v249, v10, v13
	v_add_f32_e32 v10, v14, v16
	v_add_f32_e32 v11, v15, v17
	global_load_dwordx4 v[160:163], v30, s[10:11]
	global_load_dwordx4 v[164:167], v30, s[10:11] offset:1024
	s_add_u32 s10, s10, 0x1000
	s_addc_u32 s11, s11, 0
	s_sub_i32 s16, s16, 1
	s_cmp_lg_u32 s16, 0
	s_cbranch_scc1 .Lscl_p1r0_1
	s_waitcnt vmcnt(0)
	s_branch .Lsc_mid
.Lsc_p1r1:
	s_mov_b64 s[10:11], s[68:69]
	global_load_dwordx4 v[136:139], v30, s[10:11]
	global_load_dwordx4 v[140:143], v30, s[10:11] offset:1024
	s_sub_u32 s10, s10, 0x1000
	s_subb_u32 s11, s11, 0
	global_load_dwordx4 v[144:147], v30, s[10:11]
	global_load_dwordx4 v[148:151], v30, s[10:11] offset:1024
	s_sub_u32 s10, s10, 0x1000
	s_subb_u32 s11, s11, 0
	global_load_dwordx4 v[152:155], v30, s[10:11]
	global_load_dwordx4 v[156:159], v30, s[10:11] offset:1024
	s_sub_u32 s10, s10, 0x1000
	s_subb_u32 s11, s11, 0
	global_load_dwordx4 v[160:163], v30, s[10:11]
	global_load_dwordx4 v[164:167], v30, s[10:11] offset:1024
	s_sub_u32 s10, s10, 0x1000
	s_subb_u32 s11, s11, 0
	s_waitcnt vmcnt(0)
	v_mov_b32_e32 v38, v39
	s_mov_b32 s16, 2
.Lscl_p1r1_0:
	s_waitcnt vmcnt(6)
	ds_write_b128 v38, v[136:139] offset:0
	ds_write_b128 v38, v[140:143] offset:1024
	v_and_b32_e32 v16, 0xffff0000, v139
	v_and_b32_e32 v17, 0xffff0000, v143
	v_mul_f32_e32 v12, v249, v11
	v_mul_f32_e32 v13, v248, v11
	v_fma_f32 v14, v248, v10, -v12
	v_fma_f32 v15, v249, v10, v13
	v_add_f32_e32 v10, v14, v16
	v_add_f32_e32 v11, v15, v17
	v_lshlrev_b32_e32 v16, 16, v139
	v_lshlrev_b32_e32 v17, 16, v143
	v_mul_f32_e32 v12, v249, v11
	v_mul_f32_e32 v13, v248, v11
	v_fma_f32 v14, v248, v10, -v12
	v_fma_f32 v15, v249, v10, v13
	v_add_f32_e32 v10, v14, v16
	v_add_f32_e32 v11, v15, v17
	v_and_b32_e32 v16, 0xffff0000, v138
	v_and_b32_e32 v17, 0xffff0000, v142
	v_mul_f32_e32 v12, v249, v11
	v_mul_f32_e32 v13, v248, v11
	v_fma_f32 v14, v248, v10, -v12
	v_fma_f32 v15, v249, v10, v13
	v_add_f32_e32 v10, v14, v16
	v_add_f32_e32 v11, v15, v17
	v_lshlrev_b32_e32 v16, 16, v138
	v_lshlrev_b32_e32 v17, 16, v142
	v_mul_f32_e32 v12, v249, v11
	v_mul_f32_e32 v13, v248, v11
	v_fma_f32 v14, v248, v10, -v12
	v_fma_f32 v15, v249, v10, v13
	v_add_f32_e32 v10, v14, v16
	v_add_f32_e32 v11, v15, v17
	v_and_b32_e32 v16, 0xffff0000, v137
	v_and_b32_e32 v17, 0xffff0000, v141
	v_mul_f32_e32 v12, v249, v11
	v_mul_f32_e32 v13, v248, v11
	v_fma_f32 v14, v248, v10, -v12
	v_fma_f32 v15, v249, v10, v13
	v_add_f32_e32 v10, v14, v16
	v_add_f32_e32 v11, v15, v17
	v_lshlrev_b32_e32 v16, 16, v137
	v_lshlrev_b32_e32 v17, 16, v141
	v_mul_f32_e32 v12, v249, v11
	v_mul_f32_e32 v13, v248, v11
	v_fma_f32 v14, v248, v10, -v12
	v_fma_f32 v15, v249, v10, v13
	v_add_f32_e32 v10, v14, v16
	v_add_f32_e32 v11, v15, v17
	v_and_b32_e32 v16, 0xffff0000, v136
	v_and_b32_e32 v17, 0xffff0000, v140
	v_mul_f32_e32 v12, v249, v11
	v_mul_f32_e32 v13, v248, v11
	v_fma_f32 v14, v248, v10, -v12
	v_fma_f32 v15, v249, v10, v13
	v_add_f32_e32 v10, v14, v16
	v_add_f32_e32 v11, v15, v17
	v_lshlrev_b32_e32 v16, 16, v136
	v_lshlrev_b32_e32 v17, 16, v140
	v_mul_f32_e32 v12, v249, v11
	v_mul_f32_e32 v13, v248, v11
	v_fma_f32 v14, v248, v10, -v12
	v_fma_f32 v15, v249, v10, v13
	v_add_f32_e32 v10, v14, v16
	v_add_f32_e32 v11, v15, v17
	global_load_dwordx4 v[136:139], v30, s[10:11]
	global_load_dwordx4 v[140:143], v30, s[10:11] offset:1024
	s_sub_u32 s10, s10, 0x1000
	s_subb_u32 s11, s11, 0
	s_waitcnt vmcnt(6)
; #define SCAN_LOAD(HALF) do { _Pragma("unroll") for (int k = 0; k < 8; ++k) { const int kk = r ? (15 - 8 * (HALF) - k) : (8 * (HALF) + k); pre[k] = *(const u32x4*)(re_row + 2048 * kk); pim[k] = *(const u32x4*)(im_row + 2048 * kk); } } while (0)
; __device__ __forceinline__ void scan_pair(Frame& F, const int g, const int b, unsigned long long& pt0, unsigned long long& pt1) {
;     ...
;     float er = 0.f, ei = 0.f;
; #pragma unroll
;     for (int half = 0; half < 2; ++half) { SCAN_LOAD(half);
;         if (r == 0) {
; #pragma unroll
;             for (int i = 0; i < 64; ++i) cmul_acc(er, ei, aTr, aTi, bf2f(pre[i >> 3][(i & 7) >> 1] >> (16 * (i & 1))), bf2f(pim[i >> 3][(i & 7) >> 1] >> (16 * (i & 1))));
;         } else {
; #pragma unroll
;             for (int i = 0; i < 64; ++i) { const int e = 7 - (i & 7); cmul_acc(er, ei, aTr, aTi, bf2f(pre[i >> 3][e >> 1] >> (16 * (e & 1))), bf2f(pim[i >> 3][e >> 1] >> (16 * (e & 1)))); }
;         }
;         asm volatile("" ::: "memory"); }
	ds_write_b128 v38, v[144:147] offset:2048
	ds_write_b128 v38, v[148:151] offset:3072
	v_and_b32_e32 v16, 0xffff0000, v147
	v_and_b32_e32 v17, 0xffff0000, v151
	v_mul_f32_e32 v12, v249, v11
	v_mul_f32_e32 v13, v248, v11
	v_fma_f32 v14, v248, v10, -v12
	v_fma_f32 v15, v249, v10, v13
	v_add_f32_e32 v10, v14, v16
	v_add_f32_e32 v11, v15, v17
	v_lshlrev_b32_e32 v16, 16, v147
	v_lshlrev_b32_e32 v17, 16, v151
	v_mul_f32_e32 v12, v249, v11
	v_mul_f32_e32 v13, v248, v11
	v_fma_f32 v14, v248, v10, -v12
	v_fma_f32 v15, v249, v10, v13
	v_add_f32_e32 v10, v14, v16
	v_add_f32_e32 v11, v15, v17
	v_and_b32_e32 v16, 0xffff0000, v146
	v_and_b32_e32 v17, 0xffff0000, v150
	v_mul_f32_e32 v12, v249, v11
	v_mul_f32_e32 v13, v248, v11
	v_fma_f32 v14, v248, v10, -v12
	v_fma_f32 v15, v249, v10, v13
	v_add_f32_e32 v10, v14, v16
	v_add_f32_e32 v11, v15, v17
	v_lshlrev_b32_e32 v16, 16, v146
	v_lshlrev_b32_e32 v17, 16, v150
	v_mul_f32_e32 v12, v249, v11
	v_mul_f32_e32 v13, v248, v11
	v_fma_f32 v14, v248, v10, -v12
	v_fma_f32 v15, v249, v10, v13
	v_add_f32_e32 v10, v14, v16
	v_add_f32_e32 v11, v15, v17
	v_and_b32_e32 v16, 0xffff0000, v145
	v_and_b32_e32 v17, 0xffff0000, v149
	v_mul_f32_e32 v12, v249, v11
	v_mul_f32_e32 v13, v248, v11
	v_fma_f32 v14, v248, v10, -v12
	v_fma_f32 v15, v249, v10, v13
	v_add_f32_e32 v10, v14, v16
	v_add_f32_e32 v11, v15, v17
	v_lshlrev_b32_e32 v16, 16, v145
	v_lshlrev_b32_e32 v17, 16, v149
	v_mul_f32_e32 v12, v249, v11
	v_mul_f32_e32 v13, v248, v11
	v_fma_f32 v14, v248, v10, -v12
	v_fma_f32 v15, v249, v10, v13
	v_add_f32_e32 v10, v14, v16
	v_add_f32_e32 v11, v15, v17
	v_and_b32_e32 v16, 0xffff0000, v144
	v_and_b32_e32 v17, 0xffff0000, v148
	v_mul_f32_e32 v12, v249, v11
	v_mul_f32_e32 v13, v248, v11
	v_fma_f32 v14, v248, v10, -v12
	v_fma_f32 v15, v249, v10, v13
	v_add_f32_e32 v10, v14, v16
	v_add_f32_e32 v11, v15, v17
	v_lshlrev_b32_e32 v16, 16, v144
	v_lshlrev_b32_e32 v17, 16, v148
	v_mul_f32_e32 v12, v249, v11
	v_mul_f32_e32 v13, v248, v11
	v_fma_f32 v14, v248, v10, -v12
	v_fma_f32 v15, v249, v10, v13
	v_add_f32_e32 v10, v14, v16
	v_add_f32_e32 v11, v15, v17
	global_load_dwordx4 v[144:147], v30, s[10:11]
	global_load_dwordx4 v[148:151], v30, s[10:11] offset:1024
	s_sub_u32 s10, s10, 0x1000
	s_subb_u32 s11, s11, 0
	s_waitcnt vmcnt(6)
	ds_write_b128 v38, v[152:155] offset:4096
	ds_write_b128 v38, v[156:159] offset:5120
	v_and_b32_e32 v16, 0xffff0000, v155
	v_and_b32_e32 v17, 0xffff0000, v159
	v_mul_f32_e32 v12, v249, v11
	v_mul_f32_e32 v13, v248, v11
	v_fma_f32 v14, v248, v10, -v12
	v_fma_f32 v15, v249, v10, v13
	v_add_f32_e32 v10, v14, v16
	v_add_f32_e32 v11, v15, v17
	v_lshlrev_b32_e32 v16, 16, v155
	v_lshlrev_b32_e32 v17, 16, v159
	v_mul_f32_e32 v12, v249, v11
	v_mul_f32_e32 v13, v248, v11
	v_fma_f32 v14, v248, v10, -v12
	v_fma_f32 v15, v249, v10, v13
	v_add_f32_e32 v10, v14, v16
	v_add_f32_e32 v11, v15, v17
	v_and_b32_e32 v16, 0xffff0000, v154
	v_and_b32_e32 v17, 0xffff0000, v158
	v_mul_f32_e32 v12, v249, v11
	v_mul_f32_e32 v13, v248, v11
	v_fma_f32 v14, v248, v10, -v12
	v_fma_f32 v15, v249, v10, v13
	v_add_f32_e32 v10, v14, v16
	v_add_f32_e32 v11, v15, v17
	v_lshlrev_b32_e32 v16, 16, v154
	v_lshlrev_b32_e32 v17, 16, v158
	v_mul_f32_e32 v12, v249, v11
	v_mul_f32_e32 v13, v248, v11
	v_fma_f32 v14, v248, v10, -v12
	v_fma_f32 v15, v249, v10, v13
	v_add_f32_e32 v10, v14, v16
	v_add_f32_e32 v11, v15, v17
	v_and_b32_e32 v16, 0xffff0000, v153
	v_and_b32_e32 v17, 0xffff0000, v157
	v_mul_f32_e32 v12, v249, v11
	v_mul_f32_e32 v13, v248, v11
	v_fma_f32 v14, v248, v10, -v12
	v_fma_f32 v15, v249, v10, v13
	v_add_f32_e32 v10, v14, v16
	v_add_f32_e32 v11, v15, v17
	v_lshlrev_b32_e32 v16, 16, v153
	v_lshlrev_b32_e32 v17, 16, v157
	v_mul_f32_e32 v12, v249, v11
	v_mul_f32_e32 v13, v248, v11
	v_fma_f32 v14, v248, v10, -v12
	v_fma_f32 v15, v249, v10, v13
	v_add_f32_e32 v10, v14, v16
	v_add_f32_e32 v11, v15, v17
	v_and_b32_e32 v16, 0xffff0000, v152
	v_and_b32_e32 v17, 0xffff0000, v156
	v_mul_f32_e32 v12, v249, v11
	v_mul_f32_e32 v13, v248, v11
	v_fma_f32 v14, v248, v10, -v12
	v_fma_f32 v15, v249, v10, v13
	v_add_f32_e32 v10, v14, v16
	v_add_f32_e32 v11, v15, v17
	v_lshlrev_b32_e32 v16, 16, v152
	v_lshlrev_b32_e32 v17, 16, v156
	v_mul_f32_e32 v12, v249, v11
	v_mul_f32_e32 v13, v248, v11
	v_fma_f32 v14, v248, v10, -v12
	v_fma_f32 v15, v249, v10, v13
	v_add_f32_e32 v10, v14, v16
	v_add_f32_e32 v11, v15, v17
	global_load_dwordx4 v[152:155], v30, s[10:11]
	global_load_dwordx4 v[156:159], v30, s[10:11] offset:1024
	s_sub_u32 s10, s10, 0x1000
	s_subb_u32 s11, s11, 0
	s_waitcnt vmcnt(6)
	ds_write_b128 v38, v[160:163] offset:6144
	ds_write_b128 v38, v[164:167] offset:7168
	v_and_b32_e32 v16, 0xffff0000, v163
	v_and_b32_e32 v17, 0xffff0000, v167
	v_mul_f32_e32 v12, v249, v11
	v_mul_f32_e32 v13, v248, v11
	v_fma_f32 v14, v248, v10, -v12
	v_fma_f32 v15, v249, v10, v13
	v_add_f32_e32 v10, v14, v16
	v_add_f32_e32 v11, v15, v17
	v_lshlrev_b32_e32 v16, 16, v163
	v_lshlrev_b32_e32 v17, 16, v167
	v_mul_f32_e32 v12, v249, v11
	v_mul_f32_e32 v13, v248, v11
	v_fma_f32 v14, v248, v10, -v12
	v_fma_f32 v15, v249, v10, v13
	v_add_f32_e32 v10, v14, v16
	v_add_f32_e32 v11, v15, v17
	v_and_b32_e32 v16, 0xffff0000, v162
	v_and_b32_e32 v17, 0xffff0000, v166
	v_mul_f32_e32 v12, v249, v11
	v_mul_f32_e32 v13, v248, v11
	v_fma_f32 v14, v248, v10, -v12
	v_fma_f32 v15, v249, v10, v13
	v_add_f32_e32 v10, v14, v16
	v_add_f32_e32 v11, v15, v17
	v_lshlrev_b32_e32 v16, 16, v162
	v_lshlrev_b32_e32 v17, 16, v166
	v_mul_f32_e32 v12, v249, v11
	v_mul_f32_e32 v13, v248, v11
	v_fma_f32 v14, v248, v10, -v12
	v_fma_f32 v15, v249, v10, v13
	v_add_f32_e32 v10, v14, v16
	v_add_f32_e32 v11, v15, v17
	v_and_b32_e32 v16, 0xffff0000, v161
	v_and_b32_e32 v17, 0xffff0000, v165
	v_mul_f32_e32 v12, v249, v11
	v_mul_f32_e32 v13, v248, v11
	v_fma_f32 v14, v248, v10, -v12
	v_fma_f32 v15, v249, v10, v13
	v_add_f32_e32 v10, v14, v16
	v_add_f32_e32 v11, v15, v17
	v_lshlrev_b32_e32 v16, 16, v161
	v_lshlrev_b32_e32 v17, 16, v165
	v_mul_f32_e32 v12, v249, v11
	v_mul_f32_e32 v13, v248, v11
	v_fma_f32 v14, v248, v10, -v12
	v_fma_f32 v15, v249, v10, v13
	v_add_f32_e32 v10, v14, v16
	v_add_f32_e32 v11, v15, v17
	v_and_b32_e32 v16, 0xffff0000, v160
	v_and_b32_e32 v17, 0xffff0000, v164
	v_mul_f32_e32 v12, v249, v11
	v_mul_f32_e32 v13, v248, v11
	v_fma_f32 v14, v248, v10, -v12
	v_fma_f32 v15, v249, v10, v13
	v_add_f32_e32 v10, v14, v16
	v_add_f32_e32 v11, v15, v17
	v_lshlrev_b32_e32 v16, 16, v160
	v_lshlrev_b32_e32 v17, 16, v164
	v_mul_f32_e32 v12, v249, v11
	v_mul_f32_e32 v13, v248, v11
	v_fma_f32 v14, v248, v10, -v12
	v_fma_f32 v15, v249, v10, v13
	v_add_f32_e32 v10, v14, v16
	v_add_f32_e32 v11, v15, v17
	global_load_dwordx4 v[160:163], v30, s[10:11]
	global_load_dwordx4 v[164:167], v30, s[10:11] offset:1024
	s_sub_u32 s10, s10, 0x1000
	s_subb_u32 s11, s11, 0
	v_add_u32_e32 v38, 0x2000, v38
	s_sub_i32 s16, s16, 1
	s_cmp_lg_u32 s16, 0
	s_cbranch_scc1 .Lscl_p1r1_0
	s_mov_b32 s16, 2
; #define SCAN_LOAD(HALF) do { _Pragma("unroll") for (int k = 0; k < 8; ++k) { const int kk = r ? (15 - 8 * (HALF) - k) : (8 * (HALF) + k); pre[k] = *(const u32x4*)(re_row + 2048 * kk); pim[k] = *(const u32x4*)(im_row + 2048 * kk); } } while (0)
; __device__ __forceinline__ void scan_pair(Frame& F, const int g, const int b, unsigned long long& pt0, unsigned long long& pt1) {
;     ...
;     float er = 0.f, ei = 0.f;
; #pragma unroll
;     for (int half = 0; half < 2; ++half) { SCAN_LOAD(half);
;         if (r == 0) {
; #pragma unroll
;             for (int i = 0; i < 64; ++i) cmul_acc(er, ei, aTr, aTi, bf2f(pre[i >> 3][(i & 7) >> 1] >> (16 * (i & 1))), bf2f(pim[i >> 3][(i & 7) >> 1] >> (16 * (i & 1))));
;         } else {
; #pragma unroll
;             for (int i = 0; i < 64; ++i) { const int e = 7 - (i & 7); cmul_acc(er, ei, aTr, aTi, bf2f(pre[i >> 3][e >> 1] >> (16 * (e & 1))), bf2f(pim[i >> 3][e >> 1] >> (16 * (e & 1)))); }
;         }
;         asm volatile("" ::: "memory"); }
.Lscl_p1r1_1:
	s_waitcnt vmcnt(6)
	v_and_b32_e32 v16, 0xffff0000, v139
	v_and_b32_e32 v17, 0xffff0000, v143
	v_mul_f32_e32 v12, v249, v11
	v_mul_f32_e32 v13, v248, v11
	v_fma_f32 v14, v248, v10, -v12
	v_fma_f32 v15, v249, v10, v13
	v_add_f32_e32 v10, v14, v16
	v_add_f32_e32 v11, v15, v17
	v_lshlrev_b32_e32 v16, 16, v139
	v_lshlrev_b32_e32 v17, 16, v143
	v_mul_f32_e32 v12, v249, v11
	v_mul_f32_e32 v13, v248, v11
	v_fma_f32 v14, v248, v10, -v12
	v_fma_f32 v15, v249, v10, v13
	v_add_f32_e32 v10, v14, v16
	v_add_f32_e32 v11, v15, v17
	v_and_b32_e32 v16, 0xffff0000, v138
	v_and_b32_e32 v17, 0xffff0000, v142
	v_mul_f32_e32 v12, v249, v11
	v_mul_f32_e32 v13, v248, v11
	v_fma_f32 v14, v248, v10, -v12
	v_fma_f32 v15, v249, v10, v13
	v_add_f32_e32 v10, v14, v16
	v_add_f32_e32 v11, v15, v17
	v_lshlrev_b32_e32 v16, 16, v138
	v_lshlrev_b32_e32 v17, 16, v142
	v_mul_f32_e32 v12, v249, v11
	v_mul_f32_e32 v13, v248, v11
	v_fma_f32 v14, v248, v10, -v12
	v_fma_f32 v15, v249, v10, v13
	v_add_f32_e32 v10, v14, v16
	v_add_f32_e32 v11, v15, v17
	v_and_b32_e32 v16, 0xffff0000, v137
	v_and_b32_e32 v17, 0xffff0000, v141
	v_mul_f32_e32 v12, v249, v11
	v_mul_f32_e32 v13, v248, v11
	v_fma_f32 v14, v248, v10, -v12
	v_fma_f32 v15, v249, v10, v13
	v_add_f32_e32 v10, v14, v16
	v_add_f32_e32 v11, v15, v17
	v_lshlrev_b32_e32 v16, 16, v137
	v_lshlrev_b32_e32 v17, 16, v141
	v_mul_f32_e32 v12, v249, v11
	v_mul_f32_e32 v13, v248, v11
	v_fma_f32 v14, v248, v10, -v12
	v_fma_f32 v15, v249, v10, v13
	v_add_f32_e32 v10, v14, v16
	v_add_f32_e32 v11, v15, v17
	v_and_b32_e32 v16, 0xffff0000, v136
	v_and_b32_e32 v17, 0xffff0000, v140
	v_mul_f32_e32 v12, v249, v11
	v_mul_f32_e32 v13, v248, v11
	v_fma_f32 v14, v248, v10, -v12
	v_fma_f32 v15, v249, v10, v13
	v_add_f32_e32 v10, v14, v16
	v_add_f32_e32 v11, v15, v17
	v_lshlrev_b32_e32 v16, 16, v136
	v_lshlrev_b32_e32 v17, 16, v140
	v_mul_f32_e32 v12, v249, v11
	v_mul_f32_e32 v13, v248, v11
	v_fma_f32 v14, v248, v10, -v12
	v_fma_f32 v15, v249, v10, v13
	v_add_f32_e32 v10, v14, v16
	v_add_f32_e32 v11, v15, v17
	global_load_dwordx4 v[136:139], v30, s[10:11]
	global_load_dwordx4 v[140:143], v30, s[10:11] offset:1024
	s_sub_u32 s10, s10, 0x1000
	s_subb_u32 s11, s11, 0
	s_waitcnt vmcnt(6)
	v_and_b32_e32 v16, 0xffff0000, v147
	v_and_b32_e32 v17, 0xffff0000, v151
	v_mul_f32_e32 v12, v249, v11
	v_mul_f32_e32 v13, v248, v11
	v_fma_f32 v14, v248, v10, -v12
	v_fma_f32 v15, v249, v10, v13
	v_add_f32_e32 v10, v14, v16
	v_add_f32_e32 v11, v15, v17
	v_lshlrev_b32_e32 v16, 16, v147
	v_lshlrev_b32_e32 v17, 16, v151
	v_mul_f32_e32 v12, v249, v11
	v_mul_f32_e32 v13, v248, v11
	v_fma_f32 v14, v248, v10, -v12
	v_fma_f32 v15, v249, v10, v13
	v_add_f32_e32 v10, v14, v16
	v_add_f32_e32 v11, v15, v17
	v_and_b32_e32 v16, 0xffff0000, v146
	v_and_b32_e32 v17, 0xffff0000, v150
	v_mul_f32_e32 v12, v249, v11
	v_mul_f32_e32 v13, v248, v11
	v_fma_f32 v14, v248, v10, -v12
	v_fma_f32 v15, v249, v10, v13
	v_add_f32_e32 v10, v14, v16
	v_add_f32_e32 v11, v15, v17
	v_lshlrev_b32_e32 v16, 16, v146
	v_lshlrev_b32_e32 v17, 16, v150
	v_mul_f32_e32 v12, v249, v11
	v_mul_f32_e32 v13, v248, v11
	v_fma_f32 v14, v248, v10, -v12
	v_fma_f32 v15, v249, v10, v13
	v_add_f32_e32 v10, v14, v16
	v_add_f32_e32 v11, v15, v17
	v_and_b32_e32 v16, 0xffff0000, v145
	v_and_b32_e32 v17, 0xffff0000, v149
	v_mul_f32_e32 v12, v249, v11
	v_mul_f32_e32 v13, v248, v11
	v_fma_f32 v14, v248, v10, -v12
	v_fma_f32 v15, v249, v10, v13
	v_add_f32_e32 v10, v14, v16
	v_add_f32_e32 v11, v15, v17
	v_lshlrev_b32_e32 v16, 16, v145
	v_lshlrev_b32_e32 v17, 16, v149
	v_mul_f32_e32 v12, v249, v11
	v_mul_f32_e32 v13, v248, v11
	v_fma_f32 v14, v248, v10, -v12
	v_fma_f32 v15, v249, v10, v13
	v_add_f32_e32 v10, v14, v16
	v_add_f32_e32 v11, v15, v17
	v_and_b32_e32 v16, 0xffff0000, v144
	v_and_b32_e32 v17, 0xffff0000, v148
	v_mul_f32_e32 v12, v249, v11
	v_mul_f32_e32 v13, v248, v11
	v_fma_f32 v14, v248, v10, -v12
	v_fma_f32 v15, v249, v10, v13
	v_add_f32_e32 v10, v14, v16
	v_add_f32_e32 v11, v15, v17
	v_lshlrev_b32_e32 v16, 16, v144
	v_lshlrev_b32_e32 v17, 16, v148
	v_mul_f32_e32 v12, v249, v11
	v_mul_f32_e32 v13, v248, v11
	v_fma_f32 v14, v248, v10, -v12
	v_fma_f32 v15, v249, v10, v13
	v_add_f32_e32 v10, v14, v16
	v_add_f32_e32 v11, v15, v17
	global_load_dwordx4 v[144:147], v30, s[10:11]
	global_load_dwordx4 v[148:151], v30, s[10:11] offset:1024
	s_sub_u32 s10, s10, 0x1000
	s_subb_u32 s11, s11, 0
	s_waitcnt vmcnt(6)
; #define SCAN_LOAD(HALF) do { _Pragma("unroll") for (int k = 0; k < 8; ++k) { const int kk = r ? (15 - 8 * (HALF) - k) : (8 * (HALF) + k); pre[k] = *(const u32x4*)(re_row + 2048 * kk); pim[k] = *(const u32x4*)(im_row + 2048 * kk); } } while (0)
; __device__ __forceinline__ void scan_pair(Frame& F, const int g, const int b, unsigned long long& pt0, unsigned long long& pt1) {
;     ...
;     float er = 0.f, ei = 0.f;
; #pragma unroll
;     for (int half = 0; half < 2; ++half) { SCAN_LOAD(half);
;         if (r == 0) {
; #pragma unroll
;             for (int i = 0; i < 64; ++i) cmul_acc(er, ei, aTr, aTi, bf2f(pre[i >> 3][(i & 7) >> 1] >> (16 * (i & 1))), bf2f(pim[i >> 3][(i & 7) >> 1] >> (16 * (i & 1))));
;         } else {
; #pragma unroll
;             for (int i = 0; i < 64; ++i) { const int e = 7 - (i & 7); cmul_acc(er, ei, aTr, aTi, bf2f(pre[i >> 3][e >> 1] >> (16 * (e & 1))), bf2f(pim[i >> 3][e >> 1] >> (16 * (e & 1)))); }
;         }
;         asm volatile("" ::: "memory"); }
	v_and_b32_e32 v16, 0xffff0000, v155
	v_and_b32_e32 v17, 0xffff0000, v159
	v_mul_f32_e32 v12, v249, v11
	v_mul_f32_e32 v13, v248, v11
	v_fma_f32 v14, v248, v10, -v12
	v_fma_f32 v15, v249, v10, v13
	v_add_f32_e32 v10, v14, v16
	v_add_f32_e32 v11, v15, v17
	v_lshlrev_b32_e32 v16, 16, v155
	v_lshlrev_b32_e32 v17, 16, v159
	v_mul_f32_e32 v12, v249, v11
	v_mul_f32_e32 v13, v248, v11
	v_fma_f32 v14, v248, v10, -v12
	v_fma_f32 v15, v249, v10, v13
	v_add_f32_e32 v10, v14, v16
	v_add_f32_e32 v11, v15, v17
	v_and_b32_e32 v16, 0xffff0000, v154
	v_and_b32_e32 v17, 0xffff0000, v158
	v_mul_f32_e32 v12, v249, v11
	v_mul_f32_e32 v13, v248, v11
	v_fma_f32 v14, v248, v10, -v12
	v_fma_f32 v15, v249, v10, v13
	v_add_f32_e32 v10, v14, v16
	v_add_f32_e32 v11, v15, v17
	v_lshlrev_b32_e32 v16, 16, v154
	v_lshlrev_b32_e32 v17, 16, v158
	v_mul_f32_e32 v12, v249, v11
	v_mul_f32_e32 v13, v248, v11
	v_fma_f32 v14, v248, v10, -v12
	v_fma_f32 v15, v249, v10, v13
	v_add_f32_e32 v10, v14, v16
	v_add_f32_e32 v11, v15, v17
	v_and_b32_e32 v16, 0xffff0000, v153
	v_and_b32_e32 v17, 0xffff0000, v157
	v_mul_f32_e32 v12, v249, v11
	v_mul_f32_e32 v13, v248, v11
	v_fma_f32 v14, v248, v10, -v12
	v_fma_f32 v15, v249, v10, v13
	v_add_f32_e32 v10, v14, v16
	v_add_f32_e32 v11, v15, v17
	v_lshlrev_b32_e32 v16, 16, v153
	v_lshlrev_b32_e32 v17, 16, v157
	v_mul_f32_e32 v12, v249, v11
	v_mul_f32_e32 v13, v248, v11
	v_fma_f32 v14, v248, v10, -v12
	v_fma_f32 v15, v249, v10, v13
	v_add_f32_e32 v10, v14, v16
	v_add_f32_e32 v11, v15, v17
	v_and_b32_e32 v16, 0xffff0000, v152
	v_and_b32_e32 v17, 0xffff0000, v156
	v_mul_f32_e32 v12, v249, v11
	v_mul_f32_e32 v13, v248, v11
	v_fma_f32 v14, v248, v10, -v12
	v_fma_f32 v15, v249, v10, v13
	v_add_f32_e32 v10, v14, v16
	v_add_f32_e32 v11, v15, v17
	v_lshlrev_b32_e32 v16, 16, v152
	v_lshlrev_b32_e32 v17, 16, v156
	v_mul_f32_e32 v12, v249, v11
	v_mul_f32_e32 v13, v248, v11
	v_fma_f32 v14, v248, v10, -v12
	v_fma_f32 v15, v249, v10, v13
	v_add_f32_e32 v10, v14, v16
	v_add_f32_e32 v11, v15, v17
	global_load_dwordx4 v[152:155], v30, s[10:11]
	global_load_dwordx4 v[156:159], v30, s[10:11] offset:1024
	s_sub_u32 s10, s10, 0x1000
	s_subb_u32 s11, s11, 0
	s_waitcnt vmcnt(6)
	v_and_b32_e32 v16, 0xffff0000, v163
	v_and_b32_e32 v17, 0xffff0000, v167
	v_mul_f32_e32 v12, v249, v11
	v_mul_f32_e32 v13, v248, v11
	v_fma_f32 v14, v248, v10, -v12
	v_fma_f32 v15, v249, v10, v13
	v_add_f32_e32 v10, v14, v16
	v_add_f32_e32 v11, v15, v17
	v_lshlrev_b32_e32 v16, 16, v163
	v_lshlrev_b32_e32 v17, 16, v167
	v_mul_f32_e32 v12, v249, v11
	v_mul_f32_e32 v13, v248, v11
	v_fma_f32 v14, v248, v10, -v12
	v_fma_f32 v15, v249, v10, v13
	v_add_f32_e32 v10, v14, v16
	v_add_f32_e32 v11, v15, v17
	v_and_b32_e32 v16, 0xffff0000, v162
	v_and_b32_e32 v17, 0xffff0000, v166
	v_mul_f32_e32 v12, v249, v11
	v_mul_f32_e32 v13, v248, v11
	v_fma_f32 v14, v248, v10, -v12
	v_fma_f32 v15, v249, v10, v13
	v_add_f32_e32 v10, v14, v16
	v_add_f32_e32 v11, v15, v17
	v_lshlrev_b32_e32 v16, 16, v162
	v_lshlrev_b32_e32 v17, 16, v166
	v_mul_f32_e32 v12, v249, v11
	v_mul_f32_e32 v13, v248, v11
	v_fma_f32 v14, v248, v10, -v12
	v_fma_f32 v15, v249, v10, v13
	v_add_f32_e32 v10, v14, v16
	v_add_f32_e32 v11, v15, v17
	v_and_b32_e32 v16, 0xffff0000, v161
	v_and_b32_e32 v17, 0xffff0000, v165
	v_mul_f32_e32 v12, v249, v11
	v_mul_f32_e32 v13, v248, v11
	v_fma_f32 v14, v248, v10, -v12
	v_fma_f32 v15, v249, v10, v13
	v_add_f32_e32 v10, v14, v16
	v_add_f32_e32 v11, v15, v17
	v_lshlrev_b32_e32 v16, 16, v161
	v_lshlrev_b32_e32 v17, 16, v165
	v_mul_f32_e32 v12, v249, v11
	v_mul_f32_e32 v13, v248, v11
	v_fma_f32 v14, v248, v10, -v12
	v_fma_f32 v15, v249, v10, v13
	v_add_f32_e32 v10, v14, v16
	v_add_f32_e32 v11, v15, v17
	v_and_b32_e32 v16, 0xffff0000, v160
	v_and_b32_e32 v17, 0xffff0000, v164
	v_mul_f32_e32 v12, v249, v11
	v_mul_f32_e32 v13, v248, v11
	v_fma_f32 v14, v248, v10, -v12
	v_fma_f32 v15, v249, v10, v13
	v_add_f32_e32 v10, v14, v16
	v_add_f32_e32 v11, v15, v17
	v_lshlrev_b32_e32 v16, 16, v160
	v_lshlrev_b32_e32 v17, 16, v164
	v_mul_f32_e32 v12, v249, v11
	v_mul_f32_e32 v13, v248, v11
	v_fma_f32 v14, v248, v10, -v12
	v_fma_f32 v15, v249, v10, v13
	v_add_f32_e32 v10, v14, v16
	v_add_f32_e32 v11, v15, v17
	global_load_dwordx4 v[160:163], v30, s[10:11]
	global_load_dwordx4 v[164:167], v30, s[10:11] offset:1024
	s_sub_u32 s10, s10, 0x1000
	s_subb_u32 s11, s11, 0
	s_sub_i32 s16, s16, 1
	s_cmp_lg_u32 s16, 0
	s_cbranch_scc1 .Lscl_p1r1_1
	s_waitcnt vmcnt(0)

; #define GAS __attribute__((address_space(1)))
; #define LAS __attribute__((address_space(3)))
; #define SCAN_LOAD(HALF) do { _Pragma("unroll") for (int k = 0; k < 8; ++k) { const int kk = r ? (15 - 8 * (HALF) - k) : (8 * (HALF) + k); pre[k] = *(const u32x4*)(re_row + 2048 * kk); pim[k] = *(const u32x4*)(im_row + 2048 * kk); } } while (0)
; __device__ __forceinline__ void scan_pair(Frame& F, const int g, const int b, unsigned long long& pt0, unsigned long long& pt1) {
;     ...
; #pragma unroll
;     for (int half = 0; half < 2; ++half) { SCAN_LOAD(half);
;         if (r == 0) {
; #pragma unroll
;             for (int i = 0; i < 64; ++i) {
;                 ((LAS unsigned*)tile)[(i & 3) * 64 + n] = pk2(hr, hi);
;                 if ((i & 3) == 3) { const u32x4 w = *(const LAS u32x4*)((const LAS char*)tile + n * 16); *(GAS u32x4*)hp = w; hp += hstep4; asm volatile("" : "+v"(hp)); }
;                 cmul_acc(hr, hi, aTr, aTi, bf2f(pre[i >> 3][(i & 7) >> 1] >> (16 * (i & 1))), bf2f(pim[i >> 3][(i & 7) >> 1] >> (16 * (i & 1)))); }
.Lsc_cmbd:
	s_cmp_lg_u32 s5, 0
	s_cbranch_scc1 .Lsc_p2r1
	s_add_u32 s10, s68, 0x8000
	s_addc_u32 s11, s69, 0
	global_load_dwordx4 v[168:171], v30, s[10:11]
	global_load_dwordx4 v[172:175], v30, s[10:11] offset:1024
	s_add_u32 s10, s10, 0x1000
	s_addc_u32 s11, s11, 0
	global_load_dwordx4 v[176:179], v30, s[10:11]
	global_load_dwordx4 v[180:183], v30, s[10:11] offset:1024
	s_add_u32 s10, s10, 0x1000
	s_addc_u32 s11, s11, 0
	global_load_dwordx4 v[184:187], v30, s[10:11]
	global_load_dwordx4 v[188:191], v30, s[10:11] offset:1024
	s_add_u32 s10, s10, 0x1000
	s_addc_u32 s11, s11, 0
	global_load_dwordx4 v[192:195], v30, s[10:11]
	global_load_dwordx4 v[196:199], v30, s[10:11] offset:1024
	s_add_u32 s10, s10, 0x1000
	s_addc_u32 s11, s11, 0
	v_mov_b32_e32 v38, v39
	s_mov_b32 s16, 2
.Lscl_p2r0_a:
	ds_read_b128 v[136:139], v38 offset:0
	ds_read_b128 v[140:143], v38 offset:1024
	ds_read_b128 v[144:147], v38 offset:2048
	ds_read_b128 v[148:151], v38 offset:3072
	ds_read_b128 v[152:155], v38 offset:4096
	ds_read_b128 v[156:159], v38 offset:5120
	ds_read_b128 v[160:163], v38 offset:6144
	ds_read_b128 v[164:167], v38 offset:7168
	s_waitcnt lgkmcnt(0)
	v_cvt_pk_bf16_f32 v76, v10, v11
	ds_write_b32 v32, v76
	v_lshlrev_b32_e32 v16, 16, v136
	v_lshlrev_b32_e32 v17, 16, v140
	v_mul_f32_e32 v12, v249, v11
	v_mul_f32_e32 v13, v248, v11
	v_fma_f32 v14, v248, v10, -v12
	v_fma_f32 v15, v249, v10, v13
	v_add_f32_e32 v10, v14, v16
	v_add_f32_e32 v11, v15, v17
	v_cvt_pk_bf16_f32 v76, v10, v11
	ds_write_b32 v32, v76 offset:256
	v_and_b32_e32 v16, 0xffff0000, v136
	v_and_b32_e32 v17, 0xffff0000, v140
	v_mul_f32_e32 v12, v249, v11
	v_mul_f32_e32 v13, v248, v11
	v_fma_f32 v14, v248, v10, -v12
	v_fma_f32 v15, v249, v10, v13
	v_add_f32_e32 v10, v14, v16
	v_add_f32_e32 v11, v15, v17
	v_cvt_pk_bf16_f32 v76, v10, v11
	ds_write_b32 v32, v76 offset:512
	v_lshlrev_b32_e32 v16, 16, v137
	v_lshlrev_b32_e32 v17, 16, v141
	v_mul_f32_e32 v12, v249, v11
	v_mul_f32_e32 v13, v248, v11
	v_fma_f32 v14, v248, v10, -v12
	v_fma_f32 v15, v249, v10, v13
	v_add_f32_e32 v10, v14, v16
	v_add_f32_e32 v11, v15, v17
	v_cvt_pk_bf16_f32 v76, v10, v11
	ds_write_b32 v32, v76 offset:768
	ds_read_b128 v[72:75], v33
	v_and_b32_e32 v16, 0xffff0000, v137
	v_and_b32_e32 v17, 0xffff0000, v141
	v_mul_f32_e32 v12, v249, v11
	v_mul_f32_e32 v13, v248, v11
	v_fma_f32 v14, v248, v10, -v12
	v_fma_f32 v15, v249, v10, v13
	v_add_f32_e32 v10, v14, v16
	v_add_f32_e32 v11, v15, v17
	s_waitcnt lgkmcnt(0)
	global_store_dwordx4 v31, v[72:75], s[28:29]
	s_add_u32 s28, s28, 0x200
	s_addc_u32 s29, s29, 0
	v_cvt_pk_bf16_f32 v76, v10, v11
	ds_write_b32 v32, v76
	v_lshlrev_b32_e32 v16, 16, v138
	v_lshlrev_b32_e32 v17, 16, v142
	v_mul_f32_e32 v12, v249, v11
	v_mul_f32_e32 v13, v248, v11
	v_fma_f32 v14, v248, v10, -v12
	v_fma_f32 v15, v249, v10, v13
	v_add_f32_e32 v10, v14, v16
	v_add_f32_e32 v11, v15, v17
	v_cvt_pk_bf16_f32 v76, v10, v11
	ds_write_b32 v32, v76 offset:256
	v_and_b32_e32 v16, 0xffff0000, v138
	v_and_b32_e32 v17, 0xffff0000, v142
	v_mul_f32_e32 v12, v249, v11
	v_mul_f32_e32 v13, v248, v11
	v_fma_f32 v14, v248, v10, -v12
	v_fma_f32 v15, v249, v10, v13
	v_add_f32_e32 v10, v14, v16
	v_add_f32_e32 v11, v15, v17
	v_cvt_pk_bf16_f32 v76, v10, v11
	ds_write_b32 v32, v76 offset:512
	v_lshlrev_b32_e32 v16, 16, v139
	v_lshlrev_b32_e32 v17, 16, v143
	v_mul_f32_e32 v12, v249, v11
	v_mul_f32_e32 v13, v248, v11
	v_fma_f32 v14, v248, v10, -v12
	v_fma_f32 v15, v249, v10, v13
	v_add_f32_e32 v10, v14, v16
	v_add_f32_e32 v11, v15, v17
	v_cvt_pk_bf16_f32 v76, v10, v11
	ds_write_b32 v32, v76 offset:768
	ds_read_b128 v[72:75], v33
	v_and_b32_e32 v16, 0xffff0000, v139
	v_and_b32_e32 v17, 0xffff0000, v143
	v_mul_f32_e32 v12, v249, v11
	v_mul_f32_e32 v13, v248, v11
	v_fma_f32 v14, v248, v10, -v12
	v_fma_f32 v15, v249, v10, v13
	v_add_f32_e32 v10, v14, v16
	v_add_f32_e32 v11, v15, v17
	s_waitcnt lgkmcnt(0)
	global_store_dwordx4 v31, v[72:75], s[28:29]
	s_add_u32 s28, s28, 0x200
	s_addc_u32 s29, s29, 0
	v_cvt_pk_bf16_f32 v76, v10, v11
	ds_write_b32 v32, v76
	v_lshlrev_b32_e32 v16, 16, v144
	v_lshlrev_b32_e32 v17, 16, v148
	v_mul_f32_e32 v12, v249, v11
	v_mul_f32_e32 v13, v248, v11
	v_fma_f32 v14, v248, v10, -v12
	v_fma_f32 v15, v249, v10, v13
	v_add_f32_e32 v10, v14, v16
	v_add_f32_e32 v11, v15, v17
	v_cvt_pk_bf16_f32 v76, v10, v11
	ds_write_b32 v32, v76 offset:256
	v_and_b32_e32 v16, 0xffff0000, v144
	v_and_b32_e32 v17, 0xffff0000, v148
	v_mul_f32_e32 v12, v249, v11
	v_mul_f32_e32 v13, v248, v11
	v_fma_f32 v14, v248, v10, -v12
	v_fma_f32 v15, v249, v10, v13
	v_add_f32_e32 v10, v14, v16
	v_add_f32_e32 v11, v15, v17
	v_cvt_pk_bf16_f32 v76, v10, v11
	ds_write_b32 v32, v76 offset:512
	v_lshlrev_b32_e32 v16, 16, v145
	v_lshlrev_b32_e32 v17, 16, v149
	v_mul_f32_e32 v12, v249, v11
	v_mul_f32_e32 v13, v248, v11
	v_fma_f32 v14, v248, v10, -v12
	v_fma_f32 v15, v249, v10, v13
	v_add_f32_e32 v10, v14, v16
	v_add_f32_e32 v11, v15, v17
	v_cvt_pk_bf16_f32 v76, v10, v11
	ds_write_b32 v32, v76 offset:768
	ds_read_b128 v[72:75], v33
	v_and_b32_e32 v16, 0xffff0000, v145
	v_and_b32_e32 v17, 0xffff0000, v149
	v_mul_f32_e32 v12, v249, v11
	v_mul_f32_e32 v13, v248, v11
	v_fma_f32 v14, v248, v10, -v12
	v_fma_f32 v15, v249, v10, v13
	v_add_f32_e32 v10, v14, v16
	v_add_f32_e32 v11, v15, v17
	s_waitcnt lgkmcnt(0)
; #define GAS __attribute__((address_space(1)))
; #define LAS __attribute__((address_space(3)))
; #define SCAN_LOAD(HALF) do { _Pragma("unroll") for (int k = 0; k < 8; ++k) { const int kk = r ? (15 - 8 * (HALF) - k) : (8 * (HALF) + k); pre[k] = *(const u32x4*)(re_row + 2048 * kk); pim[k] = *(const u32x4*)(im_row + 2048 * kk); } } while (0)
; __device__ __forceinline__ void scan_pair(Frame& F, const int g, const int b, unsigned long long& pt0, unsigned long long& pt1) {
;     ...
;     for (int half = 0; half < 2; ++half) { SCAN_LOAD(half);
;         if (r == 0) {
; #pragma unroll
;             for (int i = 0; i < 64; ++i) {
;                 ((LAS unsigned*)tile)[(i & 3) * 64 + n] = pk2(hr, hi);
;                 if ((i & 3) == 3) { const u32x4 w = *(const LAS u32x4*)((const LAS char*)tile + n * 16); *(GAS u32x4*)hp = w; hp += hstep4; asm volatile("" : "+v"(hp)); }
;                 cmul_acc(hr, hi, aTr, aTi, bf2f(pre[i >> 3][(i & 7) >> 1] >> (16 * (i & 1))), bf2f(pim[i >> 3][(i & 7) >> 1] >> (16 * (i & 1)))); }
;         } else {
; #pragma unroll
;             for (int i = 0; i < 64; ++i) { const int e = 7 - (i & 7);
;                 ((LAS unsigned*)tile)[(i & 3) * 64 + n] = pk2(hr, hi);
;                 if ((i & 3) == 3) { const u32x4 w = *(const LAS u32x4*)((const LAS char*)tile + n * 16); *(GAS u32x4*)hp = w; hp += hstep4; asm volatile("" : "+v"(hp)); }
;                 cmul_acc(hr, hi, aTr, aTi, bf2f(pre[i >> 3][e >> 1] >> (16 * (e & 1))), bf2f(pim[i >> 3][e >> 1] >> (16 * (e & 1)))); }
;         }
;         asm volatile("" ::: "memory"); }
	global_store_dwordx4 v31, v[72:75], s[28:29]
	s_add_u32 s28, s28, 0x200
	s_addc_u32 s29, s29, 0
	v_cvt_pk_bf16_f32 v76, v10, v11
	ds_write_b32 v32, v76
	v_lshlrev_b32_e32 v16, 16, v146
	v_lshlrev_b32_e32 v17, 16, v150
	v_mul_f32_e32 v12, v249, v11
	v_mul_f32_e32 v13, v248, v11
	v_fma_f32 v14, v248, v10, -v12
	v_fma_f32 v15, v249, v10, v13
	v_add_f32_e32 v10, v14, v16
	v_add_f32_e32 v11, v15, v17
	v_cvt_pk_bf16_f32 v76, v10, v11
	ds_write_b32 v32, v76 offset:256
	v_and_b32_e32 v16, 0xffff0000, v146
	v_and_b32_e32 v17, 0xffff0000, v150
	v_mul_f32_e32 v12, v249, v11
	v_mul_f32_e32 v13, v248, v11
	v_fma_f32 v14, v248, v10, -v12
	v_fma_f32 v15, v249, v10, v13
	v_add_f32_e32 v10, v14, v16
	v_add_f32_e32 v11, v15, v17
	v_cvt_pk_bf16_f32 v76, v10, v11
	ds_write_b32 v32, v76 offset:512
	v_lshlrev_b32_e32 v16, 16, v147
	v_lshlrev_b32_e32 v17, 16, v151
	v_mul_f32_e32 v12, v249, v11
	v_mul_f32_e32 v13, v248, v11
	v_fma_f32 v14, v248, v10, -v12
	v_fma_f32 v15, v249, v10, v13
	v_add_f32_e32 v10, v14, v16
	v_add_f32_e32 v11, v15, v17
	v_cvt_pk_bf16_f32 v76, v10, v11
	ds_write_b32 v32, v76 offset:768
	ds_read_b128 v[72:75], v33
	v_and_b32_e32 v16, 0xffff0000, v147
	v_and_b32_e32 v17, 0xffff0000, v151
	v_mul_f32_e32 v12, v249, v11
	v_mul_f32_e32 v13, v248, v11
	v_fma_f32 v14, v248, v10, -v12
	v_fma_f32 v15, v249, v10, v13
	v_add_f32_e32 v10, v14, v16
	v_add_f32_e32 v11, v15, v17
	s_waitcnt lgkmcnt(0)
	global_store_dwordx4 v31, v[72:75], s[28:29]
	s_add_u32 s28, s28, 0x200
	s_addc_u32 s29, s29, 0
	v_cvt_pk_bf16_f32 v76, v10, v11
	ds_write_b32 v32, v76
	v_lshlrev_b32_e32 v16, 16, v152
	v_lshlrev_b32_e32 v17, 16, v156
	v_mul_f32_e32 v12, v249, v11
	v_mul_f32_e32 v13, v248, v11
	v_fma_f32 v14, v248, v10, -v12
	v_fma_f32 v15, v249, v10, v13
	v_add_f32_e32 v10, v14, v16
	v_add_f32_e32 v11, v15, v17
	v_cvt_pk_bf16_f32 v76, v10, v11
	ds_write_b32 v32, v76 offset:256
	v_and_b32_e32 v16, 0xffff0000, v152
	v_and_b32_e32 v17, 0xffff0000, v156
	v_mul_f32_e32 v12, v249, v11
	v_mul_f32_e32 v13, v248, v11
	v_fma_f32 v14, v248, v10, -v12
	v_fma_f32 v15, v249, v10, v13
	v_add_f32_e32 v10, v14, v16
	v_add_f32_e32 v11, v15, v17
	v_cvt_pk_bf16_f32 v76, v10, v11
	ds_write_b32 v32, v76 offset:512
	v_lshlrev_b32_e32 v16, 16, v153
	v_lshlrev_b32_e32 v17, 16, v157
	v_mul_f32_e32 v12, v249, v11
	v_mul_f32_e32 v13, v248, v11
	v_fma_f32 v14, v248, v10, -v12
	v_fma_f32 v15, v249, v10, v13
	v_add_f32_e32 v10, v14, v16
	v_add_f32_e32 v11, v15, v17
	v_cvt_pk_bf16_f32 v76, v10, v11
	ds_write_b32 v32, v76 offset:768
	ds_read_b128 v[72:75], v33
	v_and_b32_e32 v16, 0xffff0000, v153
	v_and_b32_e32 v17, 0xffff0000, v157
	v_mul_f32_e32 v12, v249, v11
	v_mul_f32_e32 v13, v248, v11
	v_fma_f32 v14, v248, v10, -v12
	v_fma_f32 v15, v249, v10, v13
	v_add_f32_e32 v10, v14, v16
	v_add_f32_e32 v11, v15, v17
	s_waitcnt lgkmcnt(0)
	global_store_dwordx4 v31, v[72:75], s[28:29]
	s_add_u32 s28, s28, 0x200
	s_addc_u32 s29, s29, 0
	v_cvt_pk_bf16_f32 v76, v10, v11
	ds_write_b32 v32, v76
	v_lshlrev_b32_e32 v16, 16, v154
	v_lshlrev_b32_e32 v17, 16, v158
	v_mul_f32_e32 v12, v249, v11
	v_mul_f32_e32 v13, v248, v11
	v_fma_f32 v14, v248, v10, -v12
	v_fma_f32 v15, v249, v10, v13
	v_add_f32_e32 v10, v14, v16
	v_add_f32_e32 v11, v15, v17
	v_cvt_pk_bf16_f32 v76, v10, v11
	ds_write_b32 v32, v76 offset:256
	v_and_b32_e32 v16, 0xffff0000, v154
	v_and_b32_e32 v17, 0xffff0000, v158
	v_mul_f32_e32 v12, v249, v11
	v_mul_f32_e32 v13, v248, v11
	v_fma_f32 v14, v248, v10, -v12
	v_fma_f32 v15, v249, v10, v13
	v_add_f32_e32 v10, v14, v16
	v_add_f32_e32 v11, v15, v17
	v_cvt_pk_bf16_f32 v76, v10, v11
	ds_write_b32 v32, v76 offset:512
	v_lshlrev_b32_e32 v16, 16, v155
	v_lshlrev_b32_e32 v17, 16, v159
	v_mul_f32_e32 v12, v249, v11
	v_mul_f32_e32 v13, v248, v11
	v_fma_f32 v14, v248, v10, -v12
	v_fma_f32 v15, v249, v10, v13
	v_add_f32_e32 v10, v14, v16
	v_add_f32_e32 v11, v15, v17
	v_cvt_pk_bf16_f32 v76, v10, v11
	ds_write_b32 v32, v76 offset:768
	ds_read_b128 v[72:75], v33
	v_and_b32_e32 v16, 0xffff0000, v155
	v_and_b32_e32 v17, 0xffff0000, v159
	v_mul_f32_e32 v12, v249, v11
	v_mul_f32_e32 v13, v248, v11
	v_fma_f32 v14, v248, v10, -v12
	v_fma_f32 v15, v249, v10, v13
	v_add_f32_e32 v10, v14, v16
	v_add_f32_e32 v11, v15, v17
	s_waitcnt lgkmcnt(0)
	global_store_dwordx4 v31, v[72:75], s[28:29]
	s_add_u32 s28, s28, 0x200
	s_addc_u32 s29, s29, 0
	v_cvt_pk_bf16_f32 v76, v10, v11
	ds_write_b32 v32, v76
	v_lshlrev_b32_e32 v16, 16, v160
	v_lshlrev_b32_e32 v17, 16, v164
	v_mul_f32_e32 v12, v249, v11
	v_mul_f32_e32 v13, v248, v11
	v_fma_f32 v14, v248, v10, -v12
	v_fma_f32 v15, v249, v10, v13
	v_add_f32_e32 v10, v14, v16
	v_add_f32_e32 v11, v15, v17
	v_cvt_pk_bf16_f32 v76, v10, v11
	ds_write_b32 v32, v76 offset:256
	v_and_b32_e32 v16, 0xffff0000, v160
	v_and_b32_e32 v17, 0xffff0000, v164
	v_mul_f32_e32 v12, v249, v11
	v_mul_f32_e32 v13, v248, v11
	v_fma_f32 v14, v248, v10, -v12
	v_fma_f32 v15, v249, v10, v13
	v_add_f32_e32 v10, v14, v16
	v_add_f32_e32 v11, v15, v17
	v_cvt_pk_bf16_f32 v76, v10, v11
	ds_write_b32 v32, v76 offset:512
	v_lshlrev_b32_e32 v16, 16, v161
	v_lshlrev_b32_e32 v17, 16, v165
	v_mul_f32_e32 v12, v249, v11
	v_mul_f32_e32 v13, v248, v11
	v_fma_f32 v14, v248, v10, -v12
	v_fma_f32 v15, v249, v10, v13
	v_add_f32_e32 v10, v14, v16
	v_add_f32_e32 v11, v15, v17
	v_cvt_pk_bf16_f32 v76, v10, v11
	ds_write_b32 v32, v76 offset:768
	ds_read_b128 v[72:75], v33
	v_and_b32_e32 v16, 0xffff0000, v161
	v_and_b32_e32 v17, 0xffff0000, v165
	v_mul_f32_e32 v12, v249, v11
	v_mul_f32_e32 v13, v248, v11
	v_fma_f32 v14, v248, v10, -v12
	v_fma_f32 v15, v249, v10, v13
	v_add_f32_e32 v10, v14, v16
	v_add_f32_e32 v11, v15, v17
	s_waitcnt lgkmcnt(0)
; #define GAS __attribute__((address_space(1)))
; #define LAS __attribute__((address_space(3)))
; #define SCAN_LOAD(HALF) do { _Pragma("unroll") for (int k = 0; k < 8; ++k) { const int kk = r ? (15 - 8 * (HALF) - k) : (8 * (HALF) + k); pre[k] = *(const u32x4*)(re_row + 2048 * kk); pim[k] = *(const u32x4*)(im_row + 2048 * kk); } } while (0)
; __device__ __forceinline__ void scan_pair(Frame& F, const int g, const int b, unsigned long long& pt0, unsigned long long& pt1) {
;     ...
;     for (int half = 0; half < 2; ++half) { SCAN_LOAD(half);
;         if (r == 0) {
; #pragma unroll
;             for (int i = 0; i < 64; ++i) {
;                 ((LAS unsigned*)tile)[(i & 3) * 64 + n] = pk2(hr, hi);
;                 if ((i & 3) == 3) { const u32x4 w = *(const LAS u32x4*)((const LAS char*)tile + n * 16); *(GAS u32x4*)hp = w; hp += hstep4; asm volatile("" : "+v"(hp)); }
;                 cmul_acc(hr, hi, aTr, aTi, bf2f(pre[i >> 3][(i & 7) >> 1] >> (16 * (i & 1))), bf2f(pim[i >> 3][(i & 7) >> 1] >> (16 * (i & 1)))); }
;         } else {
; #pragma unroll
;             for (int i = 0; i < 64; ++i) { const int e = 7 - (i & 7);
;                 ((LAS unsigned*)tile)[(i & 3) * 64 + n] = pk2(hr, hi);
;                 if ((i & 3) == 3) { const u32x4 w = *(const LAS u32x4*)((const LAS char*)tile + n * 16); *(GAS u32x4*)hp = w; hp += hstep4; asm volatile("" : "+v"(hp)); }
;                 cmul_acc(hr, hi, aTr, aTi, bf2f(pre[i >> 3][e >> 1] >> (16 * (e & 1))), bf2f(pim[i >> 3][e >> 1] >> (16 * (e & 1)))); }
;         }
;         asm volatile("" ::: "memory"); }
	global_store_dwordx4 v31, v[72:75], s[28:29]
	s_add_u32 s28, s28, 0x200
	s_addc_u32 s29, s29, 0
	v_cvt_pk_bf16_f32 v76, v10, v11
	ds_write_b32 v32, v76
	v_lshlrev_b32_e32 v16, 16, v162
	v_lshlrev_b32_e32 v17, 16, v166
	v_mul_f32_e32 v12, v249, v11
	v_mul_f32_e32 v13, v248, v11
	v_fma_f32 v14, v248, v10, -v12
	v_fma_f32 v15, v249, v10, v13
	v_add_f32_e32 v10, v14, v16
	v_add_f32_e32 v11, v15, v17
	v_cvt_pk_bf16_f32 v76, v10, v11
	ds_write_b32 v32, v76 offset:256
	v_and_b32_e32 v16, 0xffff0000, v162
	v_and_b32_e32 v17, 0xffff0000, v166
	v_mul_f32_e32 v12, v249, v11
	v_mul_f32_e32 v13, v248, v11
	v_fma_f32 v14, v248, v10, -v12
	v_fma_f32 v15, v249, v10, v13
	v_add_f32_e32 v10, v14, v16
	v_add_f32_e32 v11, v15, v17
	v_cvt_pk_bf16_f32 v76, v10, v11
	ds_write_b32 v32, v76 offset:512
	v_lshlrev_b32_e32 v16, 16, v163
	v_lshlrev_b32_e32 v17, 16, v167
	v_mul_f32_e32 v12, v249, v11
	v_mul_f32_e32 v13, v248, v11
	v_fma_f32 v14, v248, v10, -v12
	v_fma_f32 v15, v249, v10, v13
	v_add_f32_e32 v10, v14, v16
	v_add_f32_e32 v11, v15, v17
	v_cvt_pk_bf16_f32 v76, v10, v11
	ds_write_b32 v32, v76 offset:768
	ds_read_b128 v[72:75], v33
	v_and_b32_e32 v16, 0xffff0000, v163
	v_and_b32_e32 v17, 0xffff0000, v167
	v_mul_f32_e32 v12, v249, v11
	v_mul_f32_e32 v13, v248, v11
	v_fma_f32 v14, v248, v10, -v12
	v_fma_f32 v15, v249, v10, v13
	v_add_f32_e32 v10, v14, v16
	v_add_f32_e32 v11, v15, v17
	s_waitcnt lgkmcnt(0)
	global_store_dwordx4 v31, v[72:75], s[28:29]
	s_add_u32 s28, s28, 0x200
	s_addc_u32 s29, s29, 0
	v_add_u32_e32 v38, 0x2000, v38
	s_sub_i32 s16, s16, 1
	s_cmp_lg_u32 s16, 0
	s_cbranch_scc1 .Lscl_p2r0_a
	s_waitcnt vmcnt(0)
	s_mov_b32 s16, 2
.Lscl_p2r0_b:
	s_waitcnt vmcnt(12)
	v_cvt_pk_bf16_f32 v76, v10, v11
	ds_write_b32 v32, v76
	v_lshlrev_b32_e32 v16, 16, v168
	v_lshlrev_b32_e32 v17, 16, v172
	v_mul_f32_e32 v12, v249, v11
	v_mul_f32_e32 v13, v248, v11
	v_fma_f32 v14, v248, v10, -v12
	v_fma_f32 v15, v249, v10, v13
	v_add_f32_e32 v10, v14, v16
	v_add_f32_e32 v11, v15, v17
	v_cvt_pk_bf16_f32 v76, v10, v11
	ds_write_b32 v32, v76 offset:256
	v_and_b32_e32 v16, 0xffff0000, v168
	v_and_b32_e32 v17, 0xffff0000, v172
	v_mul_f32_e32 v12, v249, v11
	v_mul_f32_e32 v13, v248, v11
	v_fma_f32 v14, v248, v10, -v12
	v_fma_f32 v15, v249, v10, v13
	v_add_f32_e32 v10, v14, v16
	v_add_f32_e32 v11, v15, v17
	v_cvt_pk_bf16_f32 v76, v10, v11
	ds_write_b32 v32, v76 offset:512
	v_lshlrev_b32_e32 v16, 16, v169
	v_lshlrev_b32_e32 v17, 16, v173
	v_mul_f32_e32 v12, v249, v11
	v_mul_f32_e32 v13, v248, v11
	v_fma_f32 v14, v248, v10, -v12
	v_fma_f32 v15, v249, v10, v13
	v_add_f32_e32 v10, v14, v16
	v_add_f32_e32 v11, v15, v17
	v_cvt_pk_bf16_f32 v76, v10, v11
	ds_write_b32 v32, v76 offset:768
	ds_read_b128 v[72:75], v33
	v_and_b32_e32 v16, 0xffff0000, v169
	v_and_b32_e32 v17, 0xffff0000, v173
	v_mul_f32_e32 v12, v249, v11
	v_mul_f32_e32 v13, v248, v11
	v_fma_f32 v14, v248, v10, -v12
	v_fma_f32 v15, v249, v10, v13
	v_add_f32_e32 v10, v14, v16
	v_add_f32_e32 v11, v15, v17
	s_waitcnt lgkmcnt(0)
	global_store_dwordx4 v31, v[72:75], s[28:29]
	s_add_u32 s28, s28, 0x200
	s_addc_u32 s29, s29, 0
	v_cvt_pk_bf16_f32 v76, v10, v11
	ds_write_b32 v32, v76
	v_lshlrev_b32_e32 v16, 16, v170
	v_lshlrev_b32_e32 v17, 16, v174
	v_mul_f32_e32 v12, v249, v11
	v_mul_f32_e32 v13, v248, v11
	v_fma_f32 v14, v248, v10, -v12
	v_fma_f32 v15, v249, v10, v13
	v_add_f32_e32 v10, v14, v16
	v_add_f32_e32 v11, v15, v17
	v_cvt_pk_bf16_f32 v76, v10, v11
	ds_write_b32 v32, v76 offset:256
	v_and_b32_e32 v16, 0xffff0000, v170
	v_and_b32_e32 v17, 0xffff0000, v174
	v_mul_f32_e32 v12, v249, v11
	v_mul_f32_e32 v13, v248, v11
	v_fma_f32 v14, v248, v10, -v12
	v_fma_f32 v15, v249, v10, v13
	v_add_f32_e32 v10, v14, v16
	v_add_f32_e32 v11, v15, v17
	v_cvt_pk_bf16_f32 v76, v10, v11
	ds_write_b32 v32, v76 offset:512
	v_lshlrev_b32_e32 v16, 16, v171
	v_lshlrev_b32_e32 v17, 16, v175
	v_mul_f32_e32 v12, v249, v11
	v_mul_f32_e32 v13, v248, v11
	v_fma_f32 v14, v248, v10, -v12
	v_fma_f32 v15, v249, v10, v13
	v_add_f32_e32 v10, v14, v16
	v_add_f32_e32 v11, v15, v17
	v_cvt_pk_bf16_f32 v76, v10, v11
	ds_write_b32 v32, v76 offset:768
	ds_read_b128 v[72:75], v33
	v_and_b32_e32 v16, 0xffff0000, v171
	v_and_b32_e32 v17, 0xffff0000, v175
	v_mul_f32_e32 v12, v249, v11
	v_mul_f32_e32 v13, v248, v11
	v_fma_f32 v14, v248, v10, -v12
	v_fma_f32 v15, v249, v10, v13
	v_add_f32_e32 v10, v14, v16
	v_add_f32_e32 v11, v15, v17
	s_waitcnt lgkmcnt(0)
	global_store_dwordx4 v31, v[72:75], s[28:29]
	s_add_u32 s28, s28, 0x200
	s_addc_u32 s29, s29, 0
	global_load_dwordx4 v[168:171], v30, s[10:11]
	global_load_dwordx4 v[172:175], v30, s[10:11] offset:1024
	s_add_u32 s10, s10, 0x1000
	s_addc_u32 s11, s11, 0
	s_waitcnt vmcnt(12)
	v_cvt_pk_bf16_f32 v76, v10, v11
	ds_write_b32 v32, v76
	v_lshlrev_b32_e32 v16, 16, v176
	v_lshlrev_b32_e32 v17, 16, v180
	v_mul_f32_e32 v12, v249, v11
	v_mul_f32_e32 v13, v248, v11
	v_fma_f32 v14, v248, v10, -v12
	v_fma_f32 v15, v249, v10, v13
	v_add_f32_e32 v10, v14, v16
	v_add_f32_e32 v11, v15, v17
	v_cvt_pk_bf16_f32 v76, v10, v11
	ds_write_b32 v32, v76 offset:256
	v_and_b32_e32 v16, 0xffff0000, v176
	v_and_b32_e32 v17, 0xffff0000, v180
	v_mul_f32_e32 v12, v249, v11
	v_mul_f32_e32 v13, v248, v11
	v_fma_f32 v14, v248, v10, -v12
	v_fma_f32 v15, v249, v10, v13
	v_add_f32_e32 v10, v14, v16
	v_add_f32_e32 v11, v15, v17
	v_cvt_pk_bf16_f32 v76, v10, v11
	ds_write_b32 v32, v76 offset:512
	v_lshlrev_b32_e32 v16, 16, v177
	v_lshlrev_b32_e32 v17, 16, v181
	v_mul_f32_e32 v12, v249, v11
	v_mul_f32_e32 v13, v248, v11
	v_fma_f32 v14, v248, v10, -v12
	v_fma_f32 v15, v249, v10, v13
	v_add_f32_e32 v10, v14, v16
	v_add_f32_e32 v11, v15, v17
	v_cvt_pk_bf16_f32 v76, v10, v11
	ds_write_b32 v32, v76 offset:768
	ds_read_b128 v[72:75], v33
	v_and_b32_e32 v16, 0xffff0000, v177
	v_and_b32_e32 v17, 0xffff0000, v181
	v_mul_f32_e32 v12, v249, v11
	v_mul_f32_e32 v13, v248, v11
	v_fma_f32 v14, v248, v10, -v12
	v_fma_f32 v15, v249, v10, v13
	v_add_f32_e32 v10, v14, v16
	v_add_f32_e32 v11, v15, v17
	s_waitcnt lgkmcnt(0)
; #define GAS __attribute__((address_space(1)))
; #define LAS __attribute__((address_space(3)))
; #define SCAN_LOAD(HALF) do { _Pragma("unroll") for (int k = 0; k < 8; ++k) { const int kk = r ? (15 - 8 * (HALF) - k) : (8 * (HALF) + k); pre[k] = *(const u32x4*)(re_row + 2048 * kk); pim[k] = *(const u32x4*)(im_row + 2048 * kk); } } while (0)
; __device__ __forceinline__ void scan_pair(Frame& F, const int g, const int b, unsigned long long& pt0, unsigned long long& pt1) {
;     ...
;     for (int half = 0; half < 2; ++half) { SCAN_LOAD(half);
;         if (r == 0) {
; #pragma unroll
;             for (int i = 0; i < 64; ++i) {
;                 ((LAS unsigned*)tile)[(i & 3) * 64 + n] = pk2(hr, hi);
;                 if ((i & 3) == 3) { const u32x4 w = *(const LAS u32x4*)((const LAS char*)tile + n * 16); *(GAS u32x4*)hp = w; hp += hstep4; asm volatile("" : "+v"(hp)); }
;                 cmul_acc(hr, hi, aTr, aTi, bf2f(pre[i >> 3][(i & 7) >> 1] >> (16 * (i & 1))), bf2f(pim[i >> 3][(i & 7) >> 1] >> (16 * (i & 1)))); }
;         } else {
; #pragma unroll
;             for (int i = 0; i < 64; ++i) { const int e = 7 - (i & 7);
;                 ((LAS unsigned*)tile)[(i & 3) * 64 + n] = pk2(hr, hi);
;                 if ((i & 3) == 3) { const u32x4 w = *(const LAS u32x4*)((const LAS char*)tile + n * 16); *(GAS u32x4*)hp = w; hp += hstep4; asm volatile("" : "+v"(hp)); }
;                 cmul_acc(hr, hi, aTr, aTi, bf2f(pre[i >> 3][e >> 1] >> (16 * (e & 1))), bf2f(pim[i >> 3][e >> 1] >> (16 * (e & 1)))); }
;         }
;         asm volatile("" ::: "memory"); }
	global_store_dwordx4 v31, v[72:75], s[28:29]
	s_add_u32 s28, s28, 0x200
	s_addc_u32 s29, s29, 0
	v_cvt_pk_bf16_f32 v76, v10, v11
	ds_write_b32 v32, v76
	v_lshlrev_b32_e32 v16, 16, v178
	v_lshlrev_b32_e32 v17, 16, v182
	v_mul_f32_e32 v12, v249, v11
	v_mul_f32_e32 v13, v248, v11
	v_fma_f32 v14, v248, v10, -v12
	v_fma_f32 v15, v249, v10, v13
	v_add_f32_e32 v10, v14, v16
	v_add_f32_e32 v11, v15, v17
	v_cvt_pk_bf16_f32 v76, v10, v11
	ds_write_b32 v32, v76 offset:256
	v_and_b32_e32 v16, 0xffff0000, v178
	v_and_b32_e32 v17, 0xffff0000, v182
	v_mul_f32_e32 v12, v249, v11
	v_mul_f32_e32 v13, v248, v11
	v_fma_f32 v14, v248, v10, -v12
	v_fma_f32 v15, v249, v10, v13
	v_add_f32_e32 v10, v14, v16
	v_add_f32_e32 v11, v15, v17
	v_cvt_pk_bf16_f32 v76, v10, v11
	ds_write_b32 v32, v76 offset:512
	v_lshlrev_b32_e32 v16, 16, v179
	v_lshlrev_b32_e32 v17, 16, v183
	v_mul_f32_e32 v12, v249, v11
	v_mul_f32_e32 v13, v248, v11
	v_fma_f32 v14, v248, v10, -v12
	v_fma_f32 v15, v249, v10, v13
	v_add_f32_e32 v10, v14, v16
	v_add_f32_e32 v11, v15, v17
	v_cvt_pk_bf16_f32 v76, v10, v11
	ds_write_b32 v32, v76 offset:768
	ds_read_b128 v[72:75], v33
	v_and_b32_e32 v16, 0xffff0000, v179
	v_and_b32_e32 v17, 0xffff0000, v183
	v_mul_f32_e32 v12, v249, v11
	v_mul_f32_e32 v13, v248, v11
	v_fma_f32 v14, v248, v10, -v12
	v_fma_f32 v15, v249, v10, v13
	v_add_f32_e32 v10, v14, v16
	v_add_f32_e32 v11, v15, v17
	s_waitcnt lgkmcnt(0)
	global_store_dwordx4 v31, v[72:75], s[28:29]
	s_add_u32 s28, s28, 0x200
	s_addc_u32 s29, s29, 0
	global_load_dwordx4 v[176:179], v30, s[10:11]
	global_load_dwordx4 v[180:183], v30, s[10:11] offset:1024
	s_add_u32 s10, s10, 0x1000
	s_addc_u32 s11, s11, 0
	s_waitcnt vmcnt(12)
	v_cvt_pk_bf16_f32 v76, v10, v11
	ds_write_b32 v32, v76
	v_lshlrev_b32_e32 v16, 16, v184
	v_lshlrev_b32_e32 v17, 16, v188
	v_mul_f32_e32 v12, v249, v11
	v_mul_f32_e32 v13, v248, v11
	v_fma_f32 v14, v248, v10, -v12
	v_fma_f32 v15, v249, v10, v13
	v_add_f32_e32 v10, v14, v16
	v_add_f32_e32 v11, v15, v17
	v_cvt_pk_bf16_f32 v76, v10, v11
	ds_write_b32 v32, v76 offset:256
	v_and_b32_e32 v16, 0xffff0000, v184
	v_and_b32_e32 v17, 0xffff0000, v188
	v_mul_f32_e32 v12, v249, v11
	v_mul_f32_e32 v13, v248, v11
	v_fma_f32 v14, v248, v10, -v12
	v_fma_f32 v15, v249, v10, v13
	v_add_f32_e32 v10, v14, v16
	v_add_f32_e32 v11, v15, v17
	v_cvt_pk_bf16_f32 v76, v10, v11
	ds_write_b32 v32, v76 offset:512
	v_lshlrev_b32_e32 v16, 16, v185
	v_lshlrev_b32_e32 v17, 16, v189
	v_mul_f32_e32 v12, v249, v11
	v_mul_f32_e32 v13, v248, v11
	v_fma_f32 v14, v248, v10, -v12
	v_fma_f32 v15, v249, v10, v13
	v_add_f32_e32 v10, v14, v16
	v_add_f32_e32 v11, v15, v17
	v_cvt_pk_bf16_f32 v76, v10, v11
	ds_write_b32 v32, v76 offset:768
	ds_read_b128 v[72:75], v33
	v_and_b32_e32 v16, 0xffff0000, v185
	v_and_b32_e32 v17, 0xffff0000, v189
	v_mul_f32_e32 v12, v249, v11
	v_mul_f32_e32 v13, v248, v11
	v_fma_f32 v14, v248, v10, -v12
	v_fma_f32 v15, v249, v10, v13
	v_add_f32_e32 v10, v14, v16
	v_add_f32_e32 v11, v15, v17
	s_waitcnt lgkmcnt(0)
	global_store_dwordx4 v31, v[72:75], s[28:29]
	s_add_u32 s28, s28, 0x200
	s_addc_u32 s29, s29, 0
	v_cvt_pk_bf16_f32 v76, v10, v11
	ds_write_b32 v32, v76
	v_lshlrev_b32_e32 v16, 16, v186
	v_lshlrev_b32_e32 v17, 16, v190
	v_mul_f32_e32 v12, v249, v11
	v_mul_f32_e32 v13, v248, v11
	v_fma_f32 v14, v248, v10, -v12
	v_fma_f32 v15, v249, v10, v13
	v_add_f32_e32 v10, v14, v16
	v_add_f32_e32 v11, v15, v17
	v_cvt_pk_bf16_f32 v76, v10, v11
	ds_write_b32 v32, v76 offset:256
	v_and_b32_e32 v16, 0xffff0000, v186
	v_and_b32_e32 v17, 0xffff0000, v190
	v_mul_f32_e32 v12, v249, v11
	v_mul_f32_e32 v13, v248, v11
	v_fma_f32 v14, v248, v10, -v12
	v_fma_f32 v15, v249, v10, v13
	v_add_f32_e32 v10, v14, v16
	v_add_f32_e32 v11, v15, v17
	v_cvt_pk_bf16_f32 v76, v10, v11
	ds_write_b32 v32, v76 offset:512
	v_lshlrev_b32_e32 v16, 16, v187
	v_lshlrev_b32_e32 v17, 16, v191
	v_mul_f32_e32 v12, v249, v11
	v_mul_f32_e32 v13, v248, v11
	v_fma_f32 v14, v248, v10, -v12
	v_fma_f32 v15, v249, v10, v13
	v_add_f32_e32 v10, v14, v16
	v_add_f32_e32 v11, v15, v17
	v_cvt_pk_bf16_f32 v76, v10, v11
	ds_write_b32 v32, v76 offset:768
	ds_read_b128 v[72:75], v33
	v_and_b32_e32 v16, 0xffff0000, v187
	v_and_b32_e32 v17, 0xffff0000, v191
	v_mul_f32_e32 v12, v249, v11
	v_mul_f32_e32 v13, v248, v11
	v_fma_f32 v14, v248, v10, -v12
	v_fma_f32 v15, v249, v10, v13
	v_add_f32_e32 v10, v14, v16
	v_add_f32_e32 v11, v15, v17
	s_waitcnt lgkmcnt(0)
	global_store_dwordx4 v31, v[72:75], s[28:29]
	s_add_u32 s28, s28, 0x200
	s_addc_u32 s29, s29, 0
	global_load_dwordx4 v[184:187], v30, s[10:11]
	global_load_dwordx4 v[188:191], v30, s[10:11] offset:1024
	s_add_u32 s10, s10, 0x1000
	s_addc_u32 s11, s11, 0
	s_waitcnt vmcnt(12)
	v_cvt_pk_bf16_f32 v76, v10, v11
	ds_write_b32 v32, v76
	v_lshlrev_b32_e32 v16, 16, v192
	v_lshlrev_b32_e32 v17, 16, v196
	v_mul_f32_e32 v12, v249, v11
	v_mul_f32_e32 v13, v248, v11
	v_fma_f32 v14, v248, v10, -v12
	v_fma_f32 v15, v249, v10, v13
	v_add_f32_e32 v10, v14, v16
	v_add_f32_e32 v11, v15, v17
	v_cvt_pk_bf16_f32 v76, v10, v11
	ds_write_b32 v32, v76 offset:256
	v_and_b32_e32 v16, 0xffff0000, v192
	v_and_b32_e32 v17, 0xffff0000, v196
	v_mul_f32_e32 v12, v249, v11
	v_mul_f32_e32 v13, v248, v11
	v_fma_f32 v14, v248, v10, -v12
	v_fma_f32 v15, v249, v10, v13
	v_add_f32_e32 v10, v14, v16
	v_add_f32_e32 v11, v15, v17
	v_cvt_pk_bf16_f32 v76, v10, v11
	ds_write_b32 v32, v76 offset:512
	v_lshlrev_b32_e32 v16, 16, v193
	v_lshlrev_b32_e32 v17, 16, v197
	v_mul_f32_e32 v12, v249, v11
	v_mul_f32_e32 v13, v248, v11
	v_fma_f32 v14, v248, v10, -v12
	v_fma_f32 v15, v249, v10, v13
	v_add_f32_e32 v10, v14, v16
	v_add_f32_e32 v11, v15, v17
	v_cvt_pk_bf16_f32 v76, v10, v11
	ds_write_b32 v32, v76 offset:768
	ds_read_b128 v[72:75], v33
	v_and_b32_e32 v16, 0xffff0000, v193
	v_and_b32_e32 v17, 0xffff0000, v197
	v_mul_f32_e32 v12, v249, v11
	v_mul_f32_e32 v13, v248, v11
	v_fma_f32 v14, v248, v10, -v12
	v_fma_f32 v15, v249, v10, v13
	v_add_f32_e32 v10, v14, v16
	v_add_f32_e32 v11, v15, v17
	s_waitcnt lgkmcnt(0)
; #define GAS __attribute__((address_space(1)))
; #define LAS __attribute__((address_space(3)))
; #define SCAN_LOAD(HALF) do { _Pragma("unroll") for (int k = 0; k < 8; ++k) { const int kk = r ? (15 - 8 * (HALF) - k) : (8 * (HALF) + k); pre[k] = *(const u32x4*)(re_row + 2048 * kk); pim[k] = *(const u32x4*)(im_row + 2048 * kk); } } while (0)
; __device__ __forceinline__ void scan_pair(Frame& F, const int g, const int b, unsigned long long& pt0, unsigned long long& pt1) {
;     ...
;     for (int half = 0; half < 2; ++half) { SCAN_LOAD(half);
;         if (r == 0) {
; #pragma unroll
;             for (int i = 0; i < 64; ++i) {
;                 ((LAS unsigned*)tile)[(i & 3) * 64 + n] = pk2(hr, hi);
;                 if ((i & 3) == 3) { const u32x4 w = *(const LAS u32x4*)((const LAS char*)tile + n * 16); *(GAS u32x4*)hp = w; hp += hstep4; asm volatile("" : "+v"(hp)); }
;                 cmul_acc(hr, hi, aTr, aTi, bf2f(pre[i >> 3][(i & 7) >> 1] >> (16 * (i & 1))), bf2f(pim[i >> 3][(i & 7) >> 1] >> (16 * (i & 1)))); }
;         } else {
; #pragma unroll
;             for (int i = 0; i < 64; ++i) { const int e = 7 - (i & 7);
;                 ((LAS unsigned*)tile)[(i & 3) * 64 + n] = pk2(hr, hi);
;                 if ((i & 3) == 3) { const u32x4 w = *(const LAS u32x4*)((const LAS char*)tile + n * 16); *(GAS u32x4*)hp = w; hp += hstep4; asm volatile("" : "+v"(hp)); }
;                 cmul_acc(hr, hi, aTr, aTi, bf2f(pre[i >> 3][e >> 1] >> (16 * (e & 1))), bf2f(pim[i >> 3][e >> 1] >> (16 * (e & 1)))); }
;         }
;         asm volatile("" ::: "memory"); }
	global_store_dwordx4 v31, v[72:75], s[28:29]
	s_add_u32 s28, s28, 0x200
	s_addc_u32 s29, s29, 0
	v_cvt_pk_bf16_f32 v76, v10, v11
	ds_write_b32 v32, v76
	v_lshlrev_b32_e32 v16, 16, v194
	v_lshlrev_b32_e32 v17, 16, v198
	v_mul_f32_e32 v12, v249, v11
	v_mul_f32_e32 v13, v248, v11
	v_fma_f32 v14, v248, v10, -v12
	v_fma_f32 v15, v249, v10, v13
	v_add_f32_e32 v10, v14, v16
	v_add_f32_e32 v11, v15, v17
	v_cvt_pk_bf16_f32 v76, v10, v11
	ds_write_b32 v32, v76 offset:256
	v_and_b32_e32 v16, 0xffff0000, v194
	v_and_b32_e32 v17, 0xffff0000, v198
	v_mul_f32_e32 v12, v249, v11
	v_mul_f32_e32 v13, v248, v11
	v_fma_f32 v14, v248, v10, -v12
	v_fma_f32 v15, v249, v10, v13
	v_add_f32_e32 v10, v14, v16
	v_add_f32_e32 v11, v15, v17
	v_cvt_pk_bf16_f32 v76, v10, v11
	ds_write_b32 v32, v76 offset:512
	v_lshlrev_b32_e32 v16, 16, v195
	v_lshlrev_b32_e32 v17, 16, v199
	v_mul_f32_e32 v12, v249, v11
	v_mul_f32_e32 v13, v248, v11
	v_fma_f32 v14, v248, v10, -v12
	v_fma_f32 v15, v249, v10, v13
	v_add_f32_e32 v10, v14, v16
	v_add_f32_e32 v11, v15, v17
	v_cvt_pk_bf16_f32 v76, v10, v11
	ds_write_b32 v32, v76 offset:768
	ds_read_b128 v[72:75], v33
	v_and_b32_e32 v16, 0xffff0000, v195
	v_and_b32_e32 v17, 0xffff0000, v199
	v_mul_f32_e32 v12, v249, v11
	v_mul_f32_e32 v13, v248, v11
	v_fma_f32 v14, v248, v10, -v12
	v_fma_f32 v15, v249, v10, v13
	v_add_f32_e32 v10, v14, v16
	v_add_f32_e32 v11, v15, v17
	s_waitcnt lgkmcnt(0)
	global_store_dwordx4 v31, v[72:75], s[28:29]
	s_add_u32 s28, s28, 0x200
	s_addc_u32 s29, s29, 0
	global_load_dwordx4 v[192:195], v30, s[10:11]
	global_load_dwordx4 v[196:199], v30, s[10:11] offset:1024
	s_add_u32 s10, s10, 0x1000
	s_addc_u32 s11, s11, 0
	s_sub_i32 s16, s16, 1
	s_cmp_lg_u32 s16, 0
	s_cbranch_scc1 .Lscl_p2r0_b
	s_waitcnt vmcnt(0)
	s_branch .Lsc_end
.Lsc_p2r1:
	s_sub_u32 s10, s68, 0x8000
	s_subb_u32 s11, s69, 0
	global_load_dwordx4 v[168:171], v30, s[10:11]
	global_load_dwordx4 v[172:175], v30, s[10:11] offset:1024
	s_sub_u32 s10, s10, 0x1000
	s_subb_u32 s11, s11, 0
	global_load_dwordx4 v[176:179], v30, s[10:11]
	global_load_dwordx4 v[180:183], v30, s[10:11] offset:1024
	s_sub_u32 s10, s10, 0x1000
	s_subb_u32 s11, s11, 0
	global_load_dwordx4 v[184:187], v30, s[10:11]
	global_load_dwordx4 v[188:191], v30, s[10:11] offset:1024
	s_sub_u32 s10, s10, 0x1000
	s_subb_u32 s11, s11, 0
	global_load_dwordx4 v[192:195], v30, s[10:11]
	global_load_dwordx4 v[196:199], v30, s[10:11] offset:1024
	s_sub_u32 s10, s10, 0x1000
	s_subb_u32 s11, s11, 0
	v_mov_b32_e32 v38, v39
	s_mov_b32 s16, 2
.Lscl_p2r1_a:
	ds_read_b128 v[136:139], v38 offset:0
	ds_read_b128 v[140:143], v38 offset:1024
	ds_read_b128 v[144:147], v38 offset:2048
	ds_read_b128 v[148:151], v38 offset:3072
	ds_read_b128 v[152:155], v38 offset:4096
	ds_read_b128 v[156:159], v38 offset:5120
	ds_read_b128 v[160:163], v38 offset:6144
	ds_read_b128 v[164:167], v38 offset:7168
	s_waitcnt lgkmcnt(0)
	v_cvt_pk_bf16_f32 v76, v10, v11
	ds_write_b32 v32, v76
	v_and_b32_e32 v16, 0xffff0000, v139
	v_and_b32_e32 v17, 0xffff0000, v143
	v_mul_f32_e32 v12, v249, v11
	v_mul_f32_e32 v13, v248, v11
	v_fma_f32 v14, v248, v10, -v12
	v_fma_f32 v15, v249, v10, v13
	v_add_f32_e32 v10, v14, v16
	v_add_f32_e32 v11, v15, v17
	v_cvt_pk_bf16_f32 v76, v10, v11
	ds_write_b32 v32, v76 offset:256
	v_lshlrev_b32_e32 v16, 16, v139
	v_lshlrev_b32_e32 v17, 16, v143
	v_mul_f32_e32 v12, v249, v11
	v_mul_f32_e32 v13, v248, v11
	v_fma_f32 v14, v248, v10, -v12
	v_fma_f32 v15, v249, v10, v13
	v_add_f32_e32 v10, v14, v16
	v_add_f32_e32 v11, v15, v17
	v_cvt_pk_bf16_f32 v76, v10, v11
	ds_write_b32 v32, v76 offset:512
	v_and_b32_e32 v16, 0xffff0000, v138
	v_and_b32_e32 v17, 0xffff0000, v142
	v_mul_f32_e32 v12, v249, v11
	v_mul_f32_e32 v13, v248, v11
	v_fma_f32 v14, v248, v10, -v12
	v_fma_f32 v15, v249, v10, v13
	v_add_f32_e32 v10, v14, v16
	v_add_f32_e32 v11, v15, v17
	v_cvt_pk_bf16_f32 v76, v10, v11
	ds_write_b32 v32, v76 offset:768
	ds_read_b128 v[72:75], v33
	v_lshlrev_b32_e32 v16, 16, v138
	v_lshlrev_b32_e32 v17, 16, v142
	v_mul_f32_e32 v12, v249, v11
	v_mul_f32_e32 v13, v248, v11
	v_fma_f32 v14, v248, v10, -v12
	v_fma_f32 v15, v249, v10, v13
	v_add_f32_e32 v10, v14, v16
	v_add_f32_e32 v11, v15, v17
	s_waitcnt lgkmcnt(0)
	global_store_dwordx4 v31, v[72:75], s[28:29]
	s_sub_u32 s28, s28, 0x200
	s_subb_u32 s29, s29, 0
	v_cvt_pk_bf16_f32 v76, v10, v11
	ds_write_b32 v32, v76
	v_and_b32_e32 v16, 0xffff0000, v137
	v_and_b32_e32 v17, 0xffff0000, v141
	v_mul_f32_e32 v12, v249, v11
	v_mul_f32_e32 v13, v248, v11
	v_fma_f32 v14, v248, v10, -v12
	v_fma_f32 v15, v249, v10, v13
	v_add_f32_e32 v10, v14, v16
	v_add_f32_e32 v11, v15, v17
	v_cvt_pk_bf16_f32 v76, v10, v11
	ds_write_b32 v32, v76 offset:256
	v_lshlrev_b32_e32 v16, 16, v137
	v_lshlrev_b32_e32 v17, 16, v141
	v_mul_f32_e32 v12, v249, v11
	v_mul_f32_e32 v13, v248, v11
	v_fma_f32 v14, v248, v10, -v12
	v_fma_f32 v15, v249, v10, v13
	v_add_f32_e32 v10, v14, v16
	v_add_f32_e32 v11, v15, v17
	v_cvt_pk_bf16_f32 v76, v10, v11
	ds_write_b32 v32, v76 offset:512
	v_and_b32_e32 v16, 0xffff0000, v136
	v_and_b32_e32 v17, 0xffff0000, v140
	v_mul_f32_e32 v12, v249, v11
	v_mul_f32_e32 v13, v248, v11
	v_fma_f32 v14, v248, v10, -v12
	v_fma_f32 v15, v249, v10, v13
	v_add_f32_e32 v10, v14, v16
	v_add_f32_e32 v11, v15, v17
	v_cvt_pk_bf16_f32 v76, v10, v11
	ds_write_b32 v32, v76 offset:768
	ds_read_b128 v[72:75], v33
	v_lshlrev_b32_e32 v16, 16, v136
	v_lshlrev_b32_e32 v17, 16, v140
	v_mul_f32_e32 v12, v249, v11
	v_mul_f32_e32 v13, v248, v11
	v_fma_f32 v14, v248, v10, -v12
	v_fma_f32 v15, v249, v10, v13
	v_add_f32_e32 v10, v14, v16
	v_add_f32_e32 v11, v15, v17
	s_waitcnt lgkmcnt(0)
; #define GAS __attribute__((address_space(1)))
; #define LAS __attribute__((address_space(3)))
; #define SCAN_LOAD(HALF) do { _Pragma("unroll") for (int k = 0; k < 8; ++k) { const int kk = r ? (15 - 8 * (HALF) - k) : (8 * (HALF) + k); pre[k] = *(const u32x4*)(re_row + 2048 * kk); pim[k] = *(const u32x4*)(im_row + 2048 * kk); } } while (0)
; __device__ __forceinline__ void scan_pair(Frame& F, const int g, const int b, unsigned long long& pt0, unsigned long long& pt1) {
;     ...
;     for (int half = 0; half < 2; ++half) { SCAN_LOAD(half);
;         if (r == 0) {
; #pragma unroll
;             for (int i = 0; i < 64; ++i) {
;                 ((LAS unsigned*)tile)[(i & 3) * 64 + n] = pk2(hr, hi);
;                 if ((i & 3) == 3) { const u32x4 w = *(const LAS u32x4*)((const LAS char*)tile + n * 16); *(GAS u32x4*)hp = w; hp += hstep4; asm volatile("" : "+v"(hp)); }
;                 cmul_acc(hr, hi, aTr, aTi, bf2f(pre[i >> 3][(i & 7) >> 1] >> (16 * (i & 1))), bf2f(pim[i >> 3][(i & 7) >> 1] >> (16 * (i & 1)))); }
;         } else {
; #pragma unroll
;             for (int i = 0; i < 64; ++i) { const int e = 7 - (i & 7);
;                 ((LAS unsigned*)tile)[(i & 3) * 64 + n] = pk2(hr, hi);
;                 if ((i & 3) == 3) { const u32x4 w = *(const LAS u32x4*)((const LAS char*)tile + n * 16); *(GAS u32x4*)hp = w; hp += hstep4; asm volatile("" : "+v"(hp)); }
;                 cmul_acc(hr, hi, aTr, aTi, bf2f(pre[i >> 3][e >> 1] >> (16 * (e & 1))), bf2f(pim[i >> 3][e >> 1] >> (16 * (e & 1)))); }
;         }
;         asm volatile("" ::: "memory"); }
	global_store_dwordx4 v31, v[72:75], s[28:29]
	s_sub_u32 s28, s28, 0x200
	s_subb_u32 s29, s29, 0
	v_cvt_pk_bf16_f32 v76, v10, v11
	ds_write_b32 v32, v76
	v_and_b32_e32 v16, 0xffff0000, v147
	v_and_b32_e32 v17, 0xffff0000, v151
	v_mul_f32_e32 v12, v249, v11
	v_mul_f32_e32 v13, v248, v11
	v_fma_f32 v14, v248, v10, -v12
	v_fma_f32 v15, v249, v10, v13
	v_add_f32_e32 v10, v14, v16
	v_add_f32_e32 v11, v15, v17
	v_cvt_pk_bf16_f32 v76, v10, v11
	ds_write_b32 v32, v76 offset:256
	v_lshlrev_b32_e32 v16, 16, v147
	v_lshlrev_b32_e32 v17, 16, v151
	v_mul_f32_e32 v12, v249, v11
	v_mul_f32_e32 v13, v248, v11
	v_fma_f32 v14, v248, v10, -v12
	v_fma_f32 v15, v249, v10, v13
	v_add_f32_e32 v10, v14, v16
	v_add_f32_e32 v11, v15, v17
	v_cvt_pk_bf16_f32 v76, v10, v11
	ds_write_b32 v32, v76 offset:512
	v_and_b32_e32 v16, 0xffff0000, v146
	v_and_b32_e32 v17, 0xffff0000, v150
	v_mul_f32_e32 v12, v249, v11
	v_mul_f32_e32 v13, v248, v11
	v_fma_f32 v14, v248, v10, -v12
	v_fma_f32 v15, v249, v10, v13
	v_add_f32_e32 v10, v14, v16
	v_add_f32_e32 v11, v15, v17
	v_cvt_pk_bf16_f32 v76, v10, v11
	ds_write_b32 v32, v76 offset:768
	ds_read_b128 v[72:75], v33
	v_lshlrev_b32_e32 v16, 16, v146
	v_lshlrev_b32_e32 v17, 16, v150
	v_mul_f32_e32 v12, v249, v11
	v_mul_f32_e32 v13, v248, v11
	v_fma_f32 v14, v248, v10, -v12
	v_fma_f32 v15, v249, v10, v13
	v_add_f32_e32 v10, v14, v16
	v_add_f32_e32 v11, v15, v17
	s_waitcnt lgkmcnt(0)
	global_store_dwordx4 v31, v[72:75], s[28:29]
	s_sub_u32 s28, s28, 0x200
	s_subb_u32 s29, s29, 0
	v_cvt_pk_bf16_f32 v76, v10, v11
	ds_write_b32 v32, v76
	v_and_b32_e32 v16, 0xffff0000, v145
	v_and_b32_e32 v17, 0xffff0000, v149
	v_mul_f32_e32 v12, v249, v11
	v_mul_f32_e32 v13, v248, v11
	v_fma_f32 v14, v248, v10, -v12
	v_fma_f32 v15, v249, v10, v13
	v_add_f32_e32 v10, v14, v16
	v_add_f32_e32 v11, v15, v17
	v_cvt_pk_bf16_f32 v76, v10, v11
	ds_write_b32 v32, v76 offset:256
	v_lshlrev_b32_e32 v16, 16, v145
	v_lshlrev_b32_e32 v17, 16, v149
	v_mul_f32_e32 v12, v249, v11
	v_mul_f32_e32 v13, v248, v11
	v_fma_f32 v14, v248, v10, -v12
	v_fma_f32 v15, v249, v10, v13
	v_add_f32_e32 v10, v14, v16
	v_add_f32_e32 v11, v15, v17
	v_cvt_pk_bf16_f32 v76, v10, v11
	ds_write_b32 v32, v76 offset:512
	v_and_b32_e32 v16, 0xffff0000, v144
	v_and_b32_e32 v17, 0xffff0000, v148
	v_mul_f32_e32 v12, v249, v11
	v_mul_f32_e32 v13, v248, v11
	v_fma_f32 v14, v248, v10, -v12
	v_fma_f32 v15, v249, v10, v13
	v_add_f32_e32 v10, v14, v16
	v_add_f32_e32 v11, v15, v17
	v_cvt_pk_bf16_f32 v76, v10, v11
	ds_write_b32 v32, v76 offset:768
	ds_read_b128 v[72:75], v33
	v_lshlrev_b32_e32 v16, 16, v144
	v_lshlrev_b32_e32 v17, 16, v148
	v_mul_f32_e32 v12, v249, v11
	v_mul_f32_e32 v13, v248, v11
	v_fma_f32 v14, v248, v10, -v12
	v_fma_f32 v15, v249, v10, v13
	v_add_f32_e32 v10, v14, v16
	v_add_f32_e32 v11, v15, v17
	s_waitcnt lgkmcnt(0)
	global_store_dwordx4 v31, v[72:75], s[28:29]
	s_sub_u32 s28, s28, 0x200
	s_subb_u32 s29, s29, 0
	v_cvt_pk_bf16_f32 v76, v10, v11
	ds_write_b32 v32, v76
	v_and_b32_e32 v16, 0xffff0000, v155
	v_and_b32_e32 v17, 0xffff0000, v159
	v_mul_f32_e32 v12, v249, v11
	v_mul_f32_e32 v13, v248, v11
	v_fma_f32 v14, v248, v10, -v12
	v_fma_f32 v15, v249, v10, v13
	v_add_f32_e32 v10, v14, v16
	v_add_f32_e32 v11, v15, v17
	v_cvt_pk_bf16_f32 v76, v10, v11
	ds_write_b32 v32, v76 offset:256
	v_lshlrev_b32_e32 v16, 16, v155
	v_lshlrev_b32_e32 v17, 16, v159
	v_mul_f32_e32 v12, v249, v11
	v_mul_f32_e32 v13, v248, v11
	v_fma_f32 v14, v248, v10, -v12
	v_fma_f32 v15, v249, v10, v13
	v_add_f32_e32 v10, v14, v16
	v_add_f32_e32 v11, v15, v17
	v_cvt_pk_bf16_f32 v76, v10, v11
	ds_write_b32 v32, v76 offset:512
	v_and_b32_e32 v16, 0xffff0000, v154
	v_and_b32_e32 v17, 0xffff0000, v158
	v_mul_f32_e32 v12, v249, v11
	v_mul_f32_e32 v13, v248, v11
	v_fma_f32 v14, v248, v10, -v12
	v_fma_f32 v15, v249, v10, v13
	v_add_f32_e32 v10, v14, v16
	v_add_f32_e32 v11, v15, v17
	v_cvt_pk_bf16_f32 v76, v10, v11
	ds_write_b32 v32, v76 offset:768
	ds_read_b128 v[72:75], v33
	v_lshlrev_b32_e32 v16, 16, v154
	v_lshlrev_b32_e32 v17, 16, v158
	v_mul_f32_e32 v12, v249, v11
	v_mul_f32_e32 v13, v248, v11
	v_fma_f32 v14, v248, v10, -v12
	v_fma_f32 v15, v249, v10, v13
	v_add_f32_e32 v10, v14, v16
	v_add_f32_e32 v11, v15, v17
	s_waitcnt lgkmcnt(0)
	global_store_dwordx4 v31, v[72:75], s[28:29]
	s_sub_u32 s28, s28, 0x200
	s_subb_u32 s29, s29, 0
	v_cvt_pk_bf16_f32 v76, v10, v11
	ds_write_b32 v32, v76
	v_and_b32_e32 v16, 0xffff0000, v153
	v_and_b32_e32 v17, 0xffff0000, v157
	v_mul_f32_e32 v12, v249, v11
	v_mul_f32_e32 v13, v248, v11
	v_fma_f32 v14, v248, v10, -v12
	v_fma_f32 v15, v249, v10, v13
	v_add_f32_e32 v10, v14, v16
	v_add_f32_e32 v11, v15, v17
	v_cvt_pk_bf16_f32 v76, v10, v11
	ds_write_b32 v32, v76 offset:256
	v_lshlrev_b32_e32 v16, 16, v153
	v_lshlrev_b32_e32 v17, 16, v157
	v_mul_f32_e32 v12, v249, v11
	v_mul_f32_e32 v13, v248, v11
	v_fma_f32 v14, v248, v10, -v12
	v_fma_f32 v15, v249, v10, v13
	v_add_f32_e32 v10, v14, v16
	v_add_f32_e32 v11, v15, v17
	v_cvt_pk_bf16_f32 v76, v10, v11
	ds_write_b32 v32, v76 offset:512
	v_and_b32_e32 v16, 0xffff0000, v152
	v_and_b32_e32 v17, 0xffff0000, v156
	v_mul_f32_e32 v12, v249, v11
	v_mul_f32_e32 v13, v248, v11
	v_fma_f32 v14, v248, v10, -v12
	v_fma_f32 v15, v249, v10, v13
	v_add_f32_e32 v10, v14, v16
	v_add_f32_e32 v11, v15, v17
	v_cvt_pk_bf16_f32 v76, v10, v11
	ds_write_b32 v32, v76 offset:768
	ds_read_b128 v[72:75], v33
	v_lshlrev_b32_e32 v16, 16, v152
	v_lshlrev_b32_e32 v17, 16, v156
	v_mul_f32_e32 v12, v249, v11
	v_mul_f32_e32 v13, v248, v11
	v_fma_f32 v14, v248, v10, -v12
	v_fma_f32 v15, v249, v10, v13
	v_add_f32_e32 v10, v14, v16
	v_add_f32_e32 v11, v15, v17
	s_waitcnt lgkmcnt(0)
; #define GAS __attribute__((address_space(1)))
; #define LAS __attribute__((address_space(3)))
; #define SCAN_LOAD(HALF) do { _Pragma("unroll") for (int k = 0; k < 8; ++k) { const int kk = r ? (15 - 8 * (HALF) - k) : (8 * (HALF) + k); pre[k] = *(const u32x4*)(re_row + 2048 * kk); pim[k] = *(const u32x4*)(im_row + 2048 * kk); } } while (0)
; __device__ __forceinline__ void scan_pair(Frame& F, const int g, const int b, unsigned long long& pt0, unsigned long long& pt1) {
;     ...
;     for (int half = 0; half < 2; ++half) { SCAN_LOAD(half);
;         if (r == 0) {
; #pragma unroll
;             for (int i = 0; i < 64; ++i) {
;                 ((LAS unsigned*)tile)[(i & 3) * 64 + n] = pk2(hr, hi);
;                 if ((i & 3) == 3) { const u32x4 w = *(const LAS u32x4*)((const LAS char*)tile + n * 16); *(GAS u32x4*)hp = w; hp += hstep4; asm volatile("" : "+v"(hp)); }
;                 cmul_acc(hr, hi, aTr, aTi, bf2f(pre[i >> 3][(i & 7) >> 1] >> (16 * (i & 1))), bf2f(pim[i >> 3][(i & 7) >> 1] >> (16 * (i & 1)))); }
;         } else {
; #pragma unroll
;             for (int i = 0; i < 64; ++i) { const int e = 7 - (i & 7);
;                 ((LAS unsigned*)tile)[(i & 3) * 64 + n] = pk2(hr, hi);
;                 if ((i & 3) == 3) { const u32x4 w = *(const LAS u32x4*)((const LAS char*)tile + n * 16); *(GAS u32x4*)hp = w; hp += hstep4; asm volatile("" : "+v"(hp)); }
;                 cmul_acc(hr, hi, aTr, aTi, bf2f(pre[i >> 3][e >> 1] >> (16 * (e & 1))), bf2f(pim[i >> 3][e >> 1] >> (16 * (e & 1)))); }
;         }
;         asm volatile("" ::: "memory"); }
	global_store_dwordx4 v31, v[72:75], s[28:29]
	s_sub_u32 s28, s28, 0x200
	s_subb_u32 s29, s29, 0
	v_cvt_pk_bf16_f32 v76, v10, v11
	ds_write_b32 v32, v76
	v_and_b32_e32 v16, 0xffff0000, v163
	v_and_b32_e32 v17, 0xffff0000, v167
	v_mul_f32_e32 v12, v249, v11
	v_mul_f32_e32 v13, v248, v11
	v_fma_f32 v14, v248, v10, -v12
	v_fma_f32 v15, v249, v10, v13
	v_add_f32_e32 v10, v14, v16
	v_add_f32_e32 v11, v15, v17
	v_cvt_pk_bf16_f32 v76, v10, v11
	ds_write_b32 v32, v76 offset:256
	v_lshlrev_b32_e32 v16, 16, v163
	v_lshlrev_b32_e32 v17, 16, v167
	v_mul_f32_e32 v12, v249, v11
	v_mul_f32_e32 v13, v248, v11
	v_fma_f32 v14, v248, v10, -v12
	v_fma_f32 v15, v249, v10, v13
	v_add_f32_e32 v10, v14, v16
	v_add_f32_e32 v11, v15, v17
	v_cvt_pk_bf16_f32 v76, v10, v11
	ds_write_b32 v32, v76 offset:512
	v_and_b32_e32 v16, 0xffff0000, v162
	v_and_b32_e32 v17, 0xffff0000, v166
	v_mul_f32_e32 v12, v249, v11
	v_mul_f32_e32 v13, v248, v11
	v_fma_f32 v14, v248, v10, -v12
	v_fma_f32 v15, v249, v10, v13
	v_add_f32_e32 v10, v14, v16
	v_add_f32_e32 v11, v15, v17
	v_cvt_pk_bf16_f32 v76, v10, v11
	ds_write_b32 v32, v76 offset:768
	ds_read_b128 v[72:75], v33
	v_lshlrev_b32_e32 v16, 16, v162
	v_lshlrev_b32_e32 v17, 16, v166
	v_mul_f32_e32 v12, v249, v11
	v_mul_f32_e32 v13, v248, v11
	v_fma_f32 v14, v248, v10, -v12
	v_fma_f32 v15, v249, v10, v13
	v_add_f32_e32 v10, v14, v16
	v_add_f32_e32 v11, v15, v17
	s_waitcnt lgkmcnt(0)
	global_store_dwordx4 v31, v[72:75], s[28:29]
	s_sub_u32 s28, s28, 0x200
	s_subb_u32 s29, s29, 0
	v_cvt_pk_bf16_f32 v76, v10, v11
	ds_write_b32 v32, v76
	v_and_b32_e32 v16, 0xffff0000, v161
	v_and_b32_e32 v17, 0xffff0000, v165
	v_mul_f32_e32 v12, v249, v11
	v_mul_f32_e32 v13, v248, v11
	v_fma_f32 v14, v248, v10, -v12
	v_fma_f32 v15, v249, v10, v13
	v_add_f32_e32 v10, v14, v16
	v_add_f32_e32 v11, v15, v17
	v_cvt_pk_bf16_f32 v76, v10, v11
	ds_write_b32 v32, v76 offset:256
	v_lshlrev_b32_e32 v16, 16, v161
	v_lshlrev_b32_e32 v17, 16, v165
	v_mul_f32_e32 v12, v249, v11
	v_mul_f32_e32 v13, v248, v11
	v_fma_f32 v14, v248, v10, -v12
	v_fma_f32 v15, v249, v10, v13
	v_add_f32_e32 v10, v14, v16
	v_add_f32_e32 v11, v15, v17
	v_cvt_pk_bf16_f32 v76, v10, v11
	ds_write_b32 v32, v76 offset:512
	v_and_b32_e32 v16, 0xffff0000, v160
	v_and_b32_e32 v17, 0xffff0000, v164
	v_mul_f32_e32 v12, v249, v11
	v_mul_f32_e32 v13, v248, v11
	v_fma_f32 v14, v248, v10, -v12
	v_fma_f32 v15, v249, v10, v13
	v_add_f32_e32 v10, v14, v16
	v_add_f32_e32 v11, v15, v17
	v_cvt_pk_bf16_f32 v76, v10, v11
	ds_write_b32 v32, v76 offset:768
	ds_read_b128 v[72:75], v33
	v_lshlrev_b32_e32 v16, 16, v160
	v_lshlrev_b32_e32 v17, 16, v164
	v_mul_f32_e32 v12, v249, v11
	v_mul_f32_e32 v13, v248, v11
	v_fma_f32 v14, v248, v10, -v12
	v_fma_f32 v15, v249, v10, v13
	v_add_f32_e32 v10, v14, v16
	v_add_f32_e32 v11, v15, v17
	s_waitcnt lgkmcnt(0)
	global_store_dwordx4 v31, v[72:75], s[28:29]
	s_sub_u32 s28, s28, 0x200
	s_subb_u32 s29, s29, 0
	v_add_u32_e32 v38, 0x2000, v38
	s_sub_i32 s16, s16, 1
	s_cmp_lg_u32 s16, 0
	s_cbranch_scc1 .Lscl_p2r1_a
	s_waitcnt vmcnt(0)
	s_mov_b32 s16, 2
.Lscl_p2r1_b:
	s_waitcnt vmcnt(12)
	v_cvt_pk_bf16_f32 v76, v10, v11
	ds_write_b32 v32, v76
	v_and_b32_e32 v16, 0xffff0000, v171
	v_and_b32_e32 v17, 0xffff0000, v175
	v_mul_f32_e32 v12, v249, v11
	v_mul_f32_e32 v13, v248, v11
	v_fma_f32 v14, v248, v10, -v12
	v_fma_f32 v15, v249, v10, v13
	v_add_f32_e32 v10, v14, v16
	v_add_f32_e32 v11, v15, v17
	v_cvt_pk_bf16_f32 v76, v10, v11
	ds_write_b32 v32, v76 offset:256
	v_lshlrev_b32_e32 v16, 16, v171
	v_lshlrev_b32_e32 v17, 16, v175
	v_mul_f32_e32 v12, v249, v11
	v_mul_f32_e32 v13, v248, v11
	v_fma_f32 v14, v248, v10, -v12
	v_fma_f32 v15, v249, v10, v13
	v_add_f32_e32 v10, v14, v16
	v_add_f32_e32 v11, v15, v17
	v_cvt_pk_bf16_f32 v76, v10, v11
	ds_write_b32 v32, v76 offset:512
	v_and_b32_e32 v16, 0xffff0000, v170
	v_and_b32_e32 v17, 0xffff0000, v174
	v_mul_f32_e32 v12, v249, v11
	v_mul_f32_e32 v13, v248, v11
	v_fma_f32 v14, v248, v10, -v12
	v_fma_f32 v15, v249, v10, v13
	v_add_f32_e32 v10, v14, v16
	v_add_f32_e32 v11, v15, v17
	v_cvt_pk_bf16_f32 v76, v10, v11
	ds_write_b32 v32, v76 offset:768
	ds_read_b128 v[72:75], v33
	v_lshlrev_b32_e32 v16, 16, v170
	v_lshlrev_b32_e32 v17, 16, v174
	v_mul_f32_e32 v12, v249, v11
	v_mul_f32_e32 v13, v248, v11
	v_fma_f32 v14, v248, v10, -v12
	v_fma_f32 v15, v249, v10, v13
	v_add_f32_e32 v10, v14, v16
	v_add_f32_e32 v11, v15, v17
	s_waitcnt lgkmcnt(0)
	global_store_dwordx4 v31, v[72:75], s[28:29]
	s_sub_u32 s28, s28, 0x200
	s_subb_u32 s29, s29, 0
	v_cvt_pk_bf16_f32 v76, v10, v11
	ds_write_b32 v32, v76
	v_and_b32_e32 v16, 0xffff0000, v169
	v_and_b32_e32 v17, 0xffff0000, v173
	v_mul_f32_e32 v12, v249, v11
	v_mul_f32_e32 v13, v248, v11
	v_fma_f32 v14, v248, v10, -v12
	v_fma_f32 v15, v249, v10, v13
	v_add_f32_e32 v10, v14, v16
	v_add_f32_e32 v11, v15, v17
	v_cvt_pk_bf16_f32 v76, v10, v11
	ds_write_b32 v32, v76 offset:256
	v_lshlrev_b32_e32 v16, 16, v169
	v_lshlrev_b32_e32 v17, 16, v173
	v_mul_f32_e32 v12, v249, v11
	v_mul_f32_e32 v13, v248, v11
	v_fma_f32 v14, v248, v10, -v12
	v_fma_f32 v15, v249, v10, v13
	v_add_f32_e32 v10, v14, v16
	v_add_f32_e32 v11, v15, v17
	v_cvt_pk_bf16_f32 v76, v10, v11
	ds_write_b32 v32, v76 offset:512
	v_and_b32_e32 v16, 0xffff0000, v168
	v_and_b32_e32 v17, 0xffff0000, v172
	v_mul_f32_e32 v12, v249, v11
	v_mul_f32_e32 v13, v248, v11
	v_fma_f32 v14, v248, v10, -v12
	v_fma_f32 v15, v249, v10, v13
	v_add_f32_e32 v10, v14, v16
	v_add_f32_e32 v11, v15, v17
	v_cvt_pk_bf16_f32 v76, v10, v11
	ds_write_b32 v32, v76 offset:768
	ds_read_b128 v[72:75], v33
	v_lshlrev_b32_e32 v16, 16, v168
	v_lshlrev_b32_e32 v17, 16, v172
	v_mul_f32_e32 v12, v249, v11
	v_mul_f32_e32 v13, v248, v11
	v_fma_f32 v14, v248, v10, -v12
	v_fma_f32 v15, v249, v10, v13
	v_add_f32_e32 v10, v14, v16
	v_add_f32_e32 v11, v15, v17
	s_waitcnt lgkmcnt(0)
; #define GAS __attribute__((address_space(1)))
; #define LAS __attribute__((address_space(3)))
; #define SCAN_LOAD(HALF) do { _Pragma("unroll") for (int k = 0; k < 8; ++k) { const int kk = r ? (15 - 8 * (HALF) - k) : (8 * (HALF) + k); pre[k] = *(const u32x4*)(re_row + 2048 * kk); pim[k] = *(const u32x4*)(im_row + 2048 * kk); } } while (0)
; __device__ __forceinline__ void scan_pair(Frame& F, const int g, const int b, unsigned long long& pt0, unsigned long long& pt1) {
;     ...
;     for (int half = 0; half < 2; ++half) { SCAN_LOAD(half);
;         if (r == 0) {
; #pragma unroll
;             for (int i = 0; i < 64; ++i) {
;                 ((LAS unsigned*)tile)[(i & 3) * 64 + n] = pk2(hr, hi);
;                 if ((i & 3) == 3) { const u32x4 w = *(const LAS u32x4*)((const LAS char*)tile + n * 16); *(GAS u32x4*)hp = w; hp += hstep4; asm volatile("" : "+v"(hp)); }
;                 cmul_acc(hr, hi, aTr, aTi, bf2f(pre[i >> 3][(i & 7) >> 1] >> (16 * (i & 1))), bf2f(pim[i >> 3][(i & 7) >> 1] >> (16 * (i & 1)))); }
;         } else {
; #pragma unroll
;             for (int i = 0; i < 64; ++i) { const int e = 7 - (i & 7);
;                 ((LAS unsigned*)tile)[(i & 3) * 64 + n] = pk2(hr, hi);
;                 if ((i & 3) == 3) { const u32x4 w = *(const LAS u32x4*)((const LAS char*)tile + n * 16); *(GAS u32x4*)hp = w; hp += hstep4; asm volatile("" : "+v"(hp)); }
;                 cmul_acc(hr, hi, aTr, aTi, bf2f(pre[i >> 3][e >> 1] >> (16 * (e & 1))), bf2f(pim[i >> 3][e >> 1] >> (16 * (e & 1)))); }
;         }
;         asm volatile("" ::: "memory"); }
	global_store_dwordx4 v31, v[72:75], s[28:29]
	s_sub_u32 s28, s28, 0x200
	s_subb_u32 s29, s29, 0
	global_load_dwordx4 v[168:171], v30, s[10:11]
	global_load_dwordx4 v[172:175], v30, s[10:11] offset:1024
	s_sub_u32 s10, s10, 0x1000
	s_subb_u32 s11, s11, 0
	s_waitcnt vmcnt(12)
	v_cvt_pk_bf16_f32 v76, v10, v11
	ds_write_b32 v32, v76
	v_and_b32_e32 v16, 0xffff0000, v179
	v_and_b32_e32 v17, 0xffff0000, v183
	v_mul_f32_e32 v12, v249, v11
	v_mul_f32_e32 v13, v248, v11
	v_fma_f32 v14, v248, v10, -v12
	v_fma_f32 v15, v249, v10, v13
	v_add_f32_e32 v10, v14, v16
	v_add_f32_e32 v11, v15, v17
	v_cvt_pk_bf16_f32 v76, v10, v11
	ds_write_b32 v32, v76 offset:256
	v_lshlrev_b32_e32 v16, 16, v179
	v_lshlrev_b32_e32 v17, 16, v183
	v_mul_f32_e32 v12, v249, v11
	v_mul_f32_e32 v13, v248, v11
	v_fma_f32 v14, v248, v10, -v12
	v_fma_f32 v15, v249, v10, v13
	v_add_f32_e32 v10, v14, v16
	v_add_f32_e32 v11, v15, v17
	v_cvt_pk_bf16_f32 v76, v10, v11
	ds_write_b32 v32, v76 offset:512
	v_and_b32_e32 v16, 0xffff0000, v178
	v_and_b32_e32 v17, 0xffff0000, v182
	v_mul_f32_e32 v12, v249, v11
	v_mul_f32_e32 v13, v248, v11
	v_fma_f32 v14, v248, v10, -v12
	v_fma_f32 v15, v249, v10, v13
	v_add_f32_e32 v10, v14, v16
	v_add_f32_e32 v11, v15, v17
	v_cvt_pk_bf16_f32 v76, v10, v11
	ds_write_b32 v32, v76 offset:768
	ds_read_b128 v[72:75], v33
	v_lshlrev_b32_e32 v16, 16, v178
	v_lshlrev_b32_e32 v17, 16, v182
	v_mul_f32_e32 v12, v249, v11
	v_mul_f32_e32 v13, v248, v11
	v_fma_f32 v14, v248, v10, -v12
	v_fma_f32 v15, v249, v10, v13
	v_add_f32_e32 v10, v14, v16
	v_add_f32_e32 v11, v15, v17
	s_waitcnt lgkmcnt(0)
	global_store_dwordx4 v31, v[72:75], s[28:29]
	s_sub_u32 s28, s28, 0x200
	s_subb_u32 s29, s29, 0
	v_cvt_pk_bf16_f32 v76, v10, v11
	ds_write_b32 v32, v76
	v_and_b32_e32 v16, 0xffff0000, v177
	v_and_b32_e32 v17, 0xffff0000, v181
	v_mul_f32_e32 v12, v249, v11
	v_mul_f32_e32 v13, v248, v11
	v_fma_f32 v14, v248, v10, -v12
	v_fma_f32 v15, v249, v10, v13
	v_add_f32_e32 v10, v14, v16
	v_add_f32_e32 v11, v15, v17
	v_cvt_pk_bf16_f32 v76, v10, v11
	ds_write_b32 v32, v76 offset:256
	v_lshlrev_b32_e32 v16, 16, v177
	v_lshlrev_b32_e32 v17, 16, v181
	v_mul_f32_e32 v12, v249, v11
	v_mul_f32_e32 v13, v248, v11
	v_fma_f32 v14, v248, v10, -v12
	v_fma_f32 v15, v249, v10, v13
	v_add_f32_e32 v10, v14, v16
	v_add_f32_e32 v11, v15, v17
	v_cvt_pk_bf16_f32 v76, v10, v11
	ds_write_b32 v32, v76 offset:512
	v_and_b32_e32 v16, 0xffff0000, v176
	v_and_b32_e32 v17, 0xffff0000, v180
	v_mul_f32_e32 v12, v249, v11
	v_mul_f32_e32 v13, v248, v11
	v_fma_f32 v14, v248, v10, -v12
	v_fma_f32 v15, v249, v10, v13
	v_add_f32_e32 v10, v14, v16
	v_add_f32_e32 v11, v15, v17
	v_cvt_pk_bf16_f32 v76, v10, v11
	ds_write_b32 v32, v76 offset:768
	ds_read_b128 v[72:75], v33
	v_lshlrev_b32_e32 v16, 16, v176
	v_lshlrev_b32_e32 v17, 16, v180
	v_mul_f32_e32 v12, v249, v11
	v_mul_f32_e32 v13, v248, v11
	v_fma_f32 v14, v248, v10, -v12
	v_fma_f32 v15, v249, v10, v13
	v_add_f32_e32 v10, v14, v16
	v_add_f32_e32 v11, v15, v17
	s_waitcnt lgkmcnt(0)
	global_store_dwordx4 v31, v[72:75], s[28:29]
	s_sub_u32 s28, s28, 0x200
	s_subb_u32 s29, s29, 0
	global_load_dwordx4 v[176:179], v30, s[10:11]
	global_load_dwordx4 v[180:183], v30, s[10:11] offset:1024
	s_sub_u32 s10, s10, 0x1000
	s_subb_u32 s11, s11, 0
	s_waitcnt vmcnt(12)
	v_cvt_pk_bf16_f32 v76, v10, v11
	ds_write_b32 v32, v76
	v_and_b32_e32 v16, 0xffff0000, v187
	v_and_b32_e32 v17, 0xffff0000, v191
	v_mul_f32_e32 v12, v249, v11
	v_mul_f32_e32 v13, v248, v11
	v_fma_f32 v14, v248, v10, -v12
	v_fma_f32 v15, v249, v10, v13
	v_add_f32_e32 v10, v14, v16
	v_add_f32_e32 v11, v15, v17
	v_cvt_pk_bf16_f32 v76, v10, v11
	ds_write_b32 v32, v76 offset:256
	v_lshlrev_b32_e32 v16, 16, v187
	v_lshlrev_b32_e32 v17, 16, v191
	v_mul_f32_e32 v12, v249, v11
	v_mul_f32_e32 v13, v248, v11
	v_fma_f32 v14, v248, v10, -v12
	v_fma_f32 v15, v249, v10, v13
	v_add_f32_e32 v10, v14, v16
	v_add_f32_e32 v11, v15, v17
	v_cvt_pk_bf16_f32 v76, v10, v11
	ds_write_b32 v32, v76 offset:512
	v_and_b32_e32 v16, 0xffff0000, v186
	v_and_b32_e32 v17, 0xffff0000, v190
	v_mul_f32_e32 v12, v249, v11
	v_mul_f32_e32 v13, v248, v11
	v_fma_f32 v14, v248, v10, -v12
	v_fma_f32 v15, v249, v10, v13
	v_add_f32_e32 v10, v14, v16
	v_add_f32_e32 v11, v15, v17
	v_cvt_pk_bf16_f32 v76, v10, v11
	ds_write_b32 v32, v76 offset:768
	ds_read_b128 v[72:75], v33
	v_lshlrev_b32_e32 v16, 16, v186
	v_lshlrev_b32_e32 v17, 16, v190
	v_mul_f32_e32 v12, v249, v11
	v_mul_f32_e32 v13, v248, v11
	v_fma_f32 v14, v248, v10, -v12
	v_fma_f32 v15, v249, v10, v13
	v_add_f32_e32 v10, v14, v16
	v_add_f32_e32 v11, v15, v17
	s_waitcnt lgkmcnt(0)
; #define GAS __attribute__((address_space(1)))
; #define LAS __attribute__((address_space(3)))
; #define SCAN_LOAD(HALF) do { _Pragma("unroll") for (int k = 0; k < 8; ++k) { const int kk = r ? (15 - 8 * (HALF) - k) : (8 * (HALF) + k); pre[k] = *(const u32x4*)(re_row + 2048 * kk); pim[k] = *(const u32x4*)(im_row + 2048 * kk); } } while (0)
; __device__ __forceinline__ void scan_pair(Frame& F, const int g, const int b, unsigned long long& pt0, unsigned long long& pt1) {
;     ...
;     for (int half = 0; half < 2; ++half) { SCAN_LOAD(half);
;         if (r == 0) {
; #pragma unroll
;             for (int i = 0; i < 64; ++i) {
;                 ((LAS unsigned*)tile)[(i & 3) * 64 + n] = pk2(hr, hi);
;                 if ((i & 3) == 3) { const u32x4 w = *(const LAS u32x4*)((const LAS char*)tile + n * 16); *(GAS u32x4*)hp = w; hp += hstep4; asm volatile("" : "+v"(hp)); }
;                 cmul_acc(hr, hi, aTr, aTi, bf2f(pre[i >> 3][(i & 7) >> 1] >> (16 * (i & 1))), bf2f(pim[i >> 3][(i & 7) >> 1] >> (16 * (i & 1)))); }
;         } else {
; #pragma unroll
;             for (int i = 0; i < 64; ++i) { const int e = 7 - (i & 7);
;                 ((LAS unsigned*)tile)[(i & 3) * 64 + n] = pk2(hr, hi);
;                 if ((i & 3) == 3) { const u32x4 w = *(const LAS u32x4*)((const LAS char*)tile + n * 16); *(GAS u32x4*)hp = w; hp += hstep4; asm volatile("" : "+v"(hp)); }
;                 cmul_acc(hr, hi, aTr, aTi, bf2f(pre[i >> 3][e >> 1] >> (16 * (e & 1))), bf2f(pim[i >> 3][e >> 1] >> (16 * (e & 1)))); }
;         }
;         asm volatile("" ::: "memory"); }
	global_store_dwordx4 v31, v[72:75], s[28:29]
	s_sub_u32 s28, s28, 0x200
	s_subb_u32 s29, s29, 0
	v_cvt_pk_bf16_f32 v76, v10, v11
	ds_write_b32 v32, v76
	v_and_b32_e32 v16, 0xffff0000, v185
	v_and_b32_e32 v17, 0xffff0000, v189
	v_mul_f32_e32 v12, v249, v11
	v_mul_f32_e32 v13, v248, v11
	v_fma_f32 v14, v248, v10, -v12
	v_fma_f32 v15, v249, v10, v13
	v_add_f32_e32 v10, v14, v16
	v_add_f32_e32 v11, v15, v17
	v_cvt_pk_bf16_f32 v76, v10, v11
	ds_write_b32 v32, v76 offset:256
	v_lshlrev_b32_e32 v16, 16, v185
	v_lshlrev_b32_e32 v17, 16, v189
	v_mul_f32_e32 v12, v249, v11
	v_mul_f32_e32 v13, v248, v11
	v_fma_f32 v14, v248, v10, -v12
	v_fma_f32 v15, v249, v10, v13
	v_add_f32_e32 v10, v14, v16
	v_add_f32_e32 v11, v15, v17
	v_cvt_pk_bf16_f32 v76, v10, v11
	ds_write_b32 v32, v76 offset:512
	v_and_b32_e32 v16, 0xffff0000, v184
	v_and_b32_e32 v17, 0xffff0000, v188
	v_mul_f32_e32 v12, v249, v11
	v_mul_f32_e32 v13, v248, v11
	v_fma_f32 v14, v248, v10, -v12
	v_fma_f32 v15, v249, v10, v13
	v_add_f32_e32 v10, v14, v16
	v_add_f32_e32 v11, v15, v17
	v_cvt_pk_bf16_f32 v76, v10, v11
	ds_write_b32 v32, v76 offset:768
	ds_read_b128 v[72:75], v33
	v_lshlrev_b32_e32 v16, 16, v184
	v_lshlrev_b32_e32 v17, 16, v188
	v_mul_f32_e32 v12, v249, v11
	v_mul_f32_e32 v13, v248, v11
	v_fma_f32 v14, v248, v10, -v12
	v_fma_f32 v15, v249, v10, v13
	v_add_f32_e32 v10, v14, v16
	v_add_f32_e32 v11, v15, v17
	s_waitcnt lgkmcnt(0)
	global_store_dwordx4 v31, v[72:75], s[28:29]
	s_sub_u32 s28, s28, 0x200
	s_subb_u32 s29, s29, 0
	global_load_dwordx4 v[184:187], v30, s[10:11]
	global_load_dwordx4 v[188:191], v30, s[10:11] offset:1024
	s_sub_u32 s10, s10, 0x1000
	s_subb_u32 s11, s11, 0
	s_waitcnt vmcnt(12)
	v_cvt_pk_bf16_f32 v76, v10, v11
	ds_write_b32 v32, v76
	v_and_b32_e32 v16, 0xffff0000, v195
	v_and_b32_e32 v17, 0xffff0000, v199
	v_mul_f32_e32 v12, v249, v11
	v_mul_f32_e32 v13, v248, v11
	v_fma_f32 v14, v248, v10, -v12
	v_fma_f32 v15, v249, v10, v13
	v_add_f32_e32 v10, v14, v16
	v_add_f32_e32 v11, v15, v17
	v_cvt_pk_bf16_f32 v76, v10, v11
	ds_write_b32 v32, v76 offset:256
	v_lshlrev_b32_e32 v16, 16, v195
	v_lshlrev_b32_e32 v17, 16, v199
	v_mul_f32_e32 v12, v249, v11
	v_mul_f32_e32 v13, v248, v11
	v_fma_f32 v14, v248, v10, -v12
	v_fma_f32 v15, v249, v10, v13
	v_add_f32_e32 v10, v14, v16
	v_add_f32_e32 v11, v15, v17
	v_cvt_pk_bf16_f32 v76, v10, v11
	ds_write_b32 v32, v76 offset:512
	v_and_b32_e32 v16, 0xffff0000, v194
	v_and_b32_e32 v17, 0xffff0000, v198
	v_mul_f32_e32 v12, v249, v11
	v_mul_f32_e32 v13, v248, v11
	v_fma_f32 v14, v248, v10, -v12
	v_fma_f32 v15, v249, v10, v13
	v_add_f32_e32 v10, v14, v16
	v_add_f32_e32 v11, v15, v17
	v_cvt_pk_bf16_f32 v76, v10, v11
	ds_write_b32 v32, v76 offset:768
	ds_read_b128 v[72:75], v33
	v_lshlrev_b32_e32 v16, 16, v194
	v_lshlrev_b32_e32 v17, 16, v198
	v_mul_f32_e32 v12, v249, v11
	v_mul_f32_e32 v13, v248, v11
	v_fma_f32 v14, v248, v10, -v12
	v_fma_f32 v15, v249, v10, v13
	v_add_f32_e32 v10, v14, v16
	v_add_f32_e32 v11, v15, v17
	s_waitcnt lgkmcnt(0)
	global_store_dwordx4 v31, v[72:75], s[28:29]
	s_sub_u32 s28, s28, 0x200
	s_subb_u32 s29, s29, 0
	v_cvt_pk_bf16_f32 v76, v10, v11
	ds_write_b32 v32, v76
	v_and_b32_e32 v16, 0xffff0000, v193
	v_and_b32_e32 v17, 0xffff0000, v197
	v_mul_f32_e32 v12, v249, v11
	v_mul_f32_e32 v13, v248, v11
	v_fma_f32 v14, v248, v10, -v12
	v_fma_f32 v15, v249, v10, v13
	v_add_f32_e32 v10, v14, v16
	v_add_f32_e32 v11, v15, v17
	v_cvt_pk_bf16_f32 v76, v10, v11
	ds_write_b32 v32, v76 offset:256
	v_lshlrev_b32_e32 v16, 16, v193
	v_lshlrev_b32_e32 v17, 16, v197
	v_mul_f32_e32 v12, v249, v11
	v_mul_f32_e32 v13, v248, v11
	v_fma_f32 v14, v248, v10, -v12
	v_fma_f32 v15, v249, v10, v13
	v_add_f32_e32 v10, v14, v16
	v_add_f32_e32 v11, v15, v17
	v_cvt_pk_bf16_f32 v76, v10, v11
	ds_write_b32 v32, v76 offset:512
	v_and_b32_e32 v16, 0xffff0000, v192
	v_and_b32_e32 v17, 0xffff0000, v196
	v_mul_f32_e32 v12, v249, v11
	v_mul_f32_e32 v13, v248, v11
	v_fma_f32 v14, v248, v10, -v12
	v_fma_f32 v15, v249, v10, v13
	v_add_f32_e32 v10, v14, v16
	v_add_f32_e32 v11, v15, v17
	v_cvt_pk_bf16_f32 v76, v10, v11
	ds_write_b32 v32, v76 offset:768
	ds_read_b128 v[72:75], v33
	v_lshlrev_b32_e32 v16, 16, v192
	v_lshlrev_b32_e32 v17, 16, v196
	v_mul_f32_e32 v12, v249, v11
	v_mul_f32_e32 v13, v248, v11
	v_fma_f32 v14, v248, v10, -v12
	v_fma_f32 v15, v249, v10, v13
	v_add_f32_e32 v10, v14, v16
	v_add_f32_e32 v11, v15, v17
	s_waitcnt lgkmcnt(0)
	global_store_dwordx4 v31, v[72:75], s[28:29]
	s_sub_u32 s28, s28, 0x200
	s_subb_u32 s29, s29, 0
	global_load_dwordx4 v[192:195], v30, s[10:11]
	global_load_dwordx4 v[196:199], v30, s[10:11] offset:1024
	s_sub_u32 s10, s10, 0x1000
	s_subb_u32 s11, s11, 0
	s_sub_i32 s16, s16, 1
	s_cmp_lg_u32 s16, 0
	s_cbranch_scc1 .Lscl_p2r1_b
	s_waitcnt vmcnt(0)
